# fp8 expert tables stored slice-major (8 column slices of 128 B, rows 128 B apart) so the gather's 8-row loads spread over L2 channels; conversion stores patched accordingly
# speedup vs baseline: 1.0139x; 1.0054x over previous
; __global__ void __launch_bounds__(512) mega(Params P) {
;     ...
;         const int t = c >> 9; const size_t off = (size_t)(c & 511) * 32768;
;         const float* src = ((t & 1) ? P.peer_v : P.peer_u) + (size_t)(t >> 1) * 16384 * 1024 + off;
;         unsigned char* dst = ws + WS_TAB + (size_t)t * 16 * MB + off;
; #pragma unroll
;         for (int it = 0; it < 4; ++it) {
;           const size_t i = (size_t)(it * 512 + tid) * 16;
;           u32x4 o;
; #pragma unroll
;           for (int q = 0; q < 4; ++q) {
;             const f32x4 a = *(const f32x4*)(src + i + 4 * q);
;             int d = __builtin_amdgcn_cvt_pk_fp8_f32(a[0] * 64.f, a[1] * 64.f, 0, false);
;             d = __builtin_amdgcn_cvt_pk_fp8_f32(a[2] * 64.f, a[3] * 64.f, d, true);
;             o[q] = (unsigned)d;
;           }
;           *(u32x4*)(dst + i) = o;
;         }
.LBB0_207:
	s_andn2_b64 vcc, exec, s[16:17]
	s_cbranch_vccnz .LBB0_198
	s_lshl_b32 s2, s20, 15
	s_ashr_i32 s18, s20, 9
	s_and_b32 s2, s2, 0xff8000
	v_readlane_b32 s36, v232, 21
	s_bitcmp0_b32 s20, 9
	v_readlane_b32 s48, v232, 33
	v_readlane_b32 s49, v232, 34
	v_readlane_b32 s50, v232, 35
	v_readlane_b32 s51, v232, 36
	s_cselect_b32 s19, s49, s51
	s_cselect_b32 s21, s48, s50
	s_ashr_i32 s16, s20, 10
	s_ashr_i32 s17, s16, 31
	s_lshl_b64 s[16:17], s[16:17], 26
	s_add_u32 s16, s21, s16
	s_addc_u32 s17, s19, s17
	s_lshl_b32 s19, s2, 2
	s_add_u32 s16, s16, s19
	s_addc_u32 s17, s17, 0
	v_lshlrev_b32_e32 v0, 2, v178
	global_load_dwordx4 v[16:19], v0, s[16:17]
	global_load_dwordx4 v[20:23], v0, s[16:17] offset:16
	global_load_dwordx4 v[24:27], v0, s[16:17] offset:32
	global_load_dwordx4 v[28:31], v0, s[16:17] offset:48
	v_mov_b32_e32 v32, v1
	v_mov_b32_e32 v33, v1
	v_mov_b32_e32 v34, v1
	v_mov_b32_e32 v35, v1
	v_lshl_add_u64 v[36:37], s[16:17], 0, v[0:1]
	s_ashr_i32 s19, s18, 31
	s_lshl_b64 s[18:19], s[18:19], 24
	s_add_u32 s18, s24, s18
	s_addc_u32 s19, s25, s19
	s_add_u32 s18, s18, s2
	s_addc_u32 s19, s19, 0
	s_lshr_b32 s99, s2, 3
	s_sub_u32 s100, s18, s2
	s_subb_u32 s101, s19, 0
	s_add_u32 s100, s100, s99
	s_addc_u32 s101, s101, 0
	v_bfe_u32 v250, v178, 7, 3
	v_lshlrev_b32_e32 v250, 21, v250
	v_lshrrev_b32_e32 v251, 10, v178
	v_lshl_or_b32 v250, v251, 7, v250
	v_bfe_u32 v251, v178, 4, 3
	v_lshl_or_b32 v250, v251, 4, v250
	v_mov_b32_e32 v251, 0
	v_lshl_add_u64 v[254:255], s[100:101], 0, v[250:251]
	v_add_co_u32_e32 v38, vcc, s60, v36
	v_lshl_add_u64 v[40:41], s[18:19], 0, v[178:179]
	s_nop 0
	v_addc_co_u32_e32 v39, vcc, 0, v37, vcc
	v_readlane_b32 s37, v232, 22
	v_readlane_b32 s38, v232, 23
	v_readlane_b32 s39, v232, 24
	v_readlane_b32 s40, v232, 25
	v_readlane_b32 s41, v232, 26
	v_readlane_b32 s42, v232, 27
	v_readlane_b32 s43, v232, 28
	v_readlane_b32 s44, v232, 29
	v_readlane_b32 s45, v232, 30
	v_readlane_b32 s46, v232, 31
	v_readlane_b32 s47, v232, 32
	s_waitcnt vmcnt(3)
	v_mul_f32_e32 v0, 0x42800000, v16
	v_mul_f32_e32 v5, 0x42800000, v17
	s_waitcnt vmcnt(2)
	v_mul_f32_e32 v16, 0x42800000, v20
	v_mul_f32_e32 v17, 0x42800000, v21
	s_waitcnt vmcnt(1)
	v_mul_f32_e32 v20, 0x42800000, v24
	v_mul_f32_e32 v21, 0x42800000, v25
	s_waitcnt vmcnt(0)
	v_mul_f32_e32 v24, 0x42800000, v28
	v_mul_f32_e32 v25, 0x42800000, v29
	v_cvt_pk_fp8_f32 v32, v0, v5
	v_cvt_pk_fp8_f32 v33, v16, v17
	v_cvt_pk_fp8_f32 v34, v20, v21
	v_cvt_pk_fp8_f32 v35, v24, v25
	v_mul_f32_e32 v7, 0x42800000, v18
	v_mul_f32_e32 v15, 0x42800000, v19
	v_mul_f32_e32 v18, 0x42800000, v22
	v_mul_f32_e32 v19, 0x42800000, v23
	v_mul_f32_e32 v22, 0x42800000, v26
	v_mul_f32_e32 v23, 0x42800000, v27
	v_mul_f32_e32 v26, 0x42800000, v30
	v_mul_f32_e32 v27, 0x42800000, v31
	v_cvt_pk_fp8_f32 v32, v7, v15 op_sel:[0,0,1]
	v_cvt_pk_fp8_f32 v33, v18, v19 op_sel:[0,0,1]
	v_cvt_pk_fp8_f32 v34, v22, v23 op_sel:[0,0,1]
	v_cvt_pk_fp8_f32 v35, v26, v27 op_sel:[0,0,1]
	v_lshl_add_u64 v[28:29], v[36:37], 0, s[12:13]
	v_lshlrev_b32_e32 v0, 2, v2
	global_store_dwordx4 v[254:255], v[32:35], off
	global_load_dwordx4 v[16:19], v[38:39], off
	global_load_dwordx4 v[20:23], v[28:29], off offset:16
	global_load_dwordx4 v[24:27], v[28:29], off offset:32
	s_nop 0
	global_load_dwordx4 v[28:31], v[28:29], off offset:48
	v_mov_b32_e32 v32, v1
	v_mov_b32_e32 v33, v1
	v_mov_b32_e32 v34, v1
	v_mov_b32_e32 v35, v1
	s_waitcnt vmcnt(3)
	v_mul_f32_e32 v5, 0x42800000, v16
	v_mul_f32_e32 v7, 0x42800000, v17
	v_mul_f32_e32 v15, 0x42800000, v18
	v_mul_f32_e32 v16, 0x42800000, v19
	s_waitcnt vmcnt(2)
	v_mul_f32_e32 v17, 0x42800000, v20
	v_mul_f32_e32 v18, 0x42800000, v21
	v_mul_f32_e32 v19, 0x42800000, v22
	v_mul_f32_e32 v20, 0x42800000, v23
	s_waitcnt vmcnt(1)
; __global__ void __launch_bounds__(512) mega(Params P) {
;     ...
;         const int t = c >> 9; const size_t off = (size_t)(c & 511) * 32768;
;         const float* src = ((t & 1) ? P.peer_v : P.peer_u) + (size_t)(t >> 1) * 16384 * 1024 + off;
;         unsigned char* dst = ws + WS_TAB + (size_t)t * 16 * MB + off;
; #pragma unroll
;         for (int it = 0; it < 4; ++it) {
;           const size_t i = (size_t)(it * 512 + tid) * 16;
;           u32x4 o;
; #pragma unroll
;           for (int q = 0; q < 4; ++q) {
;             const f32x4 a = *(const f32x4*)(src + i + 4 * q);
;             int d = __builtin_amdgcn_cvt_pk_fp8_f32(a[0] * 64.f, a[1] * 64.f, 0, false);
;             d = __builtin_amdgcn_cvt_pk_fp8_f32(a[2] * 64.f, a[3] * 64.f, d, true);
;             o[q] = (unsigned)d;
;           }
;           *(u32x4*)(dst + i) = o;
;         }
	v_mul_f32_e32 v21, 0x42800000, v24
	v_mul_f32_e32 v22, 0x42800000, v25
	v_mul_f32_e32 v23, 0x42800000, v26
	s_waitcnt vmcnt(0)
	v_mul_f32_e32 v25, 0x42800000, v28
	v_mul_f32_e32 v26, 0x42800000, v29
	v_cvt_pk_fp8_f32 v32, v5, v7
	v_cvt_pk_fp8_f32 v33, v17, v18
	v_cvt_pk_fp8_f32 v34, v21, v22
	v_cvt_pk_fp8_f32 v35, v25, v26
	v_mul_f32_e32 v24, 0x42800000, v27
	v_mul_f32_e32 v27, 0x42800000, v30
	v_mul_f32_e32 v28, 0x42800000, v31
	v_cvt_pk_fp8_f32 v32, v15, v16 op_sel:[0,0,1]
	v_cvt_pk_fp8_f32 v33, v19, v20 op_sel:[0,0,1]
	v_cvt_pk_fp8_f32 v34, v23, v24 op_sel:[0,0,1]
	v_cvt_pk_fp8_f32 v35, v27, v28 op_sel:[0,0,1]
	v_add_co_u32_e32 v16, vcc, s26, v40
	s_nop 1
	v_addc_co_u32_e32 v17, vcc, 0, v41, vcc
	global_store_dwordx4 v[254:255], v[32:35], off offset:1024
	global_load_dwordx4 v[16:19], v0, s[16:17]
	s_nop 0
	global_load_dwordx4 v[20:23], v0, s[16:17] offset:16
	global_load_dwordx4 v[24:27], v0, s[16:17] offset:32
	global_load_dwordx4 v[28:31], v0, s[16:17] offset:48
	v_mov_b32_e32 v32, v1
	v_mov_b32_e32 v33, v1
	v_mov_b32_e32 v34, v1
	v_mov_b32_e32 v35, v1
	s_waitcnt vmcnt(3)
	v_mul_f32_e32 v0, 0x42800000, v16
	v_mul_f32_e32 v5, 0x42800000, v17
	s_waitcnt vmcnt(2)
	v_mul_f32_e32 v16, 0x42800000, v20
	v_mul_f32_e32 v17, 0x42800000, v21
	s_waitcnt vmcnt(1)
	v_mul_f32_e32 v20, 0x42800000, v24
	v_mul_f32_e32 v21, 0x42800000, v25
	s_waitcnt vmcnt(0)
	v_mul_f32_e32 v24, 0x42800000, v28
	v_mul_f32_e32 v25, 0x42800000, v29
	v_cvt_pk_fp8_f32 v32, v0, v5
	v_cvt_pk_fp8_f32 v33, v16, v17
	v_cvt_pk_fp8_f32 v34, v20, v21
	v_cvt_pk_fp8_f32 v35, v24, v25
	v_mul_f32_e32 v7, 0x42800000, v18
	v_mul_f32_e32 v15, 0x42800000, v19
	v_mul_f32_e32 v18, 0x42800000, v22
	v_mul_f32_e32 v19, 0x42800000, v23
	v_mul_f32_e32 v22, 0x42800000, v26
	v_mul_f32_e32 v23, 0x42800000, v27
	v_mul_f32_e32 v26, 0x42800000, v30
	v_mul_f32_e32 v27, 0x42800000, v31
	v_cvt_pk_fp8_f32 v32, v7, v15 op_sel:[0,0,1]
	v_cvt_pk_fp8_f32 v33, v18, v19 op_sel:[0,0,1]
	v_cvt_pk_fp8_f32 v34, v22, v23 op_sel:[0,0,1]
	v_cvt_pk_fp8_f32 v35, v26, v27 op_sel:[0,0,1]
	v_add_co_u32_e32 v16, vcc, s61, v36
	v_lshl_add_u64 v[18:19], s[18:19], 0, v[2:3]
	s_nop 0
	v_addc_co_u32_e32 v17, vcc, 0, v37, vcc
	global_store_dwordx4 v[254:255], v[32:35], off offset:2048
	v_lshl_add_u64 v[28:29], v[36:37], 0, s[14:15]
	global_load_dwordx4 v[16:19], v[16:17], off
	s_nop 0
	global_load_dwordx4 v[20:23], v[28:29], off offset:16
	global_load_dwordx4 v[24:27], v[28:29], off offset:32
	s_nop 0
	global_load_dwordx4 v[28:31], v[28:29], off offset:48
	v_mov_b32_e32 v32, v1
	v_mov_b32_e32 v33, v1
	v_mov_b32_e32 v34, v1
	v_mov_b32_e32 v35, v1
	s_waitcnt vmcnt(3)
	v_mul_f32_e32 v0, 0x42800000, v16
	v_mul_f32_e32 v5, 0x42800000, v17
	s_waitcnt vmcnt(2)
	v_mul_f32_e32 v16, 0x42800000, v20
	v_mul_f32_e32 v17, 0x42800000, v21
	s_waitcnt vmcnt(1)
	v_mul_f32_e32 v20, 0x42800000, v24
	v_mul_f32_e32 v21, 0x42800000, v25
	s_waitcnt vmcnt(0)
	v_mul_f32_e32 v24, 0x42800000, v28
	v_mul_f32_e32 v25, 0x42800000, v29
	v_cvt_pk_fp8_f32 v32, v0, v5
	v_cvt_pk_fp8_f32 v33, v16, v17
	v_cvt_pk_fp8_f32 v34, v20, v21
	v_cvt_pk_fp8_f32 v35, v24, v25
	v_mul_f32_e32 v7, 0x42800000, v18
	v_mul_f32_e32 v15, 0x42800000, v19
	v_mul_f32_e32 v18, 0x42800000, v22
	v_mul_f32_e32 v19, 0x42800000, v23
	v_mul_f32_e32 v22, 0x42800000, v26
	v_mul_f32_e32 v23, 0x42800000, v27
	v_mul_f32_e32 v26, 0x42800000, v30
	v_mul_f32_e32 v27, 0x42800000, v31
	v_cvt_pk_fp8_f32 v32, v7, v15 op_sel:[0,0,1]
	v_cvt_pk_fp8_f32 v33, v18, v19 op_sel:[0,0,1]
	v_cvt_pk_fp8_f32 v34, v22, v23 op_sel:[0,0,1]
	v_cvt_pk_fp8_f32 v35, v26, v27 op_sel:[0,0,1]
	v_add_co_u32_e32 v16, vcc, 0x6000, v40
	s_nop 1
	v_addc_co_u32_e32 v17, vcc, 0, v41, vcc
	global_store_dwordx4 v[254:255], v[32:35], off offset:3072
	s_branch .LBB0_198

; DEV void sort_lists(int lane, int& myi0, int& myi1, float& myg0, float& myg1) {
; #pragma unroll
;     for (int k = 2; k <= 128; k <<= 1) {
; #pragma unroll
;       for (int j = k >> 1; j >= 1; j >>= 1) {
;         if (j == 64) {
;           const bool sw_ = myi1 < myi0;
;           const int ti = sw_ ? myi1 : myi0, tj = sw_ ? myi0 : myi1; const float tg = sw_ ? myg1 : myg0, th = sw_ ? myg0 : myg1;
;           myi0 = ti; myi1 = tj; myg0 = tg; myg1 = th;
;         } else {
;           const bool lower = (lane & j) == 0;
;           {
;             const bool up = (k == 128) ? true : ((k == 64) ? true : ((lane & k) == 0));
;             const int oi = __shfl_xor(myi0, j); const float og = __shfl_xor(myg0, j);
;             const bool take = (lower == up) ? (oi < myi0) : (oi > myi0);
;             myi0 = take ? oi : myi0; myg0 = take ? og : myg0;
;           }
;           {
;             const bool up = (k == 128) ? true : ((k == 64) ? false : ((lane & k) == 0));
;             const int oi = __shfl_xor(myi1, j); const float og = __shfl_xor(myg1, j);
;             const bool take = (lower == up) ? (oi < myi1) : (oi > myi1);
;             myi1 = take ? oi : myi1; myg1 = take ? og : myg1;
;           }
;         }
;       }
;     }
; }
; DEV void peer_gather(const Params& P, int l, int m0, const int* idxs, const float* gs) {
;     ...
;   int ni0 = idxs[(wid * 16) * 128 + lane], ni1 = idxs[(wid * 16) * 128 + 64 + lane];
;   float ng0 = gs[(wid * 16) * 128 + lane], ng1 = gs[(wid * 16) * 128 + 64 + lane];
.Lpg0_p0:
	v_readlane_b32 s82, v231, 26
	v_readlane_b32 s83, v231, 27
	s_nop 4
	s_lshl_b32 s98, s2, 2
	s_add_u32 s98, s98, s33
	s_add_u32 s98, s98, 0
	s_lshl_b32 s98, s98, 9
	v_add_u32_e32 v116, s98, v234
	global_load_dword v241, v116, s[82:83]
	global_load_dword v242, v116, s[82:83] offset:256
	s_lshl_b32 s98, s2, 2
	s_add_u32 s98, s98, s33
	s_add_u32 s98, s98, 1
	s_lshl_b32 s98, s98, 9
	v_add_u32_e32 v117, s98, v234
	global_load_dword v243, v117, s[82:83]
	global_load_dword v244, v117, s[82:83] offset:256
	s_lshl_b32 s98, s2, 2
	s_add_u32 s98, s98, s33
	s_add_u32 s98, s98, 2
	s_lshl_b32 s98, s98, 9
	v_add_u32_e32 v118, s98, v234
	global_load_dword v245, v118, s[82:83]
	global_load_dword v246, v118, s[82:83] offset:256
	s_lshl_b32 s98, s2, 2
	s_add_u32 s98, s98, s33
	s_add_u32 s98, s98, 3
	s_lshl_b32 s98, s98, 9
	v_add_u32_e32 v119, s98, v234
	global_load_dword v247, v119, s[82:83]
	global_load_dword v248, v119, s[82:83] offset:256
	s_waitcnt vmcnt(0)
	v_or_b32_e32 v116, 64, v233
	v_lshl_or_b32 v241, v241, 7, v233
	v_lshl_or_b32 v242, v242, 7, v116
	v_lshl_or_b32 v243, v243, 7, v233
	v_lshl_or_b32 v244, v244, 7, v116
	v_lshl_or_b32 v245, v245, 7, v233
	v_lshl_or_b32 v246, v246, 7, v116
	v_lshl_or_b32 v247, v247, 7, v233
	v_lshl_or_b32 v248, v248, 7, v116
	v_xor_b32_e32 v116, 4, v234
	ds_bpermute_b32 v0, v116, v241
	ds_bpermute_b32 v1, v116, v243
	ds_bpermute_b32 v2, v116, v245
	ds_bpermute_b32 v3, v116, v247
	ds_bpermute_b32 v4, v116, v242
	ds_bpermute_b32 v5, v116, v244
	ds_bpermute_b32 v6, v116, v246
	ds_bpermute_b32 v7, v116, v248
	s_waitcnt lgkmcnt(0)
	s_mov_b32 s88, 0x99999999
	s_mov_b32 s89, 0x99999999
	v_min_u32_e32 v104, v241, v0
	v_max_u32_e32 v105, v241, v0
	v_cndmask_b32_e64 v241, v105, v104, s[88:89]
	v_min_u32_e32 v106, v243, v1
	v_max_u32_e32 v107, v243, v1
	v_cndmask_b32_e64 v243, v107, v106, s[88:89]
	v_min_u32_e32 v104, v245, v2
	v_max_u32_e32 v105, v245, v2
	v_cndmask_b32_e64 v245, v105, v104, s[88:89]
	v_min_u32_e32 v106, v247, v3
	v_max_u32_e32 v107, v247, v3
	v_cndmask_b32_e64 v247, v107, v106, s[88:89]
	v_min_u32_e32 v104, v242, v4
	v_max_u32_e32 v105, v242, v4
	v_cndmask_b32_e64 v242, v105, v104, s[88:89]
	v_min_u32_e32 v106, v244, v5
	v_max_u32_e32 v107, v244, v5
	v_cndmask_b32_e64 v244, v107, v106, s[88:89]
	v_min_u32_e32 v104, v246, v6
	v_max_u32_e32 v105, v246, v6
	v_cndmask_b32_e64 v246, v105, v104, s[88:89]
	v_min_u32_e32 v106, v248, v7
	v_max_u32_e32 v107, v248, v7
	v_cndmask_b32_e64 v248, v107, v106, s[88:89]
	v_xor_b32_e32 v116, 8, v234
	ds_bpermute_b32 v0, v116, v241
	ds_bpermute_b32 v1, v116, v243
	ds_bpermute_b32 v2, v116, v245
	ds_bpermute_b32 v3, v116, v247
	ds_bpermute_b32 v4, v116, v242
	ds_bpermute_b32 v5, v116, v244
	ds_bpermute_b32 v6, v116, v246
	ds_bpermute_b32 v7, v116, v248
	s_waitcnt lgkmcnt(0)
	s_mov_b32 s88, 0xc3c3c3c3
	s_mov_b32 s89, 0xc3c3c3c3
	v_min_u32_e32 v104, v241, v0
	v_max_u32_e32 v105, v241, v0
	v_cndmask_b32_e64 v241, v105, v104, s[88:89]
	v_min_u32_e32 v106, v243, v1
	v_max_u32_e32 v107, v243, v1
	v_cndmask_b32_e64 v243, v107, v106, s[88:89]
	v_min_u32_e32 v104, v245, v2
	v_max_u32_e32 v105, v245, v2
	v_cndmask_b32_e64 v245, v105, v104, s[88:89]
	v_min_u32_e32 v106, v247, v3
	v_max_u32_e32 v107, v247, v3
	v_cndmask_b32_e64 v247, v107, v106, s[88:89]
	v_min_u32_e32 v104, v242, v4
	v_max_u32_e32 v105, v242, v4
	v_cndmask_b32_e64 v242, v105, v104, s[88:89]
	v_min_u32_e32 v106, v244, v5
	v_max_u32_e32 v107, v244, v5
	v_cndmask_b32_e64 v244, v107, v106, s[88:89]
	v_min_u32_e32 v104, v246, v6
	v_max_u32_e32 v105, v246, v6
	v_cndmask_b32_e64 v246, v105, v104, s[88:89]
	v_min_u32_e32 v106, v248, v7
	v_max_u32_e32 v107, v248, v7
	v_cndmask_b32_e64 v248, v107, v106, s[88:89]
	v_xor_b32_e32 v116, 4, v234
	ds_bpermute_b32 v0, v116, v241
	ds_bpermute_b32 v1, v116, v243
	ds_bpermute_b32 v2, v116, v245
	ds_bpermute_b32 v3, v116, v247
	ds_bpermute_b32 v4, v116, v242
	ds_bpermute_b32 v5, v116, v244
	ds_bpermute_b32 v6, v116, v246
	ds_bpermute_b32 v7, v116, v248
	s_waitcnt lgkmcnt(0)
	s_mov_b32 s88, 0xa5a5a5a5
	s_mov_b32 s89, 0xa5a5a5a5
	v_min_u32_e32 v104, v241, v0
	v_max_u32_e32 v105, v241, v0
	v_cndmask_b32_e64 v241, v105, v104, s[88:89]
	v_min_u32_e32 v106, v243, v1
	v_max_u32_e32 v107, v243, v1
	v_cndmask_b32_e64 v243, v107, v106, s[88:89]
	v_min_u32_e32 v104, v245, v2
	v_max_u32_e32 v105, v245, v2
	v_cndmask_b32_e64 v245, v105, v104, s[88:89]
	v_min_u32_e32 v106, v247, v3
	v_max_u32_e32 v107, v247, v3
	v_cndmask_b32_e64 v247, v107, v106, s[88:89]
	v_min_u32_e32 v104, v242, v4
	v_max_u32_e32 v105, v242, v4
	v_cndmask_b32_e64 v242, v105, v104, s[88:89]
	v_min_u32_e32 v106, v244, v5
	v_max_u32_e32 v107, v244, v5
	v_cndmask_b32_e64 v244, v107, v106, s[88:89]
	v_min_u32_e32 v104, v246, v6
	v_max_u32_e32 v105, v246, v6
	v_cndmask_b32_e64 v246, v105, v104, s[88:89]
	v_min_u32_e32 v106, v248, v7
	v_max_u32_e32 v107, v248, v7
	v_cndmask_b32_e64 v248, v107, v106, s[88:89]
	v_xor_b32_e32 v116, 16, v234
	ds_bpermute_b32 v0, v116, v241
	ds_bpermute_b32 v1, v116, v243
	ds_bpermute_b32 v2, v116, v245
	ds_bpermute_b32 v3, v116, v247
	ds_bpermute_b32 v4, v116, v242
	ds_bpermute_b32 v5, v116, v244
	ds_bpermute_b32 v6, v116, v246
	ds_bpermute_b32 v7, v116, v248
	s_waitcnt lgkmcnt(0)
; DEV void sort_lists(int lane, int& myi0, int& myi1, float& myg0, float& myg1) {
; #pragma unroll
;     for (int k = 2; k <= 128; k <<= 1) {
; #pragma unroll
;       for (int j = k >> 1; j >= 1; j >>= 1) {
;         if (j == 64) {
;           const bool sw_ = myi1 < myi0;
;           const int ti = sw_ ? myi1 : myi0, tj = sw_ ? myi0 : myi1; const float tg = sw_ ? myg1 : myg0, th = sw_ ? myg0 : myg1;
;           myi0 = ti; myi1 = tj; myg0 = tg; myg1 = th;
;         } else {
;           const bool lower = (lane & j) == 0;
;           {
;             const bool up = (k == 128) ? true : ((k == 64) ? true : ((lane & k) == 0));
;             const int oi = __shfl_xor(myi0, j); const float og = __shfl_xor(myg0, j);
;             const bool take = (lower == up) ? (oi < myi0) : (oi > myi0);
;             myi0 = take ? oi : myi0; myg0 = take ? og : myg0;
;           }
;           {
;             const bool up = (k == 128) ? true : ((k == 64) ? false : ((lane & k) == 0));
;             const int oi = __shfl_xor(myi1, j); const float og = __shfl_xor(myg1, j);
;             const bool take = (lower == up) ? (oi < myi1) : (oi > myi1);
;             myi1 = take ? oi : myi1; myg1 = take ? og : myg1;
;           }
;         }
;       }
;     }
; }
	s_mov_b32 s88, 0xf00ff00f
	s_mov_b32 s89, 0xf00ff00f
	v_min_u32_e32 v104, v241, v0
	v_max_u32_e32 v105, v241, v0
	v_cndmask_b32_e64 v241, v105, v104, s[88:89]
	v_min_u32_e32 v106, v243, v1
	v_max_u32_e32 v107, v243, v1
	v_cndmask_b32_e64 v243, v107, v106, s[88:89]
	v_min_u32_e32 v104, v245, v2
	v_max_u32_e32 v105, v245, v2
	v_cndmask_b32_e64 v245, v105, v104, s[88:89]
	v_min_u32_e32 v106, v247, v3
	v_max_u32_e32 v107, v247, v3
	v_cndmask_b32_e64 v247, v107, v106, s[88:89]
	v_min_u32_e32 v104, v242, v4
	v_max_u32_e32 v105, v242, v4
	v_cndmask_b32_e64 v242, v105, v104, s[88:89]
	v_min_u32_e32 v106, v244, v5
	v_max_u32_e32 v107, v244, v5
	v_cndmask_b32_e64 v244, v107, v106, s[88:89]
	v_min_u32_e32 v104, v246, v6
	v_max_u32_e32 v105, v246, v6
	v_cndmask_b32_e64 v246, v105, v104, s[88:89]
	v_min_u32_e32 v106, v248, v7
	v_max_u32_e32 v107, v248, v7
	v_cndmask_b32_e64 v248, v107, v106, s[88:89]
	v_xor_b32_e32 v116, 8, v234
	ds_bpermute_b32 v0, v116, v241
	ds_bpermute_b32 v1, v116, v243
	ds_bpermute_b32 v2, v116, v245
	ds_bpermute_b32 v3, v116, v247
	ds_bpermute_b32 v4, v116, v242
	ds_bpermute_b32 v5, v116, v244
	ds_bpermute_b32 v6, v116, v246
	ds_bpermute_b32 v7, v116, v248
	s_waitcnt lgkmcnt(0)
	s_mov_b32 s88, 0xcc33cc33
	s_mov_b32 s89, 0xcc33cc33
	v_min_u32_e32 v104, v241, v0
	v_max_u32_e32 v105, v241, v0
	v_cndmask_b32_e64 v241, v105, v104, s[88:89]
	v_min_u32_e32 v106, v243, v1
	v_max_u32_e32 v107, v243, v1
	v_cndmask_b32_e64 v243, v107, v106, s[88:89]
	v_min_u32_e32 v104, v245, v2
	v_max_u32_e32 v105, v245, v2
	v_cndmask_b32_e64 v245, v105, v104, s[88:89]
	v_min_u32_e32 v106, v247, v3
	v_max_u32_e32 v107, v247, v3
	v_cndmask_b32_e64 v247, v107, v106, s[88:89]
	v_min_u32_e32 v104, v242, v4
	v_max_u32_e32 v105, v242, v4
	v_cndmask_b32_e64 v242, v105, v104, s[88:89]
	v_min_u32_e32 v106, v244, v5
	v_max_u32_e32 v107, v244, v5
	v_cndmask_b32_e64 v244, v107, v106, s[88:89]
	v_min_u32_e32 v104, v246, v6
	v_max_u32_e32 v105, v246, v6
	v_cndmask_b32_e64 v246, v105, v104, s[88:89]
	v_min_u32_e32 v106, v248, v7
	v_max_u32_e32 v107, v248, v7
	v_cndmask_b32_e64 v248, v107, v106, s[88:89]
	v_xor_b32_e32 v116, 4, v234
	ds_bpermute_b32 v0, v116, v241
	ds_bpermute_b32 v1, v116, v243
	ds_bpermute_b32 v2, v116, v245
	ds_bpermute_b32 v3, v116, v247
	ds_bpermute_b32 v4, v116, v242
	ds_bpermute_b32 v5, v116, v244
	ds_bpermute_b32 v6, v116, v246
	ds_bpermute_b32 v7, v116, v248
	s_waitcnt lgkmcnt(0)
	s_mov_b32 s88, 0xaa55aa55
	s_mov_b32 s89, 0xaa55aa55
	v_min_u32_e32 v104, v241, v0
	v_max_u32_e32 v105, v241, v0
	v_cndmask_b32_e64 v241, v105, v104, s[88:89]
	v_min_u32_e32 v106, v243, v1
	v_max_u32_e32 v107, v243, v1
	v_cndmask_b32_e64 v243, v107, v106, s[88:89]
	v_min_u32_e32 v104, v245, v2
	v_max_u32_e32 v105, v245, v2
	v_cndmask_b32_e64 v245, v105, v104, s[88:89]
	v_min_u32_e32 v106, v247, v3
	v_max_u32_e32 v107, v247, v3
	v_cndmask_b32_e64 v247, v107, v106, s[88:89]
	v_min_u32_e32 v104, v242, v4
	v_max_u32_e32 v105, v242, v4
	v_cndmask_b32_e64 v242, v105, v104, s[88:89]
	v_min_u32_e32 v106, v244, v5
	v_max_u32_e32 v107, v244, v5
	v_cndmask_b32_e64 v244, v107, v106, s[88:89]
	v_min_u32_e32 v104, v246, v6
	v_max_u32_e32 v105, v246, v6
	v_cndmask_b32_e64 v246, v105, v104, s[88:89]
	v_min_u32_e32 v106, v248, v7
	v_max_u32_e32 v107, v248, v7
	v_cndmask_b32_e64 v248, v107, v106, s[88:89]
	v_xor_b32_e32 v116, 32, v234
	ds_bpermute_b32 v0, v116, v241
	ds_bpermute_b32 v1, v116, v243
	ds_bpermute_b32 v2, v116, v245
	ds_bpermute_b32 v3, v116, v247
	ds_bpermute_b32 v4, v116, v242
	ds_bpermute_b32 v5, v116, v244
	ds_bpermute_b32 v6, v116, v246
	ds_bpermute_b32 v7, v116, v248
	s_waitcnt lgkmcnt(0)
	s_mov_b32 s88, 0xff0000ff
	s_mov_b32 s89, 0xff0000ff
	v_min_u32_e32 v104, v241, v0
	v_max_u32_e32 v105, v241, v0
	v_cndmask_b32_e64 v241, v105, v104, s[88:89]
	v_min_u32_e32 v106, v243, v1
	v_max_u32_e32 v107, v243, v1
	v_cndmask_b32_e64 v243, v107, v106, s[88:89]
	v_min_u32_e32 v104, v245, v2
	v_max_u32_e32 v105, v245, v2
	v_cndmask_b32_e64 v245, v105, v104, s[88:89]
	v_min_u32_e32 v106, v247, v3
	v_max_u32_e32 v107, v247, v3
	v_cndmask_b32_e64 v247, v107, v106, s[88:89]
	v_min_u32_e32 v104, v242, v4
	v_max_u32_e32 v105, v242, v4
	v_cndmask_b32_e64 v242, v105, v104, s[88:89]
	v_min_u32_e32 v106, v244, v5
	v_max_u32_e32 v107, v244, v5
	v_cndmask_b32_e64 v244, v107, v106, s[88:89]
	v_min_u32_e32 v104, v246, v6
	v_max_u32_e32 v105, v246, v6
	v_cndmask_b32_e64 v246, v105, v104, s[88:89]
	v_min_u32_e32 v106, v248, v7
	v_max_u32_e32 v107, v248, v7
	v_cndmask_b32_e64 v248, v107, v106, s[88:89]
	v_xor_b32_e32 v116, 16, v234
	ds_bpermute_b32 v0, v116, v241
	ds_bpermute_b32 v1, v116, v243
	ds_bpermute_b32 v2, v116, v245
	ds_bpermute_b32 v3, v116, v247
	ds_bpermute_b32 v4, v116, v242
	ds_bpermute_b32 v5, v116, v244
	ds_bpermute_b32 v6, v116, v246
	ds_bpermute_b32 v7, v116, v248
	s_waitcnt lgkmcnt(0)
	s_mov_b32 s88, 0xf0f00f0f
	s_mov_b32 s89, 0xf0f00f0f
	v_min_u32_e32 v104, v241, v0
	v_max_u32_e32 v105, v241, v0
	v_cndmask_b32_e64 v241, v105, v104, s[88:89]
	v_min_u32_e32 v106, v243, v1
	v_max_u32_e32 v107, v243, v1
	v_cndmask_b32_e64 v243, v107, v106, s[88:89]
	v_min_u32_e32 v104, v245, v2
	v_max_u32_e32 v105, v245, v2
	v_cndmask_b32_e64 v245, v105, v104, s[88:89]
	v_min_u32_e32 v106, v247, v3
	v_max_u32_e32 v107, v247, v3
	v_cndmask_b32_e64 v247, v107, v106, s[88:89]
	v_min_u32_e32 v104, v242, v4
	v_max_u32_e32 v105, v242, v4
	v_cndmask_b32_e64 v242, v105, v104, s[88:89]
	v_min_u32_e32 v106, v244, v5
	v_max_u32_e32 v107, v244, v5
	v_cndmask_b32_e64 v244, v107, v106, s[88:89]
	v_min_u32_e32 v104, v246, v6
	v_max_u32_e32 v105, v246, v6
	v_cndmask_b32_e64 v246, v105, v104, s[88:89]
	v_min_u32_e32 v106, v248, v7
	v_max_u32_e32 v107, v248, v7
	v_cndmask_b32_e64 v248, v107, v106, s[88:89]
	v_xor_b32_e32 v116, 8, v234
	ds_bpermute_b32 v0, v116, v241
	ds_bpermute_b32 v1, v116, v243
	ds_bpermute_b32 v2, v116, v245
	ds_bpermute_b32 v3, v116, v247
	ds_bpermute_b32 v4, v116, v242
	ds_bpermute_b32 v5, v116, v244
	ds_bpermute_b32 v6, v116, v246
	ds_bpermute_b32 v7, v116, v248
	s_waitcnt lgkmcnt(0)
; DEV void sort_lists(int lane, int& myi0, int& myi1, float& myg0, float& myg1) {
; #pragma unroll
;     for (int k = 2; k <= 128; k <<= 1) {
; #pragma unroll
;       for (int j = k >> 1; j >= 1; j >>= 1) {
;         if (j == 64) {
;           const bool sw_ = myi1 < myi0;
;           const int ti = sw_ ? myi1 : myi0, tj = sw_ ? myi0 : myi1; const float tg = sw_ ? myg1 : myg0, th = sw_ ? myg0 : myg1;
;           myi0 = ti; myi1 = tj; myg0 = tg; myg1 = th;
;         } else {
;           const bool lower = (lane & j) == 0;
;           {
;             const bool up = (k == 128) ? true : ((k == 64) ? true : ((lane & k) == 0));
;             const int oi = __shfl_xor(myi0, j); const float og = __shfl_xor(myg0, j);
;             const bool take = (lower == up) ? (oi < myi0) : (oi > myi0);
;             myi0 = take ? oi : myi0; myg0 = take ? og : myg0;
;           }
;           {
;             const bool up = (k == 128) ? true : ((k == 64) ? false : ((lane & k) == 0));
;             const int oi = __shfl_xor(myi1, j); const float og = __shfl_xor(myg1, j);
;             const bool take = (lower == up) ? (oi < myi1) : (oi > myi1);
;             myi1 = take ? oi : myi1; myg1 = take ? og : myg1;
;           }
;         }
;       }
;     }
; }
	s_mov_b32 s88, 0xcccc3333
	s_mov_b32 s89, 0xcccc3333
	v_min_u32_e32 v104, v241, v0
	v_max_u32_e32 v105, v241, v0
	v_cndmask_b32_e64 v241, v105, v104, s[88:89]
	v_min_u32_e32 v106, v243, v1
	v_max_u32_e32 v107, v243, v1
	v_cndmask_b32_e64 v243, v107, v106, s[88:89]
	v_min_u32_e32 v104, v245, v2
	v_max_u32_e32 v105, v245, v2
	v_cndmask_b32_e64 v245, v105, v104, s[88:89]
	v_min_u32_e32 v106, v247, v3
	v_max_u32_e32 v107, v247, v3
	v_cndmask_b32_e64 v247, v107, v106, s[88:89]
	v_min_u32_e32 v104, v242, v4
	v_max_u32_e32 v105, v242, v4
	v_cndmask_b32_e64 v242, v105, v104, s[88:89]
	v_min_u32_e32 v106, v244, v5
	v_max_u32_e32 v107, v244, v5
	v_cndmask_b32_e64 v244, v107, v106, s[88:89]
	v_min_u32_e32 v104, v246, v6
	v_max_u32_e32 v105, v246, v6
	v_cndmask_b32_e64 v246, v105, v104, s[88:89]
	v_min_u32_e32 v106, v248, v7
	v_max_u32_e32 v107, v248, v7
	v_cndmask_b32_e64 v248, v107, v106, s[88:89]
	v_xor_b32_e32 v116, 4, v234
	ds_bpermute_b32 v0, v116, v241
	ds_bpermute_b32 v1, v116, v243
	ds_bpermute_b32 v2, v116, v245
	ds_bpermute_b32 v3, v116, v247
	ds_bpermute_b32 v4, v116, v242
	ds_bpermute_b32 v5, v116, v244
	ds_bpermute_b32 v6, v116, v246
	ds_bpermute_b32 v7, v116, v248
	s_waitcnt lgkmcnt(0)
	s_mov_b32 s88, 0xaaaa5555
	s_mov_b32 s89, 0xaaaa5555
	v_min_u32_e32 v104, v241, v0
	v_max_u32_e32 v105, v241, v0
	v_cndmask_b32_e64 v241, v105, v104, s[88:89]
	v_min_u32_e32 v106, v243, v1
	v_max_u32_e32 v107, v243, v1
	v_cndmask_b32_e64 v243, v107, v106, s[88:89]
	v_min_u32_e32 v104, v245, v2
	v_max_u32_e32 v105, v245, v2
	v_cndmask_b32_e64 v245, v105, v104, s[88:89]
	v_min_u32_e32 v106, v247, v3
	v_max_u32_e32 v107, v247, v3
	v_cndmask_b32_e64 v247, v107, v106, s[88:89]
	v_min_u32_e32 v104, v242, v4
	v_max_u32_e32 v105, v242, v4
	v_cndmask_b32_e64 v242, v105, v104, s[88:89]
	v_min_u32_e32 v106, v244, v5
	v_max_u32_e32 v107, v244, v5
	v_cndmask_b32_e64 v244, v107, v106, s[88:89]
	v_min_u32_e32 v104, v246, v6
	v_max_u32_e32 v105, v246, v6
	v_cndmask_b32_e64 v246, v105, v104, s[88:89]
	v_min_u32_e32 v106, v248, v7
	v_max_u32_e32 v107, v248, v7
	v_cndmask_b32_e64 v248, v107, v106, s[88:89]
	v_xor_b32_e32 v116, 64, v234
	ds_bpermute_b32 v0, v116, v241
	ds_bpermute_b32 v1, v116, v243
	ds_bpermute_b32 v2, v116, v245
	ds_bpermute_b32 v3, v116, v247
	ds_bpermute_b32 v4, v116, v242
	ds_bpermute_b32 v5, v116, v244
	ds_bpermute_b32 v6, v116, v246
	ds_bpermute_b32 v7, v116, v248
	s_waitcnt lgkmcnt(0)
	s_mov_b32 s88, 0xffff
	s_mov_b32 s89, 0xffff0000
	v_min_u32_e32 v104, v241, v0
	v_max_u32_e32 v105, v241, v0
	v_cndmask_b32_e64 v241, v105, v104, s[88:89]
	v_min_u32_e32 v106, v243, v1
	v_max_u32_e32 v107, v243, v1
	v_cndmask_b32_e64 v243, v107, v106, s[88:89]
	v_min_u32_e32 v104, v245, v2
	v_max_u32_e32 v105, v245, v2
	v_cndmask_b32_e64 v245, v105, v104, s[88:89]
	v_min_u32_e32 v106, v247, v3
	v_max_u32_e32 v107, v247, v3
	v_cndmask_b32_e64 v247, v107, v106, s[88:89]
	v_min_u32_e32 v104, v242, v4
	v_max_u32_e32 v105, v242, v4
	v_cndmask_b32_e64 v242, v105, v104, s[88:89]
	v_min_u32_e32 v106, v244, v5
	v_max_u32_e32 v107, v244, v5
	v_cndmask_b32_e64 v244, v107, v106, s[88:89]
	v_min_u32_e32 v104, v246, v6
	v_max_u32_e32 v105, v246, v6
	v_cndmask_b32_e64 v246, v105, v104, s[88:89]
	v_min_u32_e32 v106, v248, v7
	v_max_u32_e32 v107, v248, v7
	v_cndmask_b32_e64 v248, v107, v106, s[88:89]
	v_xor_b32_e32 v116, 32, v234
	ds_bpermute_b32 v0, v116, v241
	ds_bpermute_b32 v1, v116, v243
	ds_bpermute_b32 v2, v116, v245
	ds_bpermute_b32 v3, v116, v247
	ds_bpermute_b32 v4, v116, v242
	ds_bpermute_b32 v5, v116, v244
	ds_bpermute_b32 v6, v116, v246
	ds_bpermute_b32 v7, v116, v248
	s_waitcnt lgkmcnt(0)
	s_mov_b32 s88, 0xff00ff
	s_mov_b32 s89, 0xff00ff00
	v_min_u32_e32 v104, v241, v0
	v_max_u32_e32 v105, v241, v0
	v_cndmask_b32_e64 v241, v105, v104, s[88:89]
	v_min_u32_e32 v106, v243, v1
	v_max_u32_e32 v107, v243, v1
	v_cndmask_b32_e64 v243, v107, v106, s[88:89]
	v_min_u32_e32 v104, v245, v2
	v_max_u32_e32 v105, v245, v2
	v_cndmask_b32_e64 v245, v105, v104, s[88:89]
	v_min_u32_e32 v106, v247, v3
	v_max_u32_e32 v107, v247, v3
	v_cndmask_b32_e64 v247, v107, v106, s[88:89]
	v_min_u32_e32 v104, v242, v4
	v_max_u32_e32 v105, v242, v4
	v_cndmask_b32_e64 v242, v105, v104, s[88:89]
	v_min_u32_e32 v106, v244, v5
	v_max_u32_e32 v107, v244, v5
	v_cndmask_b32_e64 v244, v107, v106, s[88:89]
	v_min_u32_e32 v104, v246, v6
	v_max_u32_e32 v105, v246, v6
	v_cndmask_b32_e64 v246, v105, v104, s[88:89]
	v_min_u32_e32 v106, v248, v7
	v_max_u32_e32 v107, v248, v7
	v_cndmask_b32_e64 v248, v107, v106, s[88:89]
	v_xor_b32_e32 v116, 16, v234
	ds_bpermute_b32 v0, v116, v241
	ds_bpermute_b32 v1, v116, v243
	ds_bpermute_b32 v2, v116, v245
	ds_bpermute_b32 v3, v116, v247
	ds_bpermute_b32 v4, v116, v242
	ds_bpermute_b32 v5, v116, v244
	ds_bpermute_b32 v6, v116, v246
	ds_bpermute_b32 v7, v116, v248
	s_waitcnt lgkmcnt(0)
	s_mov_b32 s88, 0xf0f0f0f
	s_mov_b32 s89, 0xf0f0f0f0
	v_min_u32_e32 v104, v241, v0
	v_max_u32_e32 v105, v241, v0
	v_cndmask_b32_e64 v241, v105, v104, s[88:89]
	v_min_u32_e32 v106, v243, v1
	v_max_u32_e32 v107, v243, v1
	v_cndmask_b32_e64 v243, v107, v106, s[88:89]
	v_min_u32_e32 v104, v245, v2
	v_max_u32_e32 v105, v245, v2
	v_cndmask_b32_e64 v245, v105, v104, s[88:89]
	v_min_u32_e32 v106, v247, v3
	v_max_u32_e32 v107, v247, v3
	v_cndmask_b32_e64 v247, v107, v106, s[88:89]
	v_min_u32_e32 v104, v242, v4
	v_max_u32_e32 v105, v242, v4
	v_cndmask_b32_e64 v242, v105, v104, s[88:89]
	v_min_u32_e32 v106, v244, v5
	v_max_u32_e32 v107, v244, v5
	v_cndmask_b32_e64 v244, v107, v106, s[88:89]
	v_min_u32_e32 v104, v246, v6
	v_max_u32_e32 v105, v246, v6
	v_cndmask_b32_e64 v246, v105, v104, s[88:89]
	v_min_u32_e32 v106, v248, v7
	v_max_u32_e32 v107, v248, v7
	v_cndmask_b32_e64 v248, v107, v106, s[88:89]
	v_xor_b32_e32 v116, 8, v234
	ds_bpermute_b32 v0, v116, v241
	ds_bpermute_b32 v1, v116, v243
	ds_bpermute_b32 v2, v116, v245
	ds_bpermute_b32 v3, v116, v247
	ds_bpermute_b32 v4, v116, v242
	ds_bpermute_b32 v5, v116, v244
	ds_bpermute_b32 v6, v116, v246
	ds_bpermute_b32 v7, v116, v248
	s_waitcnt lgkmcnt(0)
; DEV void sort_lists(int lane, int& myi0, int& myi1, float& myg0, float& myg1) {
; #pragma unroll
;     for (int k = 2; k <= 128; k <<= 1) {
; #pragma unroll
;       for (int j = k >> 1; j >= 1; j >>= 1) {
;         if (j == 64) {
;           const bool sw_ = myi1 < myi0;
;           const int ti = sw_ ? myi1 : myi0, tj = sw_ ? myi0 : myi1; const float tg = sw_ ? myg1 : myg0, th = sw_ ? myg0 : myg1;
;           myi0 = ti; myi1 = tj; myg0 = tg; myg1 = th;
;         } else {
;           const bool lower = (lane & j) == 0;
;           {
;             const bool up = (k == 128) ? true : ((k == 64) ? true : ((lane & k) == 0));
;             const int oi = __shfl_xor(myi0, j); const float og = __shfl_xor(myg0, j);
;             const bool take = (lower == up) ? (oi < myi0) : (oi > myi0);
;             myi0 = take ? oi : myi0; myg0 = take ? og : myg0;
;           }
;           {
;             const bool up = (k == 128) ? true : ((k == 64) ? false : ((lane & k) == 0));
;             const int oi = __shfl_xor(myi1, j); const float og = __shfl_xor(myg1, j);
;             const bool take = (lower == up) ? (oi < myi1) : (oi > myi1);
;             myi1 = take ? oi : myi1; myg1 = take ? og : myg1;
;           }
;         }
;       }
;     }
; }
	s_mov_b32 s88, 0x33333333
	s_mov_b32 s89, 0xcccccccc
	v_min_u32_e32 v104, v241, v0
	v_max_u32_e32 v105, v241, v0
	v_cndmask_b32_e64 v241, v105, v104, s[88:89]
	v_min_u32_e32 v106, v243, v1
	v_max_u32_e32 v107, v243, v1
	v_cndmask_b32_e64 v243, v107, v106, s[88:89]
	v_min_u32_e32 v104, v245, v2
	v_max_u32_e32 v105, v245, v2
	v_cndmask_b32_e64 v245, v105, v104, s[88:89]
	v_min_u32_e32 v106, v247, v3
	v_max_u32_e32 v107, v247, v3
	v_cndmask_b32_e64 v247, v107, v106, s[88:89]
	v_min_u32_e32 v104, v242, v4
	v_max_u32_e32 v105, v242, v4
	v_cndmask_b32_e64 v242, v105, v104, s[88:89]
	v_min_u32_e32 v106, v244, v5
	v_max_u32_e32 v107, v244, v5
	v_cndmask_b32_e64 v244, v107, v106, s[88:89]
	v_min_u32_e32 v104, v246, v6
	v_max_u32_e32 v105, v246, v6
	v_cndmask_b32_e64 v246, v105, v104, s[88:89]
	v_min_u32_e32 v106, v248, v7
	v_max_u32_e32 v107, v248, v7
	v_cndmask_b32_e64 v248, v107, v106, s[88:89]
	v_xor_b32_e32 v116, 4, v234
	ds_bpermute_b32 v0, v116, v241
	ds_bpermute_b32 v1, v116, v243
	ds_bpermute_b32 v2, v116, v245
	ds_bpermute_b32 v3, v116, v247
	ds_bpermute_b32 v4, v116, v242
	ds_bpermute_b32 v5, v116, v244
	ds_bpermute_b32 v6, v116, v246
	ds_bpermute_b32 v7, v116, v248
	s_waitcnt lgkmcnt(0)
	s_mov_b32 s88, 0x55555555
	s_mov_b32 s89, 0xaaaaaaaa
	v_min_u32_e32 v104, v241, v0
	v_max_u32_e32 v105, v241, v0
	v_cndmask_b32_e64 v241, v105, v104, s[88:89]
	v_min_u32_e32 v106, v243, v1
	v_max_u32_e32 v107, v243, v1
	v_cndmask_b32_e64 v243, v107, v106, s[88:89]
	v_min_u32_e32 v104, v245, v2
	v_max_u32_e32 v105, v245, v2
	v_cndmask_b32_e64 v245, v105, v104, s[88:89]
	v_min_u32_e32 v106, v247, v3
	v_max_u32_e32 v107, v247, v3
	v_cndmask_b32_e64 v247, v107, v106, s[88:89]
	v_min_u32_e32 v104, v242, v4
	v_max_u32_e32 v105, v242, v4
	v_cndmask_b32_e64 v242, v105, v104, s[88:89]
	v_min_u32_e32 v106, v244, v5
	v_max_u32_e32 v107, v244, v5
	v_cndmask_b32_e64 v244, v107, v106, s[88:89]
	v_min_u32_e32 v104, v246, v6
	v_max_u32_e32 v105, v246, v6
	v_cndmask_b32_e64 v246, v105, v104, s[88:89]
	v_min_u32_e32 v106, v248, v7
	v_max_u32_e32 v107, v248, v7
	v_cndmask_b32_e64 v248, v107, v106, s[88:89]
	v_xor_b32_e32 v116, 128, v234
	ds_bpermute_b32 v0, v116, v241
	ds_bpermute_b32 v1, v116, v243
	ds_bpermute_b32 v2, v116, v245
	ds_bpermute_b32 v3, v116, v247
	ds_bpermute_b32 v4, v116, v242
	ds_bpermute_b32 v5, v116, v244
	ds_bpermute_b32 v6, v116, v246
	ds_bpermute_b32 v7, v116, v248
	s_waitcnt lgkmcnt(0)
	s_mov_b32 s88, 0xffffffff
	s_mov_b32 s89, 0x0
	v_min_u32_e32 v104, v241, v0
	v_max_u32_e32 v105, v241, v0
	v_cndmask_b32_e64 v241, v105, v104, s[88:89]
	v_min_u32_e32 v106, v243, v1
	v_max_u32_e32 v107, v243, v1
	v_cndmask_b32_e64 v243, v107, v106, s[88:89]
	v_min_u32_e32 v104, v245, v2
	v_max_u32_e32 v105, v245, v2
	v_cndmask_b32_e64 v245, v105, v104, s[88:89]
	v_min_u32_e32 v106, v247, v3
	v_max_u32_e32 v107, v247, v3
	v_cndmask_b32_e64 v247, v107, v106, s[88:89]
	s_mov_b32 s88, 0x0
	s_mov_b32 s89, 0xffffffff
	v_min_u32_e32 v104, v242, v4
	v_max_u32_e32 v105, v242, v4
	v_cndmask_b32_e64 v242, v105, v104, s[88:89]
	v_min_u32_e32 v106, v244, v5
	v_max_u32_e32 v107, v244, v5
	v_cndmask_b32_e64 v244, v107, v106, s[88:89]
	v_min_u32_e32 v104, v246, v6
	v_max_u32_e32 v105, v246, v6
	v_cndmask_b32_e64 v246, v105, v104, s[88:89]
	v_min_u32_e32 v106, v248, v7
	v_max_u32_e32 v107, v248, v7
	v_cndmask_b32_e64 v248, v107, v106, s[88:89]
	v_xor_b32_e32 v116, 64, v234
	ds_bpermute_b32 v0, v116, v241
	ds_bpermute_b32 v1, v116, v243
	ds_bpermute_b32 v2, v116, v245
	ds_bpermute_b32 v3, v116, v247
	ds_bpermute_b32 v4, v116, v242
	ds_bpermute_b32 v5, v116, v244
	ds_bpermute_b32 v6, v116, v246
	ds_bpermute_b32 v7, v116, v248
	s_waitcnt lgkmcnt(0)
	s_mov_b32 s88, 0xffff
	s_mov_b32 s89, 0xffff
	v_min_u32_e32 v104, v241, v0
	v_max_u32_e32 v105, v241, v0
	v_cndmask_b32_e64 v241, v105, v104, s[88:89]
	v_min_u32_e32 v106, v243, v1
	v_max_u32_e32 v107, v243, v1
	v_cndmask_b32_e64 v243, v107, v106, s[88:89]
	v_min_u32_e32 v104, v245, v2
	v_max_u32_e32 v105, v245, v2
	v_cndmask_b32_e64 v245, v105, v104, s[88:89]
	v_min_u32_e32 v106, v247, v3
	v_max_u32_e32 v107, v247, v3
	v_cndmask_b32_e64 v247, v107, v106, s[88:89]
	s_mov_b32 s88, 0xffff0000
	s_mov_b32 s89, 0xffff0000
	v_min_u32_e32 v104, v242, v4
	v_max_u32_e32 v105, v242, v4
	v_cndmask_b32_e64 v242, v105, v104, s[88:89]
	v_min_u32_e32 v106, v244, v5
	v_max_u32_e32 v107, v244, v5
	v_cndmask_b32_e64 v244, v107, v106, s[88:89]
	v_min_u32_e32 v104, v246, v6
	v_max_u32_e32 v105, v246, v6
	v_cndmask_b32_e64 v246, v105, v104, s[88:89]
	v_min_u32_e32 v106, v248, v7
	v_max_u32_e32 v107, v248, v7
	v_cndmask_b32_e64 v248, v107, v106, s[88:89]
	v_xor_b32_e32 v116, 32, v234
	ds_bpermute_b32 v0, v116, v241
	ds_bpermute_b32 v1, v116, v243
	ds_bpermute_b32 v2, v116, v245
	ds_bpermute_b32 v3, v116, v247
	ds_bpermute_b32 v4, v116, v242
	ds_bpermute_b32 v5, v116, v244
	ds_bpermute_b32 v6, v116, v246
	ds_bpermute_b32 v7, v116, v248
	s_waitcnt lgkmcnt(0)
	s_mov_b32 s88, 0xff00ff
	s_mov_b32 s89, 0xff00ff
	v_min_u32_e32 v104, v241, v0
	v_max_u32_e32 v105, v241, v0
	v_cndmask_b32_e64 v241, v105, v104, s[88:89]
	v_min_u32_e32 v106, v243, v1
	v_max_u32_e32 v107, v243, v1
	v_cndmask_b32_e64 v243, v107, v106, s[88:89]
	v_min_u32_e32 v104, v245, v2
	v_max_u32_e32 v105, v245, v2
	v_cndmask_b32_e64 v245, v105, v104, s[88:89]
	v_min_u32_e32 v106, v247, v3
	v_max_u32_e32 v107, v247, v3
	v_cndmask_b32_e64 v247, v107, v106, s[88:89]
	s_mov_b32 s88, 0xff00ff00
	s_mov_b32 s89, 0xff00ff00
	v_min_u32_e32 v104, v242, v4
	v_max_u32_e32 v105, v242, v4
	v_cndmask_b32_e64 v242, v105, v104, s[88:89]
	v_min_u32_e32 v106, v244, v5
	v_max_u32_e32 v107, v244, v5
	v_cndmask_b32_e64 v244, v107, v106, s[88:89]
	v_min_u32_e32 v104, v246, v6
	v_max_u32_e32 v105, v246, v6
	v_cndmask_b32_e64 v246, v105, v104, s[88:89]
	v_min_u32_e32 v106, v248, v7
	v_max_u32_e32 v107, v248, v7
	v_cndmask_b32_e64 v248, v107, v106, s[88:89]
	v_xor_b32_e32 v116, 16, v234
	ds_bpermute_b32 v0, v116, v241
	ds_bpermute_b32 v1, v116, v243
	ds_bpermute_b32 v2, v116, v245
	ds_bpermute_b32 v3, v116, v247
	ds_bpermute_b32 v4, v116, v242
	ds_bpermute_b32 v5, v116, v244
	ds_bpermute_b32 v6, v116, v246
	ds_bpermute_b32 v7, v116, v248
	s_waitcnt lgkmcnt(0)
; DEV void sort_lists(int lane, int& myi0, int& myi1, float& myg0, float& myg1) {
; #pragma unroll
;     for (int k = 2; k <= 128; k <<= 1) {
; #pragma unroll
;       for (int j = k >> 1; j >= 1; j >>= 1) {
;         if (j == 64) {
;           const bool sw_ = myi1 < myi0;
;           const int ti = sw_ ? myi1 : myi0, tj = sw_ ? myi0 : myi1; const float tg = sw_ ? myg1 : myg0, th = sw_ ? myg0 : myg1;
;           myi0 = ti; myi1 = tj; myg0 = tg; myg1 = th;
;         } else {
;           const bool lower = (lane & j) == 0;
;           {
;             const bool up = (k == 128) ? true : ((k == 64) ? true : ((lane & k) == 0));
;             const int oi = __shfl_xor(myi0, j); const float og = __shfl_xor(myg0, j);
;             const bool take = (lower == up) ? (oi < myi0) : (oi > myi0);
;             myi0 = take ? oi : myi0; myg0 = take ? og : myg0;
;           }
;           {
;             const bool up = (k == 128) ? true : ((k == 64) ? false : ((lane & k) == 0));
;             const int oi = __shfl_xor(myi1, j); const float og = __shfl_xor(myg1, j);
;             const bool take = (lower == up) ? (oi < myi1) : (oi > myi1);
;             myi1 = take ? oi : myi1; myg1 = take ? og : myg1;
;           }
;         }
;       }
;     }
; }
	s_mov_b32 s88, 0xf0f0f0f
	s_mov_b32 s89, 0xf0f0f0f
	v_min_u32_e32 v104, v241, v0
	v_max_u32_e32 v105, v241, v0
	v_cndmask_b32_e64 v241, v105, v104, s[88:89]
	v_min_u32_e32 v106, v243, v1
	v_max_u32_e32 v107, v243, v1
	v_cndmask_b32_e64 v243, v107, v106, s[88:89]
	v_min_u32_e32 v104, v245, v2
	v_max_u32_e32 v105, v245, v2
	v_cndmask_b32_e64 v245, v105, v104, s[88:89]
	v_min_u32_e32 v106, v247, v3
	v_max_u32_e32 v107, v247, v3
	v_cndmask_b32_e64 v247, v107, v106, s[88:89]
	s_mov_b32 s88, 0xf0f0f0f0
	s_mov_b32 s89, 0xf0f0f0f0
	v_min_u32_e32 v104, v242, v4
	v_max_u32_e32 v105, v242, v4
	v_cndmask_b32_e64 v242, v105, v104, s[88:89]
	v_min_u32_e32 v106, v244, v5
	v_max_u32_e32 v107, v244, v5
	v_cndmask_b32_e64 v244, v107, v106, s[88:89]
	v_min_u32_e32 v104, v246, v6
	v_max_u32_e32 v105, v246, v6
	v_cndmask_b32_e64 v246, v105, v104, s[88:89]
	v_min_u32_e32 v106, v248, v7
	v_max_u32_e32 v107, v248, v7
	v_cndmask_b32_e64 v248, v107, v106, s[88:89]
	v_xor_b32_e32 v116, 8, v234
	ds_bpermute_b32 v0, v116, v241
	ds_bpermute_b32 v1, v116, v243
	ds_bpermute_b32 v2, v116, v245
	ds_bpermute_b32 v3, v116, v247
	ds_bpermute_b32 v4, v116, v242
	ds_bpermute_b32 v5, v116, v244
	ds_bpermute_b32 v6, v116, v246
	ds_bpermute_b32 v7, v116, v248
	s_waitcnt lgkmcnt(0)
	s_mov_b32 s88, 0x33333333
	s_mov_b32 s89, 0x33333333
	v_min_u32_e32 v104, v241, v0
	v_max_u32_e32 v105, v241, v0
	v_cndmask_b32_e64 v241, v105, v104, s[88:89]
	v_min_u32_e32 v106, v243, v1
	v_max_u32_e32 v107, v243, v1
	v_cndmask_b32_e64 v243, v107, v106, s[88:89]
	v_min_u32_e32 v104, v245, v2
	v_max_u32_e32 v105, v245, v2
	v_cndmask_b32_e64 v245, v105, v104, s[88:89]
	v_min_u32_e32 v106, v247, v3
	v_max_u32_e32 v107, v247, v3
	v_cndmask_b32_e64 v247, v107, v106, s[88:89]
	s_mov_b32 s88, 0xcccccccc
	s_mov_b32 s89, 0xcccccccc
	v_min_u32_e32 v104, v242, v4
	v_max_u32_e32 v105, v242, v4
	v_cndmask_b32_e64 v242, v105, v104, s[88:89]
	v_min_u32_e32 v106, v244, v5
	v_max_u32_e32 v107, v244, v5
	v_cndmask_b32_e64 v244, v107, v106, s[88:89]
	v_min_u32_e32 v104, v246, v6
	v_max_u32_e32 v105, v246, v6
	v_cndmask_b32_e64 v246, v105, v104, s[88:89]
	v_min_u32_e32 v106, v248, v7
	v_max_u32_e32 v107, v248, v7
	v_cndmask_b32_e64 v248, v107, v106, s[88:89]
	v_xor_b32_e32 v116, 4, v234
	ds_bpermute_b32 v0, v116, v241
	ds_bpermute_b32 v1, v116, v243
	ds_bpermute_b32 v2, v116, v245
	ds_bpermute_b32 v3, v116, v247
	ds_bpermute_b32 v4, v116, v242
	ds_bpermute_b32 v5, v116, v244
	ds_bpermute_b32 v6, v116, v246
	ds_bpermute_b32 v7, v116, v248
	s_waitcnt lgkmcnt(0)
	s_mov_b32 s88, 0x55555555
	s_mov_b32 s89, 0x55555555
	v_min_u32_e32 v104, v241, v0
	v_max_u32_e32 v105, v241, v0
	v_cndmask_b32_e64 v241, v105, v104, s[88:89]
	v_min_u32_e32 v106, v243, v1
	v_max_u32_e32 v107, v243, v1
	v_cndmask_b32_e64 v243, v107, v106, s[88:89]
	v_min_u32_e32 v104, v245, v2
	v_max_u32_e32 v105, v245, v2
	v_cndmask_b32_e64 v245, v105, v104, s[88:89]
	v_min_u32_e32 v106, v247, v3
	v_max_u32_e32 v107, v247, v3
	v_cndmask_b32_e64 v247, v107, v106, s[88:89]
	s_mov_b32 s88, 0xaaaaaaaa
	s_mov_b32 s89, 0xaaaaaaaa
	v_min_u32_e32 v104, v242, v4
	v_max_u32_e32 v105, v242, v4
	v_cndmask_b32_e64 v242, v105, v104, s[88:89]
	v_min_u32_e32 v106, v244, v5
	v_max_u32_e32 v107, v244, v5
	v_cndmask_b32_e64 v244, v107, v106, s[88:89]
	v_min_u32_e32 v104, v246, v6
	v_max_u32_e32 v105, v246, v6
	v_cndmask_b32_e64 v246, v105, v104, s[88:89]
	v_min_u32_e32 v106, v248, v7
	v_max_u32_e32 v107, v248, v7
	v_cndmask_b32_e64 v248, v107, v106, s[88:89]
	v_min_u32_e32 v104, v241, v242
	v_max_u32_e32 v242, v241, v242
	v_mov_b32_e32 v241, v104
	v_min_u32_e32 v106, v243, v244
	v_max_u32_e32 v244, v243, v244
	v_mov_b32_e32 v243, v106
	v_min_u32_e32 v104, v245, v246
	v_max_u32_e32 v246, v245, v246
	v_mov_b32_e32 v245, v104
	v_min_u32_e32 v106, v247, v248
	v_max_u32_e32 v248, v247, v248
	v_mov_b32_e32 v247, v106
	v_xor_b32_e32 v116, 128, v234
	ds_bpermute_b32 v0, v116, v241
	ds_bpermute_b32 v1, v116, v243
	ds_bpermute_b32 v2, v116, v245
	ds_bpermute_b32 v3, v116, v247
	ds_bpermute_b32 v4, v116, v242
	ds_bpermute_b32 v5, v116, v244
	ds_bpermute_b32 v6, v116, v246
	ds_bpermute_b32 v7, v116, v248
	s_waitcnt lgkmcnt(0)
	s_mov_b32 s88, 0xffffffff
	s_mov_b32 s89, 0x0
	v_min_u32_e32 v104, v241, v0
	v_max_u32_e32 v105, v241, v0
	v_cndmask_b32_e64 v241, v105, v104, s[88:89]
	v_min_u32_e32 v106, v243, v1
	v_max_u32_e32 v107, v243, v1
	v_cndmask_b32_e64 v243, v107, v106, s[88:89]
	v_min_u32_e32 v104, v245, v2
	v_max_u32_e32 v105, v245, v2
	v_cndmask_b32_e64 v245, v105, v104, s[88:89]
	v_min_u32_e32 v106, v247, v3
	v_max_u32_e32 v107, v247, v3
	v_cndmask_b32_e64 v247, v107, v106, s[88:89]
	v_min_u32_e32 v104, v242, v4
	v_max_u32_e32 v105, v242, v4
	v_cndmask_b32_e64 v242, v105, v104, s[88:89]
	v_min_u32_e32 v106, v244, v5
	v_max_u32_e32 v107, v244, v5
	v_cndmask_b32_e64 v244, v107, v106, s[88:89]
	v_min_u32_e32 v104, v246, v6
	v_max_u32_e32 v105, v246, v6
	v_cndmask_b32_e64 v246, v105, v104, s[88:89]
	v_min_u32_e32 v106, v248, v7
	v_max_u32_e32 v107, v248, v7
	v_cndmask_b32_e64 v248, v107, v106, s[88:89]
	v_xor_b32_e32 v116, 64, v234
	ds_bpermute_b32 v0, v116, v241
	ds_bpermute_b32 v1, v116, v243
	ds_bpermute_b32 v2, v116, v245
	ds_bpermute_b32 v3, v116, v247
	ds_bpermute_b32 v4, v116, v242
	ds_bpermute_b32 v5, v116, v244
	ds_bpermute_b32 v6, v116, v246
	ds_bpermute_b32 v7, v116, v248
	s_waitcnt lgkmcnt(0)
; DEV void sort_lists(int lane, int& myi0, int& myi1, float& myg0, float& myg1) {
; #pragma unroll
;     for (int k = 2; k <= 128; k <<= 1) {
; #pragma unroll
;       for (int j = k >> 1; j >= 1; j >>= 1) {
;         if (j == 64) {
;           const bool sw_ = myi1 < myi0;
;           const int ti = sw_ ? myi1 : myi0, tj = sw_ ? myi0 : myi1; const float tg = sw_ ? myg1 : myg0, th = sw_ ? myg0 : myg1;
;           myi0 = ti; myi1 = tj; myg0 = tg; myg1 = th;
;         } else {
;           const bool lower = (lane & j) == 0;
;           {
;             const bool up = (k == 128) ? true : ((k == 64) ? true : ((lane & k) == 0));
;             const int oi = __shfl_xor(myi0, j); const float og = __shfl_xor(myg0, j);
;             const bool take = (lower == up) ? (oi < myi0) : (oi > myi0);
;             myi0 = take ? oi : myi0; myg0 = take ? og : myg0;
;           }
;           {
;             const bool up = (k == 128) ? true : ((k == 64) ? false : ((lane & k) == 0));
;             const int oi = __shfl_xor(myi1, j); const float og = __shfl_xor(myg1, j);
;             const bool take = (lower == up) ? (oi < myi1) : (oi > myi1);
;             myi1 = take ? oi : myi1; myg1 = take ? og : myg1;
;           }
;         }
;       }
;     }
; }
	s_mov_b32 s88, 0xffff
	s_mov_b32 s89, 0xffff
	v_min_u32_e32 v104, v241, v0
	v_max_u32_e32 v105, v241, v0
	v_cndmask_b32_e64 v241, v105, v104, s[88:89]
	v_min_u32_e32 v106, v243, v1
	v_max_u32_e32 v107, v243, v1
	v_cndmask_b32_e64 v243, v107, v106, s[88:89]
	v_min_u32_e32 v104, v245, v2
	v_max_u32_e32 v105, v245, v2
	v_cndmask_b32_e64 v245, v105, v104, s[88:89]
	v_min_u32_e32 v106, v247, v3
	v_max_u32_e32 v107, v247, v3
	v_cndmask_b32_e64 v247, v107, v106, s[88:89]
	v_min_u32_e32 v104, v242, v4
	v_max_u32_e32 v105, v242, v4
	v_cndmask_b32_e64 v242, v105, v104, s[88:89]
	v_min_u32_e32 v106, v244, v5
	v_max_u32_e32 v107, v244, v5
	v_cndmask_b32_e64 v244, v107, v106, s[88:89]
	v_min_u32_e32 v104, v246, v6
	v_max_u32_e32 v105, v246, v6
	v_cndmask_b32_e64 v246, v105, v104, s[88:89]
	v_min_u32_e32 v106, v248, v7
	v_max_u32_e32 v107, v248, v7
	v_cndmask_b32_e64 v248, v107, v106, s[88:89]
	v_xor_b32_e32 v116, 32, v234
	ds_bpermute_b32 v0, v116, v241
	ds_bpermute_b32 v1, v116, v243
	ds_bpermute_b32 v2, v116, v245
	ds_bpermute_b32 v3, v116, v247
	ds_bpermute_b32 v4, v116, v242
	ds_bpermute_b32 v5, v116, v244
	ds_bpermute_b32 v6, v116, v246
	ds_bpermute_b32 v7, v116, v248
	s_waitcnt lgkmcnt(0)
	s_mov_b32 s88, 0xff00ff
	s_mov_b32 s89, 0xff00ff
	v_min_u32_e32 v104, v241, v0
	v_max_u32_e32 v105, v241, v0
	v_cndmask_b32_e64 v241, v105, v104, s[88:89]
	v_min_u32_e32 v106, v243, v1
	v_max_u32_e32 v107, v243, v1
	v_cndmask_b32_e64 v243, v107, v106, s[88:89]
	v_min_u32_e32 v104, v245, v2
	v_max_u32_e32 v105, v245, v2
	v_cndmask_b32_e64 v245, v105, v104, s[88:89]
	v_min_u32_e32 v106, v247, v3
	v_max_u32_e32 v107, v247, v3
	v_cndmask_b32_e64 v247, v107, v106, s[88:89]
	v_min_u32_e32 v104, v242, v4
	v_max_u32_e32 v105, v242, v4
	v_cndmask_b32_e64 v242, v105, v104, s[88:89]
	v_min_u32_e32 v106, v244, v5
	v_max_u32_e32 v107, v244, v5
	v_cndmask_b32_e64 v244, v107, v106, s[88:89]
	v_min_u32_e32 v104, v246, v6
	v_max_u32_e32 v105, v246, v6
	v_cndmask_b32_e64 v246, v105, v104, s[88:89]
	v_min_u32_e32 v106, v248, v7
	v_max_u32_e32 v107, v248, v7
	v_cndmask_b32_e64 v248, v107, v106, s[88:89]
	v_xor_b32_e32 v116, 16, v234
	ds_bpermute_b32 v0, v116, v241
	ds_bpermute_b32 v1, v116, v243
	ds_bpermute_b32 v2, v116, v245
	ds_bpermute_b32 v3, v116, v247
	ds_bpermute_b32 v4, v116, v242
	ds_bpermute_b32 v5, v116, v244
	ds_bpermute_b32 v6, v116, v246
	ds_bpermute_b32 v7, v116, v248
	s_waitcnt lgkmcnt(0)
	s_mov_b32 s88, 0xf0f0f0f
	s_mov_b32 s89, 0xf0f0f0f
	v_min_u32_e32 v104, v241, v0
	v_max_u32_e32 v105, v241, v0
	v_cndmask_b32_e64 v241, v105, v104, s[88:89]
	v_min_u32_e32 v106, v243, v1
	v_max_u32_e32 v107, v243, v1
	v_cndmask_b32_e64 v243, v107, v106, s[88:89]
	v_min_u32_e32 v104, v245, v2
	v_max_u32_e32 v105, v245, v2
	v_cndmask_b32_e64 v245, v105, v104, s[88:89]
	v_min_u32_e32 v106, v247, v3
	v_max_u32_e32 v107, v247, v3
	v_cndmask_b32_e64 v247, v107, v106, s[88:89]
	v_min_u32_e32 v104, v242, v4
	v_max_u32_e32 v105, v242, v4
	v_cndmask_b32_e64 v242, v105, v104, s[88:89]
	v_min_u32_e32 v106, v244, v5
	v_max_u32_e32 v107, v244, v5
	v_cndmask_b32_e64 v244, v107, v106, s[88:89]
	v_min_u32_e32 v104, v246, v6
	v_max_u32_e32 v105, v246, v6
	v_cndmask_b32_e64 v246, v105, v104, s[88:89]
	v_min_u32_e32 v106, v248, v7
	v_max_u32_e32 v107, v248, v7
	v_cndmask_b32_e64 v248, v107, v106, s[88:89]
	v_xor_b32_e32 v116, 8, v234
	ds_bpermute_b32 v0, v116, v241
	ds_bpermute_b32 v1, v116, v243
	ds_bpermute_b32 v2, v116, v245
	ds_bpermute_b32 v3, v116, v247
	ds_bpermute_b32 v4, v116, v242
	ds_bpermute_b32 v5, v116, v244
	ds_bpermute_b32 v6, v116, v246
	ds_bpermute_b32 v7, v116, v248
	s_waitcnt lgkmcnt(0)
	s_mov_b32 s88, 0x33333333
	s_mov_b32 s89, 0x33333333
	v_min_u32_e32 v104, v241, v0
	v_max_u32_e32 v105, v241, v0
	v_cndmask_b32_e64 v241, v105, v104, s[88:89]
	v_min_u32_e32 v106, v243, v1
	v_max_u32_e32 v107, v243, v1
	v_cndmask_b32_e64 v243, v107, v106, s[88:89]
	v_min_u32_e32 v104, v245, v2
	v_max_u32_e32 v105, v245, v2
	v_cndmask_b32_e64 v245, v105, v104, s[88:89]
	v_min_u32_e32 v106, v247, v3
	v_max_u32_e32 v107, v247, v3
	v_cndmask_b32_e64 v247, v107, v106, s[88:89]
	v_min_u32_e32 v104, v242, v4
	v_max_u32_e32 v105, v242, v4
	v_cndmask_b32_e64 v242, v105, v104, s[88:89]
	v_min_u32_e32 v106, v244, v5
	v_max_u32_e32 v107, v244, v5
	v_cndmask_b32_e64 v244, v107, v106, s[88:89]
	v_min_u32_e32 v104, v246, v6
	v_max_u32_e32 v105, v246, v6
	v_cndmask_b32_e64 v246, v105, v104, s[88:89]
	v_min_u32_e32 v106, v248, v7
	v_max_u32_e32 v107, v248, v7
	v_cndmask_b32_e64 v248, v107, v106, s[88:89]
	v_xor_b32_e32 v116, 4, v234
	ds_bpermute_b32 v0, v116, v241
	ds_bpermute_b32 v1, v116, v243
	ds_bpermute_b32 v2, v116, v245
	ds_bpermute_b32 v3, v116, v247
	ds_bpermute_b32 v4, v116, v242
	ds_bpermute_b32 v5, v116, v244
	ds_bpermute_b32 v6, v116, v246
	ds_bpermute_b32 v7, v116, v248
	s_waitcnt lgkmcnt(0)
	s_mov_b32 s88, 0x55555555
	s_mov_b32 s89, 0x55555555
	v_min_u32_e32 v104, v241, v0
	v_max_u32_e32 v105, v241, v0
	v_cndmask_b32_e64 v241, v105, v104, s[88:89]
	v_min_u32_e32 v106, v243, v1
	v_max_u32_e32 v107, v243, v1
	v_cndmask_b32_e64 v243, v107, v106, s[88:89]
	v_min_u32_e32 v104, v245, v2
	v_max_u32_e32 v105, v245, v2
	v_cndmask_b32_e64 v245, v105, v104, s[88:89]
	v_min_u32_e32 v106, v247, v3
	v_max_u32_e32 v107, v247, v3
	v_cndmask_b32_e64 v247, v107, v106, s[88:89]
	v_min_u32_e32 v104, v242, v4
	v_max_u32_e32 v105, v242, v4
	v_cndmask_b32_e64 v242, v105, v104, s[88:89]
	v_min_u32_e32 v106, v244, v5
	v_max_u32_e32 v107, v244, v5
	v_cndmask_b32_e64 v244, v107, v106, s[88:89]
	v_min_u32_e32 v104, v246, v6
	v_max_u32_e32 v105, v246, v6
	v_cndmask_b32_e64 v246, v105, v104, s[88:89]
	v_min_u32_e32 v106, v248, v7
	v_max_u32_e32 v107, v248, v7
	v_cndmask_b32_e64 v248, v107, v106, s[88:89]
	v_mov_b32_e32 v117, 0
	s_lshl_b32 s98, s2, 11
	s_add_u32 s98, s98, s101
	v_add_u32_e32 v116, s98, v234
	ds_write_b32 v116, v241 offset:0
	ds_write_b32 v116, v242 offset:256
	ds_write_b32 v116, v243 offset:512
	ds_write_b32 v116, v244 offset:768
	ds_write_b32 v116, v245 offset:1024
	ds_write_b32 v116, v246 offset:1280
	ds_write_b32 v116, v247 offset:1536
	ds_write_b32 v116, v248 offset:1792
	v_add_u32_e32 v118, 0x10000, v116
	ds_write_b32 v118, v117 offset:0
	ds_write_b32 v118, v117 offset:256
	ds_write_b32 v118, v117 offset:512
	ds_write_b32 v118, v117 offset:768
	ds_write_b32 v118, v117 offset:1024
	ds_write_b32 v118, v117 offset:1280
	ds_write_b32 v118, v117 offset:1536
	ds_write_b32 v118, v117 offset:1792
	s_add_u32 s2, s2, 1
	s_cmp_lt_u32 s2, 4
	s_cbranch_scc1 .Lpg0_p0
; #define PG_ISSUE(BUF, TAB, e0_) do { const int isrc_ = ((e0_) < 64) ? myi0 : myi1; \
;       _Pragma("unroll") for (int e = 0; e < 8; ++e) { const int idx_ = __builtin_amdgcn_readlane(isrc_, ((e0_) + e) & 63); \
;         BUF[e] = *(const u32x4*)((TAB) + (size_t)idx_ * 1024 + lane * 16); } } while (0)
; DEV void peer_gather(const Params& P, int l, int m0, const int* idxs, const float* gs) {
;     ...
;     PG_ISSUE(b0, U, 0);
; #pragma nounroll
;     for (int e0 = 0; e0 < 128; e0 += 16) {
;       PG_ISSUE(b1, U, e0 + 8);
;       PG_U8(b0, 0, e0);
;       if (e0 + 16 < 128) PG_ISSUE(b0, U, e0 + 16); else PG_ISSUE(b0, V, 0);
;       PG_U8(b1, 0, e0 + 8);
	s_waitcnt lgkmcnt(0)
	v_lshrrev_b32_e32 v248, 3, v233
	v_readfirstlane_b32 s80, v124
	v_readfirstlane_b32 s81, v125
	s_nop 4
	s_mov_b32 s90, 0xffffff80
	s_mov_b32 s100, 0
	s_mov_b32 s98, 0
	s_mov_b32 s99, 0
	v_readfirstlane_b32 s82, v128
	v_readfirstlane_b32 s83, v129
	s_nop 4
	s_add_u32 vcc_lo, s3, s98
	s_lshl_b32 vcc_lo, vcc_lo, 11
	s_lshl_b32 vcc_hi, s99, 8
	s_add_u32 vcc_lo, vcc_lo, vcc_hi
	v_add_u32_e32 v119, vcc_lo, v236
	global_load_dwordx4 v[80:83], v119, s[82:83]
	global_load_dwordx4 v[84:87], v119, s[82:83] offset:16
	s_lshl_b32 vcc_lo, s98, 9
	s_add_u32 vcc_lo, vcc_lo, s101
	v_add_u32_e32 v116, vcc_lo, v234
	ds_read_b32 v134, v116
	ds_read_b32 v135, v116 offset:256
	s_lshl_b32 vcc_lo, s99, 21
	s_add_u32 s84, s80, vcc_lo
	s_addc_u32 s85, s81, 0
	v_mov_b32_e32 v240, v235
	s_waitcnt lgkmcnt(0)
	ds_bpermute_b32 v142, v249, v134
	ds_bpermute_b32 v143, v250, v134
	s_waitcnt lgkmcnt(0)
	v_and_or_b32 v142, v142, s90, v240
	v_and_or_b32 v143, v143, s90, v240
	global_load_dwordx4 v[0:3], v142, s[84:85]
	global_load_dwordx4 v[4:7], v143, s[84:85]
	ds_bpermute_b32 v142, v251, v134
	ds_bpermute_b32 v143, v252, v134
	s_waitcnt lgkmcnt(0)
	v_and_or_b32 v142, v142, s90, v240
	v_and_or_b32 v143, v143, s90, v240
	global_load_dwordx4 v[8:11], v142, s[84:85]
	global_load_dwordx4 v[12:15], v143, s[84:85]
	ds_bpermute_b32 v142, v253, v134
	ds_bpermute_b32 v143, v254, v134
	s_waitcnt lgkmcnt(0)
	v_and_or_b32 v142, v142, s90, v240
	v_and_or_b32 v143, v143, s90, v240
	global_load_dwordx4 v[16:19], v142, s[84:85]
	global_load_dwordx4 v[20:23], v143, s[84:85]
	ds_bpermute_b32 v142, v255, v134
	ds_bpermute_b32 v143, v153, v134
	s_waitcnt lgkmcnt(0)
	v_and_or_b32 v142, v142, s90, v240
	v_and_or_b32 v143, v143, s90, v240
	global_load_dwordx4 v[24:27], v142, s[84:85]
	global_load_dwordx4 v[28:31], v143, s[84:85]
	ds_bpermute_b32 v142, v249, v135
	ds_bpermute_b32 v143, v250, v135
	s_waitcnt lgkmcnt(0)
	v_and_or_b32 v142, v142, s90, v240
	v_and_or_b32 v143, v143, s90, v240
	global_load_dwordx4 v[32:35], v142, s[84:85]
	global_load_dwordx4 v[36:39], v143, s[84:85]
	ds_bpermute_b32 v142, v251, v135
	ds_bpermute_b32 v143, v252, v135
	s_waitcnt lgkmcnt(0)
	v_and_or_b32 v142, v142, s90, v240
	v_and_or_b32 v143, v143, s90, v240
	global_load_dwordx4 v[40:43], v142, s[84:85]
	global_load_dwordx4 v[44:47], v143, s[84:85]
	ds_bpermute_b32 v142, v253, v135
	ds_bpermute_b32 v143, v254, v135
	s_waitcnt lgkmcnt(0)
	v_and_or_b32 v142, v142, s90, v240
	v_and_or_b32 v143, v143, s90, v240
	global_load_dwordx4 v[48:51], v142, s[84:85]
	global_load_dwordx4 v[52:55], v143, s[84:85]
	ds_bpermute_b32 v142, v255, v135
	ds_bpermute_b32 v143, v153, v135
	s_waitcnt lgkmcnt(0)
	v_and_or_b32 v142, v142, s90, v240
	v_and_or_b32 v143, v143, s90, v240
	global_load_dwordx4 v[56:59], v142, s[84:85]
	global_load_dwordx4 v[60:63], v143, s[84:85]
	s_mov_b32 s92, 1
	s_lshl_b32 vcc_lo, s92, 9
	s_add_u32 vcc_lo, vcc_lo, s101
	v_add_u32_e32 v116, vcc_lo, v234
	ds_read_b32 v134, v116
	ds_read_b32 v135, v116 offset:256
.Lpg0_uloop:
	s_and_b32 s98, s100, 15
	s_lshr_b32 s99, s100, 4
	s_add_u32 s92, s100, 1
	s_min_u32 s92, s92, 127
	s_lshr_b32 s93, s92, 4
	s_and_b32 s92, s92, 15
	s_waitcnt vmcnt(16)
	v_lshlrev_b32_e32 v64, 16, v80
	v_and_b32_e32 v65, 0xffff0000, v80
	v_lshlrev_b32_e32 v66, 16, v81
	v_and_b32_e32 v67, 0xffff0000, v81
	v_lshlrev_b32_e32 v68, 16, v82
	v_and_b32_e32 v69, 0xffff0000, v82
	v_lshlrev_b32_e32 v70, 16, v83
	v_and_b32_e32 v71, 0xffff0000, v83
	v_lshlrev_b32_e32 v72, 16, v84
	v_and_b32_e32 v73, 0xffff0000, v84
	v_lshlrev_b32_e32 v74, 16, v85
	v_and_b32_e32 v75, 0xffff0000, v85
	v_lshlrev_b32_e32 v76, 16, v86
	v_and_b32_e32 v77, 0xffff0000, v86
	v_lshlrev_b32_e32 v78, 16, v87
	v_and_b32_e32 v79, 0xffff0000, v87
	v_readfirstlane_b32 s82, v128
	v_readfirstlane_b32 s83, v129
	s_nop 4
	s_add_u32 vcc_lo, s3, s92
	s_lshl_b32 vcc_lo, vcc_lo, 11
	s_lshl_b32 vcc_hi, s93, 8
	s_add_u32 vcc_lo, vcc_lo, vcc_hi
	v_add_u32_e32 v119, vcc_lo, v236
	global_load_dwordx4 v[80:83], v119, s[82:83]
	global_load_dwordx4 v[84:87], v119, s[82:83] offset:16
	s_lshl_b32 vcc_lo, s93, 21
	s_add_u32 s84, s80, vcc_lo
	s_addc_u32 s85, s81, 0
	v_mov_b32_e32 v240, v235
	s_waitcnt lgkmcnt(0)
	ds_bpermute_b32 v142, v249, v134
	ds_bpermute_b32 v143, v250, v134
	s_waitcnt vmcnt(16)
	v_cvt_pk_f32_fp8_e32 v[104:105], v0
	v_cvt_pk_f32_fp8_e32 v[108:109], v4
	v_cvt_pk_f32_fp8_sdwa v[106:107], v0 src0_sel:WORD_1
	v_cvt_pk_f32_fp8_sdwa v[110:111], v4 src0_sel:WORD_1
	v_pk_mul_f32 v[112:113], v[64:65], v[104:105]
	v_pk_mul_f32 v[114:115], v[64:65], v[108:109]
	v_pk_fma_f32 v[112:113], v[66:67], v[106:107], v[112:113]
	v_pk_fma_f32 v[114:115], v[66:67], v[110:111], v[114:115]
	v_cvt_pk_f32_fp8_e32 v[104:105], v1
	v_cvt_pk_f32_fp8_e32 v[108:109], v5
	v_cvt_pk_f32_fp8_sdwa v[106:107], v1 src0_sel:WORD_1
	v_cvt_pk_f32_fp8_sdwa v[110:111], v5 src0_sel:WORD_1
	v_pk_fma_f32 v[112:113], v[68:69], v[104:105], v[112:113]
	v_pk_fma_f32 v[114:115], v[68:69], v[108:109], v[114:115]
	v_pk_fma_f32 v[112:113], v[70:71], v[106:107], v[112:113]
	v_pk_fma_f32 v[114:115], v[70:71], v[110:111], v[114:115]
	v_cvt_pk_f32_fp8_e32 v[104:105], v2
	v_cvt_pk_f32_fp8_e32 v[108:109], v6
	v_cvt_pk_f32_fp8_sdwa v[106:107], v2 src0_sel:WORD_1
	v_cvt_pk_f32_fp8_sdwa v[110:111], v6 src0_sel:WORD_1
	v_pk_fma_f32 v[112:113], v[72:73], v[104:105], v[112:113]
	v_pk_fma_f32 v[114:115], v[72:73], v[108:109], v[114:115]
	v_pk_fma_f32 v[112:113], v[74:75], v[106:107], v[112:113]
	v_pk_fma_f32 v[114:115], v[74:75], v[110:111], v[114:115]
	v_cvt_pk_f32_fp8_e32 v[104:105], v3
	v_cvt_pk_f32_fp8_e32 v[108:109], v7
	v_cvt_pk_f32_fp8_sdwa v[106:107], v3 src0_sel:WORD_1
	v_cvt_pk_f32_fp8_sdwa v[110:111], v7 src0_sel:WORD_1
	v_pk_fma_f32 v[112:113], v[76:77], v[104:105], v[112:113]
	v_pk_fma_f32 v[114:115], v[76:77], v[108:109], v[114:115]
	s_waitcnt lgkmcnt(0)
	v_and_or_b32 v142, v142, s90, v240
	v_and_or_b32 v143, v143, s90, v240
	global_load_dwordx4 v[0:3], v142, s[84:85]
	global_load_dwordx4 v[4:7], v143, s[84:85]
	v_pk_fma_f32 v[112:113], v[78:79], v[106:107], v[112:113]
	v_pk_fma_f32 v[114:115], v[78:79], v[110:111], v[114:115]
	v_add_f32_e32 v88, v112, v113
	v_add_f32_e32 v89, v114, v115
	ds_bpermute_b32 v142, v251, v134
	ds_bpermute_b32 v143, v252, v134
	s_waitcnt vmcnt(16)
	v_cvt_pk_f32_fp8_e32 v[104:105], v8
	v_cvt_pk_f32_fp8_e32 v[108:109], v12
	v_cvt_pk_f32_fp8_sdwa v[106:107], v8 src0_sel:WORD_1
	v_cvt_pk_f32_fp8_sdwa v[110:111], v12 src0_sel:WORD_1
	v_pk_mul_f32 v[112:113], v[64:65], v[104:105]
	v_pk_mul_f32 v[114:115], v[64:65], v[108:109]
	v_pk_fma_f32 v[112:113], v[66:67], v[106:107], v[112:113]
	v_pk_fma_f32 v[114:115], v[66:67], v[110:111], v[114:115]
	v_cvt_pk_f32_fp8_e32 v[104:105], v9
	v_cvt_pk_f32_fp8_e32 v[108:109], v13
	v_cvt_pk_f32_fp8_sdwa v[106:107], v9 src0_sel:WORD_1
	v_cvt_pk_f32_fp8_sdwa v[110:111], v13 src0_sel:WORD_1
	v_pk_fma_f32 v[112:113], v[68:69], v[104:105], v[112:113]
	v_pk_fma_f32 v[114:115], v[68:69], v[108:109], v[114:115]
	v_pk_fma_f32 v[112:113], v[70:71], v[106:107], v[112:113]
	v_pk_fma_f32 v[114:115], v[70:71], v[110:111], v[114:115]
	v_cvt_pk_f32_fp8_e32 v[104:105], v10
	v_cvt_pk_f32_fp8_e32 v[108:109], v14
	v_cvt_pk_f32_fp8_sdwa v[106:107], v10 src0_sel:WORD_1
	v_cvt_pk_f32_fp8_sdwa v[110:111], v14 src0_sel:WORD_1
	v_pk_fma_f32 v[112:113], v[72:73], v[104:105], v[112:113]
	v_pk_fma_f32 v[114:115], v[72:73], v[108:109], v[114:115]
	v_pk_fma_f32 v[112:113], v[74:75], v[106:107], v[112:113]
	v_pk_fma_f32 v[114:115], v[74:75], v[110:111], v[114:115]
	v_cvt_pk_f32_fp8_e32 v[104:105], v11
	v_cvt_pk_f32_fp8_e32 v[108:109], v15
	v_cvt_pk_f32_fp8_sdwa v[106:107], v11 src0_sel:WORD_1
	v_cvt_pk_f32_fp8_sdwa v[110:111], v15 src0_sel:WORD_1
	v_pk_fma_f32 v[112:113], v[76:77], v[104:105], v[112:113]
	v_pk_fma_f32 v[114:115], v[76:77], v[108:109], v[114:115]
	s_waitcnt lgkmcnt(0)
	v_and_or_b32 v142, v142, s90, v240
	v_and_or_b32 v143, v143, s90, v240
	global_load_dwordx4 v[8:11], v142, s[84:85]
	global_load_dwordx4 v[12:15], v143, s[84:85]
	v_pk_fma_f32 v[112:113], v[78:79], v[106:107], v[112:113]
	v_pk_fma_f32 v[114:115], v[78:79], v[110:111], v[114:115]
	v_add_f32_e32 v90, v112, v113
	v_add_f32_e32 v91, v114, v115
	ds_bpermute_b32 v142, v253, v134
	ds_bpermute_b32 v143, v254, v134
	s_waitcnt vmcnt(16)
	v_cvt_pk_f32_fp8_e32 v[104:105], v16
	v_cvt_pk_f32_fp8_e32 v[108:109], v20
	v_cvt_pk_f32_fp8_sdwa v[106:107], v16 src0_sel:WORD_1
	v_cvt_pk_f32_fp8_sdwa v[110:111], v20 src0_sel:WORD_1
	v_pk_mul_f32 v[112:113], v[64:65], v[104:105]
	v_pk_mul_f32 v[114:115], v[64:65], v[108:109]
	v_pk_fma_f32 v[112:113], v[66:67], v[106:107], v[112:113]
	v_pk_fma_f32 v[114:115], v[66:67], v[110:111], v[114:115]
	v_cvt_pk_f32_fp8_e32 v[104:105], v17
	v_cvt_pk_f32_fp8_e32 v[108:109], v21
	v_cvt_pk_f32_fp8_sdwa v[106:107], v17 src0_sel:WORD_1
	v_cvt_pk_f32_fp8_sdwa v[110:111], v21 src0_sel:WORD_1
	v_pk_fma_f32 v[112:113], v[68:69], v[104:105], v[112:113]
	v_pk_fma_f32 v[114:115], v[68:69], v[108:109], v[114:115]
	v_pk_fma_f32 v[112:113], v[70:71], v[106:107], v[112:113]
	v_pk_fma_f32 v[114:115], v[70:71], v[110:111], v[114:115]
	v_cvt_pk_f32_fp8_e32 v[104:105], v18
	v_cvt_pk_f32_fp8_e32 v[108:109], v22
	v_cvt_pk_f32_fp8_sdwa v[106:107], v18 src0_sel:WORD_1
	v_cvt_pk_f32_fp8_sdwa v[110:111], v22 src0_sel:WORD_1
	v_pk_fma_f32 v[112:113], v[72:73], v[104:105], v[112:113]
	v_pk_fma_f32 v[114:115], v[72:73], v[108:109], v[114:115]
	v_pk_fma_f32 v[112:113], v[74:75], v[106:107], v[112:113]
	v_pk_fma_f32 v[114:115], v[74:75], v[110:111], v[114:115]
	v_cvt_pk_f32_fp8_e32 v[104:105], v19
	v_cvt_pk_f32_fp8_e32 v[108:109], v23
	v_cvt_pk_f32_fp8_sdwa v[106:107], v19 src0_sel:WORD_1
	v_cvt_pk_f32_fp8_sdwa v[110:111], v23 src0_sel:WORD_1
	v_pk_fma_f32 v[112:113], v[76:77], v[104:105], v[112:113]
	v_pk_fma_f32 v[114:115], v[76:77], v[108:109], v[114:115]
	s_waitcnt lgkmcnt(0)
	v_and_or_b32 v142, v142, s90, v240
	v_and_or_b32 v143, v143, s90, v240
	global_load_dwordx4 v[16:19], v142, s[84:85]
	global_load_dwordx4 v[20:23], v143, s[84:85]
	v_pk_fma_f32 v[112:113], v[78:79], v[106:107], v[112:113]
	v_pk_fma_f32 v[114:115], v[78:79], v[110:111], v[114:115]
	v_add_f32_e32 v92, v112, v113
	v_add_f32_e32 v93, v114, v115
	ds_bpermute_b32 v142, v255, v134
	ds_bpermute_b32 v143, v153, v134
	s_waitcnt vmcnt(16)
	v_cvt_pk_f32_fp8_e32 v[104:105], v24
	v_cvt_pk_f32_fp8_e32 v[108:109], v28
	v_cvt_pk_f32_fp8_sdwa v[106:107], v24 src0_sel:WORD_1
	v_cvt_pk_f32_fp8_sdwa v[110:111], v28 src0_sel:WORD_1
	v_pk_mul_f32 v[112:113], v[64:65], v[104:105]
	v_pk_mul_f32 v[114:115], v[64:65], v[108:109]
	v_pk_fma_f32 v[112:113], v[66:67], v[106:107], v[112:113]
	v_pk_fma_f32 v[114:115], v[66:67], v[110:111], v[114:115]
	v_cvt_pk_f32_fp8_e32 v[104:105], v25
	v_cvt_pk_f32_fp8_e32 v[108:109], v29
	v_cvt_pk_f32_fp8_sdwa v[106:107], v25 src0_sel:WORD_1
	v_cvt_pk_f32_fp8_sdwa v[110:111], v29 src0_sel:WORD_1
	v_pk_fma_f32 v[112:113], v[68:69], v[104:105], v[112:113]
	v_pk_fma_f32 v[114:115], v[68:69], v[108:109], v[114:115]
	v_pk_fma_f32 v[112:113], v[70:71], v[106:107], v[112:113]
	v_pk_fma_f32 v[114:115], v[70:71], v[110:111], v[114:115]
	v_cvt_pk_f32_fp8_e32 v[104:105], v26
	v_cvt_pk_f32_fp8_e32 v[108:109], v30
	v_cvt_pk_f32_fp8_sdwa v[106:107], v26 src0_sel:WORD_1
	v_cvt_pk_f32_fp8_sdwa v[110:111], v30 src0_sel:WORD_1
	v_pk_fma_f32 v[112:113], v[72:73], v[104:105], v[112:113]
	v_pk_fma_f32 v[114:115], v[72:73], v[108:109], v[114:115]
	v_pk_fma_f32 v[112:113], v[74:75], v[106:107], v[112:113]
	v_pk_fma_f32 v[114:115], v[74:75], v[110:111], v[114:115]
	v_cvt_pk_f32_fp8_e32 v[104:105], v27
	v_cvt_pk_f32_fp8_e32 v[108:109], v31
	v_cvt_pk_f32_fp8_sdwa v[106:107], v27 src0_sel:WORD_1
	v_cvt_pk_f32_fp8_sdwa v[110:111], v31 src0_sel:WORD_1
	v_pk_fma_f32 v[112:113], v[76:77], v[104:105], v[112:113]
	v_pk_fma_f32 v[114:115], v[76:77], v[108:109], v[114:115]
	s_waitcnt lgkmcnt(0)
	v_and_or_b32 v142, v142, s90, v240
	v_and_or_b32 v143, v143, s90, v240
	global_load_dwordx4 v[24:27], v142, s[84:85]
	global_load_dwordx4 v[28:31], v143, s[84:85]
	v_pk_fma_f32 v[112:113], v[78:79], v[106:107], v[112:113]
	v_pk_fma_f32 v[114:115], v[78:79], v[110:111], v[114:115]
	v_add_f32_e32 v94, v112, v113
	v_add_f32_e32 v95, v114, v115
	ds_bpermute_b32 v142, v249, v135
	ds_bpermute_b32 v143, v250, v135
	s_waitcnt vmcnt(16)
	v_cvt_pk_f32_fp8_e32 v[104:105], v32
	v_cvt_pk_f32_fp8_e32 v[108:109], v36
	v_cvt_pk_f32_fp8_sdwa v[106:107], v32 src0_sel:WORD_1
	v_cvt_pk_f32_fp8_sdwa v[110:111], v36 src0_sel:WORD_1
	v_pk_mul_f32 v[112:113], v[64:65], v[104:105]
	v_pk_mul_f32 v[114:115], v[64:65], v[108:109]
	v_pk_fma_f32 v[112:113], v[66:67], v[106:107], v[112:113]
	v_pk_fma_f32 v[114:115], v[66:67], v[110:111], v[114:115]
	v_cvt_pk_f32_fp8_e32 v[104:105], v33
	v_cvt_pk_f32_fp8_e32 v[108:109], v37
	v_cvt_pk_f32_fp8_sdwa v[106:107], v33 src0_sel:WORD_1
	v_cvt_pk_f32_fp8_sdwa v[110:111], v37 src0_sel:WORD_1
	v_pk_fma_f32 v[112:113], v[68:69], v[104:105], v[112:113]
	v_pk_fma_f32 v[114:115], v[68:69], v[108:109], v[114:115]
	v_pk_fma_f32 v[112:113], v[70:71], v[106:107], v[112:113]
	v_pk_fma_f32 v[114:115], v[70:71], v[110:111], v[114:115]
	v_cvt_pk_f32_fp8_e32 v[104:105], v34
	v_cvt_pk_f32_fp8_e32 v[108:109], v38
	v_cvt_pk_f32_fp8_sdwa v[106:107], v34 src0_sel:WORD_1
	v_cvt_pk_f32_fp8_sdwa v[110:111], v38 src0_sel:WORD_1
	v_pk_fma_f32 v[112:113], v[72:73], v[104:105], v[112:113]
	v_pk_fma_f32 v[114:115], v[72:73], v[108:109], v[114:115]
	v_pk_fma_f32 v[112:113], v[74:75], v[106:107], v[112:113]
	v_pk_fma_f32 v[114:115], v[74:75], v[110:111], v[114:115]
	v_cvt_pk_f32_fp8_e32 v[104:105], v35
	v_cvt_pk_f32_fp8_e32 v[108:109], v39
	v_cvt_pk_f32_fp8_sdwa v[106:107], v35 src0_sel:WORD_1
	v_cvt_pk_f32_fp8_sdwa v[110:111], v39 src0_sel:WORD_1
	v_pk_fma_f32 v[112:113], v[76:77], v[104:105], v[112:113]
	v_pk_fma_f32 v[114:115], v[76:77], v[108:109], v[114:115]
	s_waitcnt lgkmcnt(0)
	v_and_or_b32 v142, v142, s90, v240
	v_and_or_b32 v143, v143, s90, v240
	global_load_dwordx4 v[32:35], v142, s[84:85]
	global_load_dwordx4 v[36:39], v143, s[84:85]
	v_pk_fma_f32 v[112:113], v[78:79], v[106:107], v[112:113]
	v_pk_fma_f32 v[114:115], v[78:79], v[110:111], v[114:115]
	v_add_f32_e32 v96, v112, v113
	v_add_f32_e32 v97, v114, v115
	ds_bpermute_b32 v142, v251, v135
	ds_bpermute_b32 v143, v252, v135
	s_waitcnt vmcnt(16)
	v_cvt_pk_f32_fp8_e32 v[104:105], v40
	v_cvt_pk_f32_fp8_e32 v[108:109], v44
	v_cvt_pk_f32_fp8_sdwa v[106:107], v40 src0_sel:WORD_1
	v_cvt_pk_f32_fp8_sdwa v[110:111], v44 src0_sel:WORD_1
	v_pk_mul_f32 v[112:113], v[64:65], v[104:105]
	v_pk_mul_f32 v[114:115], v[64:65], v[108:109]
	v_pk_fma_f32 v[112:113], v[66:67], v[106:107], v[112:113]
	v_pk_fma_f32 v[114:115], v[66:67], v[110:111], v[114:115]
	v_cvt_pk_f32_fp8_e32 v[104:105], v41
	v_cvt_pk_f32_fp8_e32 v[108:109], v45
	v_cvt_pk_f32_fp8_sdwa v[106:107], v41 src0_sel:WORD_1
	v_cvt_pk_f32_fp8_sdwa v[110:111], v45 src0_sel:WORD_1
	v_pk_fma_f32 v[112:113], v[68:69], v[104:105], v[112:113]
	v_pk_fma_f32 v[114:115], v[68:69], v[108:109], v[114:115]
	v_pk_fma_f32 v[112:113], v[70:71], v[106:107], v[112:113]
	v_pk_fma_f32 v[114:115], v[70:71], v[110:111], v[114:115]
	v_cvt_pk_f32_fp8_e32 v[104:105], v42
	v_cvt_pk_f32_fp8_e32 v[108:109], v46
	v_cvt_pk_f32_fp8_sdwa v[106:107], v42 src0_sel:WORD_1
	v_cvt_pk_f32_fp8_sdwa v[110:111], v46 src0_sel:WORD_1
	v_pk_fma_f32 v[112:113], v[72:73], v[104:105], v[112:113]
	v_pk_fma_f32 v[114:115], v[72:73], v[108:109], v[114:115]
	v_pk_fma_f32 v[112:113], v[74:75], v[106:107], v[112:113]
	v_pk_fma_f32 v[114:115], v[74:75], v[110:111], v[114:115]
	v_cvt_pk_f32_fp8_e32 v[104:105], v43
	v_cvt_pk_f32_fp8_e32 v[108:109], v47
	v_cvt_pk_f32_fp8_sdwa v[106:107], v43 src0_sel:WORD_1
	v_cvt_pk_f32_fp8_sdwa v[110:111], v47 src0_sel:WORD_1
	v_pk_fma_f32 v[112:113], v[76:77], v[104:105], v[112:113]
	v_pk_fma_f32 v[114:115], v[76:77], v[108:109], v[114:115]
	s_waitcnt lgkmcnt(0)
	v_and_or_b32 v142, v142, s90, v240
	v_and_or_b32 v143, v143, s90, v240
	global_load_dwordx4 v[40:43], v142, s[84:85]
	global_load_dwordx4 v[44:47], v143, s[84:85]
	v_pk_fma_f32 v[112:113], v[78:79], v[106:107], v[112:113]
	v_pk_fma_f32 v[114:115], v[78:79], v[110:111], v[114:115]
	v_add_f32_e32 v98, v112, v113
	v_add_f32_e32 v99, v114, v115
	ds_bpermute_b32 v142, v253, v135
	ds_bpermute_b32 v143, v254, v135
	s_waitcnt vmcnt(16)
	v_cvt_pk_f32_fp8_e32 v[104:105], v48
	v_cvt_pk_f32_fp8_e32 v[108:109], v52
	v_cvt_pk_f32_fp8_sdwa v[106:107], v48 src0_sel:WORD_1
	v_cvt_pk_f32_fp8_sdwa v[110:111], v52 src0_sel:WORD_1
	v_pk_mul_f32 v[112:113], v[64:65], v[104:105]
	v_pk_mul_f32 v[114:115], v[64:65], v[108:109]
	v_pk_fma_f32 v[112:113], v[66:67], v[106:107], v[112:113]
	v_pk_fma_f32 v[114:115], v[66:67], v[110:111], v[114:115]
	v_cvt_pk_f32_fp8_e32 v[104:105], v49
	v_cvt_pk_f32_fp8_e32 v[108:109], v53
	v_cvt_pk_f32_fp8_sdwa v[106:107], v49 src0_sel:WORD_1
	v_cvt_pk_f32_fp8_sdwa v[110:111], v53 src0_sel:WORD_1
	v_pk_fma_f32 v[112:113], v[68:69], v[104:105], v[112:113]
	v_pk_fma_f32 v[114:115], v[68:69], v[108:109], v[114:115]
	v_pk_fma_f32 v[112:113], v[70:71], v[106:107], v[112:113]
	v_pk_fma_f32 v[114:115], v[70:71], v[110:111], v[114:115]
	v_cvt_pk_f32_fp8_e32 v[104:105], v50
	v_cvt_pk_f32_fp8_e32 v[108:109], v54
	v_cvt_pk_f32_fp8_sdwa v[106:107], v50 src0_sel:WORD_1
	v_cvt_pk_f32_fp8_sdwa v[110:111], v54 src0_sel:WORD_1
	v_pk_fma_f32 v[112:113], v[72:73], v[104:105], v[112:113]
	v_pk_fma_f32 v[114:115], v[72:73], v[108:109], v[114:115]
	v_pk_fma_f32 v[112:113], v[74:75], v[106:107], v[112:113]
	v_pk_fma_f32 v[114:115], v[74:75], v[110:111], v[114:115]
	v_cvt_pk_f32_fp8_e32 v[104:105], v51
	v_cvt_pk_f32_fp8_e32 v[108:109], v55
	v_cvt_pk_f32_fp8_sdwa v[106:107], v51 src0_sel:WORD_1
	v_cvt_pk_f32_fp8_sdwa v[110:111], v55 src0_sel:WORD_1
	v_pk_fma_f32 v[112:113], v[76:77], v[104:105], v[112:113]
	v_pk_fma_f32 v[114:115], v[76:77], v[108:109], v[114:115]
	s_waitcnt lgkmcnt(0)
	v_and_or_b32 v142, v142, s90, v240
	v_and_or_b32 v143, v143, s90, v240
	global_load_dwordx4 v[48:51], v142, s[84:85]
	global_load_dwordx4 v[52:55], v143, s[84:85]
	v_pk_fma_f32 v[112:113], v[78:79], v[106:107], v[112:113]
	v_pk_fma_f32 v[114:115], v[78:79], v[110:111], v[114:115]
	v_add_f32_e32 v100, v112, v113
	v_add_f32_e32 v101, v114, v115
	ds_bpermute_b32 v142, v255, v135
	ds_bpermute_b32 v143, v153, v135
	s_waitcnt vmcnt(16)
	v_cvt_pk_f32_fp8_e32 v[104:105], v56
	v_cvt_pk_f32_fp8_e32 v[108:109], v60
	v_cvt_pk_f32_fp8_sdwa v[106:107], v56 src0_sel:WORD_1
	v_cvt_pk_f32_fp8_sdwa v[110:111], v60 src0_sel:WORD_1
	v_pk_mul_f32 v[112:113], v[64:65], v[104:105]
	v_pk_mul_f32 v[114:115], v[64:65], v[108:109]
	v_pk_fma_f32 v[112:113], v[66:67], v[106:107], v[112:113]
	v_pk_fma_f32 v[114:115], v[66:67], v[110:111], v[114:115]
	v_cvt_pk_f32_fp8_e32 v[104:105], v57
	v_cvt_pk_f32_fp8_e32 v[108:109], v61
	v_cvt_pk_f32_fp8_sdwa v[106:107], v57 src0_sel:WORD_1
	v_cvt_pk_f32_fp8_sdwa v[110:111], v61 src0_sel:WORD_1
	v_pk_fma_f32 v[112:113], v[68:69], v[104:105], v[112:113]
	v_pk_fma_f32 v[114:115], v[68:69], v[108:109], v[114:115]
	v_pk_fma_f32 v[112:113], v[70:71], v[106:107], v[112:113]
	v_pk_fma_f32 v[114:115], v[70:71], v[110:111], v[114:115]
	v_cvt_pk_f32_fp8_e32 v[104:105], v58
	v_cvt_pk_f32_fp8_e32 v[108:109], v62
	v_cvt_pk_f32_fp8_sdwa v[106:107], v58 src0_sel:WORD_1
	v_cvt_pk_f32_fp8_sdwa v[110:111], v62 src0_sel:WORD_1
	v_pk_fma_f32 v[112:113], v[72:73], v[104:105], v[112:113]
	v_pk_fma_f32 v[114:115], v[72:73], v[108:109], v[114:115]
	v_pk_fma_f32 v[112:113], v[74:75], v[106:107], v[112:113]
	v_pk_fma_f32 v[114:115], v[74:75], v[110:111], v[114:115]
	v_cvt_pk_f32_fp8_e32 v[104:105], v59
	v_cvt_pk_f32_fp8_e32 v[108:109], v63
	v_cvt_pk_f32_fp8_sdwa v[106:107], v59 src0_sel:WORD_1
	v_cvt_pk_f32_fp8_sdwa v[110:111], v63 src0_sel:WORD_1
	v_pk_fma_f32 v[112:113], v[76:77], v[104:105], v[112:113]
	v_pk_fma_f32 v[114:115], v[76:77], v[108:109], v[114:115]
	s_waitcnt lgkmcnt(0)
	v_and_or_b32 v142, v142, s90, v240
	v_and_or_b32 v143, v143, s90, v240
	global_load_dwordx4 v[56:59], v142, s[84:85]
	global_load_dwordx4 v[60:63], v143, s[84:85]
	v_pk_fma_f32 v[112:113], v[78:79], v[106:107], v[112:113]
	v_pk_fma_f32 v[114:115], v[78:79], v[110:111], v[114:115]
	v_add_f32_e32 v102, v112, v113
	v_add_f32_e32 v103, v114, v115
	s_add_u32 s92, s100, 2
	s_min_u32 s92, s92, 127
	s_and_b32 s92, s92, 15
	s_lshl_b32 vcc_lo, s92, 9
	s_add_u32 vcc_lo, vcc_lo, s101
	v_add_u32_e32 v116, vcc_lo, v234
	ds_read_b32 v134, v116
	ds_read_b32 v135, v116 offset:256
	s_lshl_b32 vcc_lo, s98, 9
	s_add_u32 vcc_lo, vcc_lo, s101
	s_add_u32 vcc_lo, vcc_lo, 0x10000
	v_add_u32_e32 v117, vcc_lo, v234
	ds_read_b32 v136, v117
	ds_read_b32 v137, v117 offset:256
	s_mov_b32 s88, 0xf0f0f0f0
	s_mov_b32 s89, 0xf0f0f0f0
	v_cndmask_b32_e64 v144, v88, v92, s[88:89]
	v_cndmask_b32_e64 v92, v92, v88, s[88:89]
	v_cndmask_b32_e64 v145, v89, v93, s[88:89]
	v_cndmask_b32_e64 v93, v93, v89, s[88:89]
	v_cndmask_b32_e64 v146, v90, v94, s[88:89]
	v_cndmask_b32_e64 v94, v94, v90, s[88:89]
	v_cndmask_b32_e64 v147, v91, v95, s[88:89]
	v_cndmask_b32_e64 v95, v95, v91, s[88:89]
	v_add_f32_dpp v88, v92, v144 row_half_mirror row_mask:0xf bank_mask:0xf
	v_add_f32_dpp v89, v93, v145 row_half_mirror row_mask:0xf bank_mask:0xf
	v_add_f32_dpp v90, v94, v146 row_half_mirror row_mask:0xf bank_mask:0xf
	v_add_f32_dpp v91, v95, v147 row_half_mirror row_mask:0xf bank_mask:0xf
	v_cndmask_b32_e64 v144, v96, v100, s[88:89]
	v_cndmask_b32_e64 v100, v100, v96, s[88:89]
	v_cndmask_b32_e64 v145, v97, v101, s[88:89]
	v_cndmask_b32_e64 v101, v101, v97, s[88:89]
	v_cndmask_b32_e64 v146, v98, v102, s[88:89]
	v_cndmask_b32_e64 v102, v102, v98, s[88:89]
	v_cndmask_b32_e64 v147, v99, v103, s[88:89]
	v_cndmask_b32_e64 v103, v103, v99, s[88:89]
	v_add_f32_dpp v96, v100, v144 row_half_mirror row_mask:0xf bank_mask:0xf
	v_add_f32_dpp v97, v101, v145 row_half_mirror row_mask:0xf bank_mask:0xf
	v_add_f32_dpp v98, v102, v146 row_half_mirror row_mask:0xf bank_mask:0xf
	v_add_f32_dpp v99, v103, v147 row_half_mirror row_mask:0xf bank_mask:0xf
	s_mov_b32 s88, 0xcccccccc
	s_mov_b32 s89, 0xcccccccc
	v_cndmask_b32_e64 v144, v88, v90, s[88:89]
	v_cndmask_b32_e64 v90, v90, v88, s[88:89]
	v_cndmask_b32_e64 v145, v89, v91, s[88:89]
	v_cndmask_b32_e64 v91, v91, v89, s[88:89]
	v_cndmask_b32_e64 v146, v96, v98, s[88:89]
	v_cndmask_b32_e64 v98, v98, v96, s[88:89]
	v_cndmask_b32_e64 v147, v97, v99, s[88:89]
	v_cndmask_b32_e64 v99, v99, v97, s[88:89]
	v_add_f32_dpp v88, v90, v144 quad_perm:[2,3,0,1] row_mask:0xf bank_mask:0xf
	v_add_f32_dpp v89, v91, v145 quad_perm:[2,3,0,1] row_mask:0xf bank_mask:0xf
	v_add_f32_dpp v96, v98, v146 quad_perm:[2,3,0,1] row_mask:0xf bank_mask:0xf
	v_add_f32_dpp v97, v99, v147 quad_perm:[2,3,0,1] row_mask:0xf bank_mask:0xf
	s_mov_b32 s88, 0xaaaaaaaa
	s_mov_b32 s89, 0xaaaaaaaa
	v_cndmask_b32_e64 v144, v88, v89, s[88:89]
	v_cndmask_b32_e64 v89, v89, v88, s[88:89]
	v_cndmask_b32_e64 v145, v96, v97, s[88:89]
	v_cndmask_b32_e64 v97, v97, v96, s[88:89]
	s_nop 1
	v_add_f32_dpp v88, v89, v144 quad_perm:[1,0,3,2] row_mask:0xf bank_mask:0xf
	v_add_f32_dpp v96, v97, v145 quad_perm:[1,0,3,2] row_mask:0xf bank_mask:0xf
	s_nop 0
	ds_bpermute_b32 v144, v239, v88
	ds_bpermute_b32 v145, v239, v96
	s_waitcnt lgkmcnt(0)
	v_add_f32_e32 v136, v136, v144
	v_add_f32_e32 v137, v137, v145
	ds_write_b32 v117, v136
	ds_write_b32 v117, v137 offset:256
	s_add_u32 s100, s100, 1
	s_cmp_lt_u32 s100, 128
	s_cbranch_scc1 .Lpg0_uloop
	s_waitcnt vmcnt(0) lgkmcnt(0)
	s_mov_b32 s2, 0
.Lpg0_act:
	v_readlane_b32 s82, v231, 28
	v_readlane_b32 s83, v231, 29
	s_nop 4
	s_lshl_b32 s98, s2, 11
	s_add_u32 s98, s98, s101
	v_add_u32_e32 v116, s98, v234
	v_add_u32_e32 v117, 0x10000, v116
	ds_read_b32 v0, v116 offset:0
	ds_read_b32 v8, v117 offset:0
	ds_read_b32 v1, v116 offset:256
	ds_read_b32 v9, v117 offset:256
	ds_read_b32 v2, v116 offset:512
	ds_read_b32 v10, v117 offset:512
	ds_read_b32 v3, v116 offset:768
	ds_read_b32 v11, v117 offset:768
	ds_read_b32 v4, v116 offset:1024
	ds_read_b32 v12, v117 offset:1024
	ds_read_b32 v5, v116 offset:1280
	ds_read_b32 v13, v117 offset:1280
	ds_read_b32 v6, v116 offset:1536
	ds_read_b32 v14, v117 offset:1536
	ds_read_b32 v7, v116 offset:1792
	ds_read_b32 v15, v117 offset:1792
	s_waitcnt lgkmcnt(0)
	s_lshl_b32 s99, s2, 2
	s_add_u32 s99, s99, s33
	s_add_u32 s99, s99, 0
	s_lshl_b32 s99, s99, 9
	v_and_b32_e32 v0, 0x7f, v0
	v_lshl_add_u32 v0, v0, 2, s99
	global_load_dword v16, v0, s[82:83]
	v_and_b32_e32 v1, 0x7f, v1
	v_lshl_add_u32 v1, v1, 2, s99
	global_load_dword v17, v1, s[82:83]
	s_lshl_b32 s99, s2, 2
	s_add_u32 s99, s99, s33
	s_add_u32 s99, s99, 1
	s_lshl_b32 s99, s99, 9
	v_and_b32_e32 v2, 0x7f, v2
	v_lshl_add_u32 v2, v2, 2, s99
	global_load_dword v18, v2, s[82:83]
	v_and_b32_e32 v3, 0x7f, v3
	v_lshl_add_u32 v3, v3, 2, s99
	global_load_dword v19, v3, s[82:83]
	s_lshl_b32 s99, s2, 2
	s_add_u32 s99, s99, s33
	s_add_u32 s99, s99, 2
	s_lshl_b32 s99, s99, 9
	v_and_b32_e32 v4, 0x7f, v4
	v_lshl_add_u32 v4, v4, 2, s99
	global_load_dword v20, v4, s[82:83]
	v_and_b32_e32 v5, 0x7f, v5
	v_lshl_add_u32 v5, v5, 2, s99
	global_load_dword v21, v5, s[82:83]
	s_lshl_b32 s99, s2, 2
	s_add_u32 s99, s99, s33
	s_add_u32 s99, s99, 3
	s_lshl_b32 s99, s99, 9
	v_and_b32_e32 v6, 0x7f, v6
	v_lshl_add_u32 v6, v6, 2, s99
	global_load_dword v22, v6, s[82:83]
	v_and_b32_e32 v7, 0x7f, v7
	v_lshl_add_u32 v7, v7, 2, s99
	global_load_dword v23, v7, s[82:83]
	v_mul_f32_e32 v8, 0x3c800000, v8
	v_mul_f32_e32 v9, 0x3c800000, v9
	v_mul_f32_e32 v10, 0x3c800000, v10
	v_mul_f32_e32 v11, 0x3c800000, v11
	v_mul_f32_e32 v12, 0x3c800000, v12
	v_mul_f32_e32 v13, 0x3c800000, v13
	v_mul_f32_e32 v14, 0x3c800000, v14
	v_mul_f32_e32 v15, 0x3c800000, v15
	v_mul_f32_e32 v24, 0x3d372713, v8
	v_mul_f32_e32 v25, 0x3d372713, v9
	v_mul_f32_e32 v26, 0x3d372713, v10
	v_mul_f32_e32 v27, 0x3d372713, v11
	v_mul_f32_e32 v28, 0x3d372713, v12
	v_mul_f32_e32 v29, 0x3d372713, v13
	v_mul_f32_e32 v30, 0x3d372713, v14
	v_mul_f32_e32 v31, 0x3d372713, v15
	v_mul_f32_e32 v24, v8, v24
	v_mul_f32_e32 v25, v9, v25
	v_mul_f32_e32 v26, v10, v26
	v_mul_f32_e32 v27, v11, v27
	v_mul_f32_e32 v28, v12, v28
	v_mul_f32_e32 v29, v13, v29
	v_mul_f32_e32 v30, v14, v30
	v_mul_f32_e32 v31, v15, v31
	v_fma_f32 v24, v8, v24, v8
	v_fma_f32 v25, v9, v25, v9
	v_fma_f32 v26, v10, v26, v10
	v_fma_f32 v27, v11, v27, v11
	v_fma_f32 v28, v12, v28, v12
	v_fma_f32 v29, v13, v29, v13
	v_fma_f32 v30, v14, v30, v14
	v_fma_f32 v31, v15, v31, v15
	v_mul_f32_e32 v24, 0xbfcc422a, v24
	v_mul_f32_e32 v25, 0xbfcc422a, v25
	v_mul_f32_e32 v26, 0xbfcc422a, v26
	v_mul_f32_e32 v27, 0xbfcc422a, v27
	v_mul_f32_e32 v28, 0xbfcc422a, v28
	v_mul_f32_e32 v29, 0xbfcc422a, v29
	v_mul_f32_e32 v30, 0xbfcc422a, v30
	v_mul_f32_e32 v31, 0xbfcc422a, v31
	v_mul_f32_e32 v24, 0x3fb8aa3b, v24
	v_mul_f32_e32 v25, 0x3fb8aa3b, v25
	v_mul_f32_e32 v26, 0x3fb8aa3b, v26
	v_mul_f32_e32 v27, 0x3fb8aa3b, v27
	v_mul_f32_e32 v28, 0x3fb8aa3b, v28
	v_mul_f32_e32 v29, 0x3fb8aa3b, v29
	v_mul_f32_e32 v30, 0x3fb8aa3b, v30
	v_mul_f32_e32 v31, 0x3fb8aa3b, v31
	v_exp_f32_e32 v24, v24
	v_exp_f32_e32 v25, v25
	v_exp_f32_e32 v26, v26
	v_exp_f32_e32 v27, v27
	v_exp_f32_e32 v28, v28
	v_exp_f32_e32 v29, v29
	v_exp_f32_e32 v30, v30
	v_exp_f32_e32 v31, v31
	s_nop 0
	v_add_f32_e32 v24, 1.0, v24
	v_add_f32_e32 v25, 1.0, v25
	v_add_f32_e32 v26, 1.0, v26
	v_add_f32_e32 v27, 1.0, v27
	v_add_f32_e32 v28, 1.0, v28
	v_add_f32_e32 v29, 1.0, v29
	v_add_f32_e32 v30, 1.0, v30
	v_add_f32_e32 v31, 1.0, v31
	v_rcp_f32_e32 v24, v24
	v_rcp_f32_e32 v25, v25
	v_rcp_f32_e32 v26, v26
	v_rcp_f32_e32 v27, v27
	v_rcp_f32_e32 v28, v28
	v_rcp_f32_e32 v29, v29
	v_rcp_f32_e32 v30, v30
	v_rcp_f32_e32 v31, v31
	s_nop 0
	v_mul_f32_e32 v24, v8, v24
	v_mul_f32_e32 v25, v9, v25
	v_mul_f32_e32 v26, v10, v26
	v_mul_f32_e32 v27, v11, v27
	v_mul_f32_e32 v28, v12, v28
	v_mul_f32_e32 v29, v13, v29
	v_mul_f32_e32 v30, v14, v30
	v_mul_f32_e32 v31, v15, v31
	s_waitcnt vmcnt(0)
	v_mul_f32_e32 v24, v24, v16
	ds_write_b32 v117, v24 offset:0
	v_mul_f32_e32 v25, v25, v17
	ds_write_b32 v117, v25 offset:256
	v_mul_f32_e32 v26, v26, v18
	ds_write_b32 v117, v26 offset:512
	v_mul_f32_e32 v27, v27, v19
	ds_write_b32 v117, v27 offset:768
	v_mul_f32_e32 v28, v28, v20
	ds_write_b32 v117, v28 offset:1024
	v_mul_f32_e32 v29, v29, v21
	ds_write_b32 v117, v29 offset:1280
	v_mul_f32_e32 v30, v30, v22
	ds_write_b32 v117, v30 offset:1536
	v_mul_f32_e32 v31, v31, v23
	ds_write_b32 v117, v31 offset:1792
	s_add_u32 s2, s2, 1
	s_cmp_lt_u32 s2, 4
	s_cbranch_scc1 .Lpg0_act
; #define PG_ISSUE(BUF, TAB, e0_) do { const int isrc_ = ((e0_) < 64) ? myi0 : myi1; \
;       _Pragma("unroll") for (int e = 0; e < 8; ++e) { const int idx_ = __builtin_amdgcn_readlane(isrc_, ((e0_) + e) & 63); \
;         BUF[e] = *(const u32x4*)((TAB) + (size_t)idx_ * 1024 + lane * 16); } } while (0)
; DEV void peer_gather(const Params& P, int l, int m0, const int* idxs, const float* gs) {
;     ...
; #pragma nounroll
;     for (int e0 = 0; e0 < 128; e0 += 16) {
;       PG_ISSUE(b1, V, e0 + 8);
;       if (e0 == 64 && i + 1 < 16) sort_lists(lane, ni0, ni1, ng0, ng1);
;       PG_V16(b0, e0);
;       if (e0 + 16 < 128) PG_ISSUE(b0, V, e0 + 16);
;       PG_V16(b1, e0 + 8);
;     }
	s_waitcnt lgkmcnt(0)
	v_add_u32_e32 v249, 0, v237
	v_add_u32_e32 v250, 32, v237
	v_add_u32_e32 v251, 64, v237
	v_add_u32_e32 v252, 96, v237
	v_add_u32_e32 v253, 128, v237
	v_add_u32_e32 v254, 160, v237
	v_add_u32_e32 v255, 192, v237
	v_add_u32_e32 v153, 224, v237
	v_readfirstlane_b32 s80, v126
	v_readfirstlane_b32 s81, v127
	s_nop 4
	s_mov_b32 s90, 0xffffff80
	s_mov_b32 s100, 0
	s_mov_b32 s98, 0
	s_mov_b32 s99, 0
	s_lshl_b32 vcc_lo, s98, 9
	s_add_u32 vcc_lo, vcc_lo, s101
	v_add_u32_e32 v116, vcc_lo, v234
	ds_read_b32 v134, v116
	ds_read_b32 v135, v116 offset:256
	s_lshl_b32 vcc_lo, s99, 21
	s_add_u32 s84, s80, vcc_lo
	s_addc_u32 s85, s81, 0
	v_mov_b32_e32 v240, v235
	s_waitcnt lgkmcnt(0)
	ds_bpermute_b32 v142, v249, v134
	ds_bpermute_b32 v143, v250, v134
	s_waitcnt lgkmcnt(0)
	v_and_or_b32 v142, v142, s90, v240
	v_and_or_b32 v143, v143, s90, v240
	global_load_dwordx4 v[0:3], v142, s[84:85]
	global_load_dwordx4 v[4:7], v143, s[84:85]
	ds_bpermute_b32 v142, v251, v134
	ds_bpermute_b32 v143, v252, v134
	s_waitcnt lgkmcnt(0)
	v_and_or_b32 v142, v142, s90, v240
	v_and_or_b32 v143, v143, s90, v240
	global_load_dwordx4 v[8:11], v142, s[84:85]
	global_load_dwordx4 v[12:15], v143, s[84:85]
	ds_bpermute_b32 v142, v253, v134
	ds_bpermute_b32 v143, v254, v134
	s_waitcnt lgkmcnt(0)
	v_and_or_b32 v142, v142, s90, v240
	v_and_or_b32 v143, v143, s90, v240
	global_load_dwordx4 v[16:19], v142, s[84:85]
	global_load_dwordx4 v[20:23], v143, s[84:85]
	ds_bpermute_b32 v142, v255, v134
	ds_bpermute_b32 v143, v153, v134
	s_waitcnt lgkmcnt(0)
	v_and_or_b32 v142, v142, s90, v240
	v_and_or_b32 v143, v143, s90, v240
	global_load_dwordx4 v[24:27], v142, s[84:85]
	global_load_dwordx4 v[28:31], v143, s[84:85]
	ds_bpermute_b32 v142, v249, v135
	ds_bpermute_b32 v143, v250, v135
	s_waitcnt lgkmcnt(0)
	v_and_or_b32 v142, v142, s90, v240
	v_and_or_b32 v143, v143, s90, v240
	global_load_dwordx4 v[32:35], v142, s[84:85]
	global_load_dwordx4 v[36:39], v143, s[84:85]
	ds_bpermute_b32 v142, v251, v135
	ds_bpermute_b32 v143, v252, v135
	s_waitcnt lgkmcnt(0)
	v_and_or_b32 v142, v142, s90, v240
	v_and_or_b32 v143, v143, s90, v240
	global_load_dwordx4 v[40:43], v142, s[84:85]
	global_load_dwordx4 v[44:47], v143, s[84:85]
	ds_bpermute_b32 v142, v253, v135
	ds_bpermute_b32 v143, v254, v135
	s_waitcnt lgkmcnt(0)
	v_and_or_b32 v142, v142, s90, v240
	v_and_or_b32 v143, v143, s90, v240
	global_load_dwordx4 v[48:51], v142, s[84:85]
	global_load_dwordx4 v[52:55], v143, s[84:85]
	ds_bpermute_b32 v142, v255, v135
	ds_bpermute_b32 v143, v153, v135
	s_waitcnt lgkmcnt(0)
	v_and_or_b32 v142, v142, s90, v240
	v_and_or_b32 v143, v143, s90, v240
	global_load_dwordx4 v[56:59], v142, s[84:85]
	global_load_dwordx4 v[60:63], v143, s[84:85]
	s_mov_b32 s92, 1
	s_lshl_b32 vcc_lo, s92, 9
	s_add_u32 vcc_lo, vcc_lo, s101
	v_add_u32_e32 v116, vcc_lo, v234
	ds_read_b32 v134, v116
	ds_read_b32 v135, v116 offset:256
	s_lshl_b32 vcc_lo, s98, 9
	s_add_u32 vcc_lo, vcc_lo, s101
	s_add_u32 vcc_lo, vcc_lo, 0x10000
	v_add_u32_e32 v117, vcc_lo, v234
	ds_read_b32 v136, v117
	ds_read_b32 v137, v117 offset:256
	s_waitcnt vmcnt(0)
.Lpg0_vloop:
	s_and_b32 s98, s100, 15
	s_lshr_b32 s99, s100, 4
	s_add_u32 s92, s100, 1
	s_min_u32 s92, s92, 127
	s_lshr_b32 s93, s92, 4
	s_and_b32 s92, s92, 15
	v_readfirstlane_b32 s82, v132
	v_readfirstlane_b32 s83, v133
	s_nop 4
	s_add_u32 vcc_lo, s3, s98
	s_lshl_b32 vcc_lo, vcc_lo, 12
	s_lshl_b32 vcc_hi, s99, 9
	s_add_u32 vcc_lo, vcc_lo, vcc_hi
	v_add_u32_e32 v119, vcc_lo, v238
	global_load_dword v80, v119, s[82:83]
	global_load_dword v81, v119, s[82:83] offset:32
	s_lshl_b32 vcc_lo, s93, 21
	s_add_u32 s84, s80, vcc_lo
	s_addc_u32 s85, s81, 0
	v_mov_b32_e32 v240, v235
	s_waitcnt lgkmcnt(0)
	ds_bpermute_b32 v138, v249, v136
	ds_bpermute_b32 v140, v250, v136
	ds_bpermute_b32 v142, v249, v134
	ds_bpermute_b32 v143, v250, v134
	ds_bpermute_b32 v144, v251, v136
	ds_bpermute_b32 v146, v252, v136
	s_waitcnt vmcnt(18) lgkmcnt(4)
	v_cvt_pk_f32_fp8_e32 v[104:105], v0
	v_cvt_pk_f32_fp8_e32 v[108:109], v4
	v_cvt_pk_f32_fp8_sdwa v[106:107], v0 src0_sel:WORD_1
	v_cvt_pk_f32_fp8_sdwa v[110:111], v4 src0_sel:WORD_1
	v_pk_mul_f32 v[64:65], v[104:105], v[138:139] op_sel_hi:[1,0]
	v_pk_mul_f32 v[66:67], v[106:107], v[138:139] op_sel_hi:[1,0]
	v_pk_fma_f32 v[64:65], v[108:109], v[140:141], v[64:65] op_sel_hi:[1,0,1]
	v_pk_fma_f32 v[66:67], v[110:111], v[140:141], v[66:67] op_sel_hi:[1,0,1]
	v_cvt_pk_f32_fp8_e32 v[104:105], v1
	v_cvt_pk_f32_fp8_e32 v[108:109], v5
	v_cvt_pk_f32_fp8_sdwa v[106:107], v1 src0_sel:WORD_1
	v_cvt_pk_f32_fp8_sdwa v[110:111], v5 src0_sel:WORD_1
	v_pk_mul_f32 v[68:69], v[104:105], v[138:139] op_sel_hi:[1,0]
	v_pk_mul_f32 v[70:71], v[106:107], v[138:139] op_sel_hi:[1,0]
	v_pk_fma_f32 v[68:69], v[108:109], v[140:141], v[68:69] op_sel_hi:[1,0,1]
	v_pk_fma_f32 v[70:71], v[110:111], v[140:141], v[70:71] op_sel_hi:[1,0,1]
	v_cvt_pk_f32_fp8_e32 v[104:105], v2
	v_cvt_pk_f32_fp8_e32 v[108:109], v6
	v_cvt_pk_f32_fp8_sdwa v[106:107], v2 src0_sel:WORD_1
	v_cvt_pk_f32_fp8_sdwa v[110:111], v6 src0_sel:WORD_1
	v_pk_mul_f32 v[72:73], v[104:105], v[138:139] op_sel_hi:[1,0]
	v_pk_mul_f32 v[74:75], v[106:107], v[138:139] op_sel_hi:[1,0]
	v_pk_fma_f32 v[72:73], v[108:109], v[140:141], v[72:73] op_sel_hi:[1,0,1]
	v_pk_fma_f32 v[74:75], v[110:111], v[140:141], v[74:75] op_sel_hi:[1,0,1]
	v_cvt_pk_f32_fp8_e32 v[104:105], v3
	v_cvt_pk_f32_fp8_e32 v[108:109], v7
	v_cvt_pk_f32_fp8_sdwa v[106:107], v3 src0_sel:WORD_1
	v_cvt_pk_f32_fp8_sdwa v[110:111], v7 src0_sel:WORD_1
	v_pk_mul_f32 v[76:77], v[104:105], v[138:139] op_sel_hi:[1,0]
	v_pk_mul_f32 v[78:79], v[106:107], v[138:139] op_sel_hi:[1,0]
	s_waitcnt lgkmcnt(0)
	v_and_or_b32 v142, v142, s90, v240
	v_and_or_b32 v143, v143, s90, v240
	global_load_dwordx4 v[0:3], v142, s[84:85]
	global_load_dwordx4 v[4:7], v143, s[84:85]
	v_pk_fma_f32 v[76:77], v[108:109], v[140:141], v[76:77] op_sel_hi:[1,0,1]
	v_pk_fma_f32 v[78:79], v[110:111], v[140:141], v[78:79] op_sel_hi:[1,0,1]
	ds_bpermute_b32 v142, v251, v134
	ds_bpermute_b32 v143, v252, v134
	ds_bpermute_b32 v138, v253, v136
	ds_bpermute_b32 v140, v254, v136
	s_waitcnt vmcnt(18) lgkmcnt(4)
	v_cvt_pk_f32_fp8_e32 v[104:105], v8
	v_cvt_pk_f32_fp8_e32 v[108:109], v12
	v_cvt_pk_f32_fp8_sdwa v[106:107], v8 src0_sel:WORD_1
	v_cvt_pk_f32_fp8_sdwa v[110:111], v12 src0_sel:WORD_1
	v_pk_fma_f32 v[64:65], v[104:105], v[144:145], v[64:65] op_sel_hi:[1,0,1]
	v_pk_fma_f32 v[66:67], v[106:107], v[144:145], v[66:67] op_sel_hi:[1,0,1]
	v_pk_fma_f32 v[64:65], v[108:109], v[146:147], v[64:65] op_sel_hi:[1,0,1]
	v_pk_fma_f32 v[66:67], v[110:111], v[146:147], v[66:67] op_sel_hi:[1,0,1]
	v_cvt_pk_f32_fp8_e32 v[104:105], v9
	v_cvt_pk_f32_fp8_e32 v[108:109], v13
	v_cvt_pk_f32_fp8_sdwa v[106:107], v9 src0_sel:WORD_1
	v_cvt_pk_f32_fp8_sdwa v[110:111], v13 src0_sel:WORD_1
	v_pk_fma_f32 v[68:69], v[104:105], v[144:145], v[68:69] op_sel_hi:[1,0,1]
	v_pk_fma_f32 v[70:71], v[106:107], v[144:145], v[70:71] op_sel_hi:[1,0,1]
	v_pk_fma_f32 v[68:69], v[108:109], v[146:147], v[68:69] op_sel_hi:[1,0,1]
	v_pk_fma_f32 v[70:71], v[110:111], v[146:147], v[70:71] op_sel_hi:[1,0,1]
	v_cvt_pk_f32_fp8_e32 v[104:105], v10
	v_cvt_pk_f32_fp8_e32 v[108:109], v14
	v_cvt_pk_f32_fp8_sdwa v[106:107], v10 src0_sel:WORD_1
	v_cvt_pk_f32_fp8_sdwa v[110:111], v14 src0_sel:WORD_1
	v_pk_fma_f32 v[72:73], v[104:105], v[144:145], v[72:73] op_sel_hi:[1,0,1]
	v_pk_fma_f32 v[74:75], v[106:107], v[144:145], v[74:75] op_sel_hi:[1,0,1]
	v_pk_fma_f32 v[72:73], v[108:109], v[146:147], v[72:73] op_sel_hi:[1,0,1]
	v_pk_fma_f32 v[74:75], v[110:111], v[146:147], v[74:75] op_sel_hi:[1,0,1]
	v_cvt_pk_f32_fp8_e32 v[104:105], v11
	v_cvt_pk_f32_fp8_e32 v[108:109], v15
	v_cvt_pk_f32_fp8_sdwa v[106:107], v11 src0_sel:WORD_1
	v_cvt_pk_f32_fp8_sdwa v[110:111], v15 src0_sel:WORD_1
	v_pk_fma_f32 v[76:77], v[104:105], v[144:145], v[76:77] op_sel_hi:[1,0,1]
	v_pk_fma_f32 v[78:79], v[106:107], v[144:145], v[78:79] op_sel_hi:[1,0,1]
	s_waitcnt lgkmcnt(0)
	v_and_or_b32 v142, v142, s90, v240
	v_and_or_b32 v143, v143, s90, v240
	global_load_dwordx4 v[8:11], v142, s[84:85]
	global_load_dwordx4 v[12:15], v143, s[84:85]
	v_pk_fma_f32 v[76:77], v[108:109], v[146:147], v[76:77] op_sel_hi:[1,0,1]
	v_pk_fma_f32 v[78:79], v[110:111], v[146:147], v[78:79] op_sel_hi:[1,0,1]
	ds_bpermute_b32 v142, v253, v134
	ds_bpermute_b32 v143, v254, v134
	ds_bpermute_b32 v144, v255, v136
	ds_bpermute_b32 v146, v153, v136
	s_waitcnt vmcnt(18) lgkmcnt(4)
	v_cvt_pk_f32_fp8_e32 v[104:105], v16
	v_cvt_pk_f32_fp8_e32 v[108:109], v20
	v_cvt_pk_f32_fp8_sdwa v[106:107], v16 src0_sel:WORD_1
	v_cvt_pk_f32_fp8_sdwa v[110:111], v20 src0_sel:WORD_1
	v_pk_fma_f32 v[64:65], v[104:105], v[138:139], v[64:65] op_sel_hi:[1,0,1]
	v_pk_fma_f32 v[66:67], v[106:107], v[138:139], v[66:67] op_sel_hi:[1,0,1]
	v_pk_fma_f32 v[64:65], v[108:109], v[140:141], v[64:65] op_sel_hi:[1,0,1]
	v_pk_fma_f32 v[66:67], v[110:111], v[140:141], v[66:67] op_sel_hi:[1,0,1]
	v_cvt_pk_f32_fp8_e32 v[104:105], v17
	v_cvt_pk_f32_fp8_e32 v[108:109], v21
	v_cvt_pk_f32_fp8_sdwa v[106:107], v17 src0_sel:WORD_1
	v_cvt_pk_f32_fp8_sdwa v[110:111], v21 src0_sel:WORD_1
	v_pk_fma_f32 v[68:69], v[104:105], v[138:139], v[68:69] op_sel_hi:[1,0,1]
	v_pk_fma_f32 v[70:71], v[106:107], v[138:139], v[70:71] op_sel_hi:[1,0,1]
	v_pk_fma_f32 v[68:69], v[108:109], v[140:141], v[68:69] op_sel_hi:[1,0,1]
	v_pk_fma_f32 v[70:71], v[110:111], v[140:141], v[70:71] op_sel_hi:[1,0,1]
	v_cvt_pk_f32_fp8_e32 v[104:105], v18
	v_cvt_pk_f32_fp8_e32 v[108:109], v22
	v_cvt_pk_f32_fp8_sdwa v[106:107], v18 src0_sel:WORD_1
	v_cvt_pk_f32_fp8_sdwa v[110:111], v22 src0_sel:WORD_1
	v_pk_fma_f32 v[72:73], v[104:105], v[138:139], v[72:73] op_sel_hi:[1,0,1]
	v_pk_fma_f32 v[74:75], v[106:107], v[138:139], v[74:75] op_sel_hi:[1,0,1]
	v_pk_fma_f32 v[72:73], v[108:109], v[140:141], v[72:73] op_sel_hi:[1,0,1]
	v_pk_fma_f32 v[74:75], v[110:111], v[140:141], v[74:75] op_sel_hi:[1,0,1]
	v_cvt_pk_f32_fp8_e32 v[104:105], v19
	v_cvt_pk_f32_fp8_e32 v[108:109], v23
	v_cvt_pk_f32_fp8_sdwa v[106:107], v19 src0_sel:WORD_1
	v_cvt_pk_f32_fp8_sdwa v[110:111], v23 src0_sel:WORD_1
	v_pk_fma_f32 v[76:77], v[104:105], v[138:139], v[76:77] op_sel_hi:[1,0,1]
	v_pk_fma_f32 v[78:79], v[106:107], v[138:139], v[78:79] op_sel_hi:[1,0,1]
	s_waitcnt lgkmcnt(0)
	v_and_or_b32 v142, v142, s90, v240
	v_and_or_b32 v143, v143, s90, v240
	global_load_dwordx4 v[16:19], v142, s[84:85]
	global_load_dwordx4 v[20:23], v143, s[84:85]
	v_pk_fma_f32 v[76:77], v[108:109], v[140:141], v[76:77] op_sel_hi:[1,0,1]
	v_pk_fma_f32 v[78:79], v[110:111], v[140:141], v[78:79] op_sel_hi:[1,0,1]
	ds_bpermute_b32 v142, v255, v134
	ds_bpermute_b32 v143, v153, v134
	ds_bpermute_b32 v138, v249, v137
	ds_bpermute_b32 v140, v250, v137
	s_waitcnt vmcnt(18) lgkmcnt(4)
	v_cvt_pk_f32_fp8_e32 v[104:105], v24
	v_cvt_pk_f32_fp8_e32 v[108:109], v28
	v_cvt_pk_f32_fp8_sdwa v[106:107], v24 src0_sel:WORD_1
	v_cvt_pk_f32_fp8_sdwa v[110:111], v28 src0_sel:WORD_1
	v_pk_fma_f32 v[64:65], v[104:105], v[144:145], v[64:65] op_sel_hi:[1,0,1]
	v_pk_fma_f32 v[66:67], v[106:107], v[144:145], v[66:67] op_sel_hi:[1,0,1]
	v_pk_fma_f32 v[64:65], v[108:109], v[146:147], v[64:65] op_sel_hi:[1,0,1]
	v_pk_fma_f32 v[66:67], v[110:111], v[146:147], v[66:67] op_sel_hi:[1,0,1]
	v_cvt_pk_f32_fp8_e32 v[104:105], v25
	v_cvt_pk_f32_fp8_e32 v[108:109], v29
	v_cvt_pk_f32_fp8_sdwa v[106:107], v25 src0_sel:WORD_1
	v_cvt_pk_f32_fp8_sdwa v[110:111], v29 src0_sel:WORD_1
	v_pk_fma_f32 v[68:69], v[104:105], v[144:145], v[68:69] op_sel_hi:[1,0,1]
	v_pk_fma_f32 v[70:71], v[106:107], v[144:145], v[70:71] op_sel_hi:[1,0,1]
	v_pk_fma_f32 v[68:69], v[108:109], v[146:147], v[68:69] op_sel_hi:[1,0,1]
	v_pk_fma_f32 v[70:71], v[110:111], v[146:147], v[70:71] op_sel_hi:[1,0,1]
	v_cvt_pk_f32_fp8_e32 v[104:105], v26
	v_cvt_pk_f32_fp8_e32 v[108:109], v30
	v_cvt_pk_f32_fp8_sdwa v[106:107], v26 src0_sel:WORD_1
	v_cvt_pk_f32_fp8_sdwa v[110:111], v30 src0_sel:WORD_1
	v_pk_fma_f32 v[72:73], v[104:105], v[144:145], v[72:73] op_sel_hi:[1,0,1]
	v_pk_fma_f32 v[74:75], v[106:107], v[144:145], v[74:75] op_sel_hi:[1,0,1]
	v_pk_fma_f32 v[72:73], v[108:109], v[146:147], v[72:73] op_sel_hi:[1,0,1]
	v_pk_fma_f32 v[74:75], v[110:111], v[146:147], v[74:75] op_sel_hi:[1,0,1]
	v_cvt_pk_f32_fp8_e32 v[104:105], v27
	v_cvt_pk_f32_fp8_e32 v[108:109], v31
	v_cvt_pk_f32_fp8_sdwa v[106:107], v27 src0_sel:WORD_1
	v_cvt_pk_f32_fp8_sdwa v[110:111], v31 src0_sel:WORD_1
	v_pk_fma_f32 v[76:77], v[104:105], v[144:145], v[76:77] op_sel_hi:[1,0,1]
	v_pk_fma_f32 v[78:79], v[106:107], v[144:145], v[78:79] op_sel_hi:[1,0,1]
	s_waitcnt lgkmcnt(0)
	v_and_or_b32 v142, v142, s90, v240
	v_and_or_b32 v143, v143, s90, v240
	global_load_dwordx4 v[24:27], v142, s[84:85]
	global_load_dwordx4 v[28:31], v143, s[84:85]
	v_pk_fma_f32 v[76:77], v[108:109], v[146:147], v[76:77] op_sel_hi:[1,0,1]
	v_pk_fma_f32 v[78:79], v[110:111], v[146:147], v[78:79] op_sel_hi:[1,0,1]
	ds_bpermute_b32 v142, v249, v135
	ds_bpermute_b32 v143, v250, v135
	ds_bpermute_b32 v144, v251, v137
	ds_bpermute_b32 v146, v252, v137
	s_waitcnt vmcnt(18) lgkmcnt(4)
	v_cvt_pk_f32_fp8_e32 v[104:105], v32
	v_cvt_pk_f32_fp8_e32 v[108:109], v36
	v_cvt_pk_f32_fp8_sdwa v[106:107], v32 src0_sel:WORD_1
	v_cvt_pk_f32_fp8_sdwa v[110:111], v36 src0_sel:WORD_1
	v_pk_fma_f32 v[64:65], v[104:105], v[138:139], v[64:65] op_sel_hi:[1,0,1]
	v_pk_fma_f32 v[66:67], v[106:107], v[138:139], v[66:67] op_sel_hi:[1,0,1]
	v_pk_fma_f32 v[64:65], v[108:109], v[140:141], v[64:65] op_sel_hi:[1,0,1]
	v_pk_fma_f32 v[66:67], v[110:111], v[140:141], v[66:67] op_sel_hi:[1,0,1]
	v_cvt_pk_f32_fp8_e32 v[104:105], v33
	v_cvt_pk_f32_fp8_e32 v[108:109], v37
	v_cvt_pk_f32_fp8_sdwa v[106:107], v33 src0_sel:WORD_1
	v_cvt_pk_f32_fp8_sdwa v[110:111], v37 src0_sel:WORD_1
	v_pk_fma_f32 v[68:69], v[104:105], v[138:139], v[68:69] op_sel_hi:[1,0,1]
	v_pk_fma_f32 v[70:71], v[106:107], v[138:139], v[70:71] op_sel_hi:[1,0,1]
	v_pk_fma_f32 v[68:69], v[108:109], v[140:141], v[68:69] op_sel_hi:[1,0,1]
	v_pk_fma_f32 v[70:71], v[110:111], v[140:141], v[70:71] op_sel_hi:[1,0,1]
	v_cvt_pk_f32_fp8_e32 v[104:105], v34
	v_cvt_pk_f32_fp8_e32 v[108:109], v38
	v_cvt_pk_f32_fp8_sdwa v[106:107], v34 src0_sel:WORD_1
	v_cvt_pk_f32_fp8_sdwa v[110:111], v38 src0_sel:WORD_1
	v_pk_fma_f32 v[72:73], v[104:105], v[138:139], v[72:73] op_sel_hi:[1,0,1]
	v_pk_fma_f32 v[74:75], v[106:107], v[138:139], v[74:75] op_sel_hi:[1,0,1]
	v_pk_fma_f32 v[72:73], v[108:109], v[140:141], v[72:73] op_sel_hi:[1,0,1]
	v_pk_fma_f32 v[74:75], v[110:111], v[140:141], v[74:75] op_sel_hi:[1,0,1]
	v_cvt_pk_f32_fp8_e32 v[104:105], v35
	v_cvt_pk_f32_fp8_e32 v[108:109], v39
	v_cvt_pk_f32_fp8_sdwa v[106:107], v35 src0_sel:WORD_1
	v_cvt_pk_f32_fp8_sdwa v[110:111], v39 src0_sel:WORD_1
	v_pk_fma_f32 v[76:77], v[104:105], v[138:139], v[76:77] op_sel_hi:[1,0,1]
	v_pk_fma_f32 v[78:79], v[106:107], v[138:139], v[78:79] op_sel_hi:[1,0,1]
	s_waitcnt lgkmcnt(0)
	v_and_or_b32 v142, v142, s90, v240
	v_and_or_b32 v143, v143, s90, v240
	global_load_dwordx4 v[32:35], v142, s[84:85]
	global_load_dwordx4 v[36:39], v143, s[84:85]
	v_pk_fma_f32 v[76:77], v[108:109], v[140:141], v[76:77] op_sel_hi:[1,0,1]
	v_pk_fma_f32 v[78:79], v[110:111], v[140:141], v[78:79] op_sel_hi:[1,0,1]
	ds_bpermute_b32 v142, v251, v135
	ds_bpermute_b32 v143, v252, v135
	ds_bpermute_b32 v138, v253, v137
	ds_bpermute_b32 v140, v254, v137
	s_waitcnt vmcnt(18) lgkmcnt(4)
	v_cvt_pk_f32_fp8_e32 v[104:105], v40
	v_cvt_pk_f32_fp8_e32 v[108:109], v44
	v_cvt_pk_f32_fp8_sdwa v[106:107], v40 src0_sel:WORD_1
	v_cvt_pk_f32_fp8_sdwa v[110:111], v44 src0_sel:WORD_1
	v_pk_fma_f32 v[64:65], v[104:105], v[144:145], v[64:65] op_sel_hi:[1,0,1]
	v_pk_fma_f32 v[66:67], v[106:107], v[144:145], v[66:67] op_sel_hi:[1,0,1]
	v_pk_fma_f32 v[64:65], v[108:109], v[146:147], v[64:65] op_sel_hi:[1,0,1]
	v_pk_fma_f32 v[66:67], v[110:111], v[146:147], v[66:67] op_sel_hi:[1,0,1]
	v_cvt_pk_f32_fp8_e32 v[104:105], v41
	v_cvt_pk_f32_fp8_e32 v[108:109], v45
	v_cvt_pk_f32_fp8_sdwa v[106:107], v41 src0_sel:WORD_1
	v_cvt_pk_f32_fp8_sdwa v[110:111], v45 src0_sel:WORD_1
	v_pk_fma_f32 v[68:69], v[104:105], v[144:145], v[68:69] op_sel_hi:[1,0,1]
	v_pk_fma_f32 v[70:71], v[106:107], v[144:145], v[70:71] op_sel_hi:[1,0,1]
	v_pk_fma_f32 v[68:69], v[108:109], v[146:147], v[68:69] op_sel_hi:[1,0,1]
	v_pk_fma_f32 v[70:71], v[110:111], v[146:147], v[70:71] op_sel_hi:[1,0,1]
	v_cvt_pk_f32_fp8_e32 v[104:105], v42
	v_cvt_pk_f32_fp8_e32 v[108:109], v46
	v_cvt_pk_f32_fp8_sdwa v[106:107], v42 src0_sel:WORD_1
	v_cvt_pk_f32_fp8_sdwa v[110:111], v46 src0_sel:WORD_1
	v_pk_fma_f32 v[72:73], v[104:105], v[144:145], v[72:73] op_sel_hi:[1,0,1]
	v_pk_fma_f32 v[74:75], v[106:107], v[144:145], v[74:75] op_sel_hi:[1,0,1]
	v_pk_fma_f32 v[72:73], v[108:109], v[146:147], v[72:73] op_sel_hi:[1,0,1]
	v_pk_fma_f32 v[74:75], v[110:111], v[146:147], v[74:75] op_sel_hi:[1,0,1]
	v_cvt_pk_f32_fp8_e32 v[104:105], v43
	v_cvt_pk_f32_fp8_e32 v[108:109], v47
	v_cvt_pk_f32_fp8_sdwa v[106:107], v43 src0_sel:WORD_1
	v_cvt_pk_f32_fp8_sdwa v[110:111], v47 src0_sel:WORD_1
	v_pk_fma_f32 v[76:77], v[104:105], v[144:145], v[76:77] op_sel_hi:[1,0,1]
	v_pk_fma_f32 v[78:79], v[106:107], v[144:145], v[78:79] op_sel_hi:[1,0,1]
	s_waitcnt lgkmcnt(0)
; DEV void peer_gather(const Params& P, int l, int m0, const int* idxs, const float* gs) {
;     ...
;       hv[q][0] += acc[2 * q][0] * TAB_INV; hv[q][1] += acc[2 * q][1] * TAB_INV; hv[q][2] += acc[2 * q + 1][0] * TAB_INV; hv[q][3] += acc[2 * q + 1][1] * TAB_INV;
;       ss += hv[q][0] * hv[q][0] + hv[q][1] * hv[q][1] + hv[q][2] * hv[q][2] + hv[q][3] * hv[q][3];
;       *(f32x4*)(hrow + 4 * q) = hv[q];
	v_and_or_b32 v142, v142, s90, v240
	v_and_or_b32 v143, v143, s90, v240
	global_load_dwordx4 v[40:43], v142, s[84:85]
	global_load_dwordx4 v[44:47], v143, s[84:85]
	v_pk_fma_f32 v[76:77], v[108:109], v[146:147], v[76:77] op_sel_hi:[1,0,1]
	v_pk_fma_f32 v[78:79], v[110:111], v[146:147], v[78:79] op_sel_hi:[1,0,1]
	ds_bpermute_b32 v142, v253, v135
	ds_bpermute_b32 v143, v254, v135
	ds_bpermute_b32 v144, v255, v137
	ds_bpermute_b32 v146, v153, v137
	s_waitcnt vmcnt(18) lgkmcnt(4)
	v_cvt_pk_f32_fp8_e32 v[104:105], v48
	v_cvt_pk_f32_fp8_e32 v[108:109], v52
	v_cvt_pk_f32_fp8_sdwa v[106:107], v48 src0_sel:WORD_1
	v_cvt_pk_f32_fp8_sdwa v[110:111], v52 src0_sel:WORD_1
	v_pk_fma_f32 v[64:65], v[104:105], v[138:139], v[64:65] op_sel_hi:[1,0,1]
	v_pk_fma_f32 v[66:67], v[106:107], v[138:139], v[66:67] op_sel_hi:[1,0,1]
	v_pk_fma_f32 v[64:65], v[108:109], v[140:141], v[64:65] op_sel_hi:[1,0,1]
	v_pk_fma_f32 v[66:67], v[110:111], v[140:141], v[66:67] op_sel_hi:[1,0,1]
	v_cvt_pk_f32_fp8_e32 v[104:105], v49
	v_cvt_pk_f32_fp8_e32 v[108:109], v53
	v_cvt_pk_f32_fp8_sdwa v[106:107], v49 src0_sel:WORD_1
	v_cvt_pk_f32_fp8_sdwa v[110:111], v53 src0_sel:WORD_1
	v_pk_fma_f32 v[68:69], v[104:105], v[138:139], v[68:69] op_sel_hi:[1,0,1]
	v_pk_fma_f32 v[70:71], v[106:107], v[138:139], v[70:71] op_sel_hi:[1,0,1]
	v_pk_fma_f32 v[68:69], v[108:109], v[140:141], v[68:69] op_sel_hi:[1,0,1]
	v_pk_fma_f32 v[70:71], v[110:111], v[140:141], v[70:71] op_sel_hi:[1,0,1]
	v_cvt_pk_f32_fp8_e32 v[104:105], v50
	v_cvt_pk_f32_fp8_e32 v[108:109], v54
	v_cvt_pk_f32_fp8_sdwa v[106:107], v50 src0_sel:WORD_1
	v_cvt_pk_f32_fp8_sdwa v[110:111], v54 src0_sel:WORD_1
	v_pk_fma_f32 v[72:73], v[104:105], v[138:139], v[72:73] op_sel_hi:[1,0,1]
	v_pk_fma_f32 v[74:75], v[106:107], v[138:139], v[74:75] op_sel_hi:[1,0,1]
	v_pk_fma_f32 v[72:73], v[108:109], v[140:141], v[72:73] op_sel_hi:[1,0,1]
	v_pk_fma_f32 v[74:75], v[110:111], v[140:141], v[74:75] op_sel_hi:[1,0,1]
	v_cvt_pk_f32_fp8_e32 v[104:105], v51
	v_cvt_pk_f32_fp8_e32 v[108:109], v55
	v_cvt_pk_f32_fp8_sdwa v[106:107], v51 src0_sel:WORD_1
	v_cvt_pk_f32_fp8_sdwa v[110:111], v55 src0_sel:WORD_1
	v_pk_fma_f32 v[76:77], v[104:105], v[138:139], v[76:77] op_sel_hi:[1,0,1]
	v_pk_fma_f32 v[78:79], v[106:107], v[138:139], v[78:79] op_sel_hi:[1,0,1]
	s_waitcnt lgkmcnt(0)
	v_and_or_b32 v142, v142, s90, v240
	v_and_or_b32 v143, v143, s90, v240
	global_load_dwordx4 v[48:51], v142, s[84:85]
	global_load_dwordx4 v[52:55], v143, s[84:85]
	v_pk_fma_f32 v[76:77], v[108:109], v[140:141], v[76:77] op_sel_hi:[1,0,1]
	v_pk_fma_f32 v[78:79], v[110:111], v[140:141], v[78:79] op_sel_hi:[1,0,1]
	ds_bpermute_b32 v142, v255, v135
	ds_bpermute_b32 v143, v153, v135
	s_waitcnt vmcnt(18) lgkmcnt(2)
	v_cvt_pk_f32_fp8_e32 v[104:105], v56
	v_cvt_pk_f32_fp8_e32 v[108:109], v60
	v_cvt_pk_f32_fp8_sdwa v[106:107], v56 src0_sel:WORD_1
	v_cvt_pk_f32_fp8_sdwa v[110:111], v60 src0_sel:WORD_1
	v_pk_fma_f32 v[64:65], v[104:105], v[144:145], v[64:65] op_sel_hi:[1,0,1]
	v_pk_fma_f32 v[66:67], v[106:107], v[144:145], v[66:67] op_sel_hi:[1,0,1]
	v_pk_fma_f32 v[64:65], v[108:109], v[146:147], v[64:65] op_sel_hi:[1,0,1]
	v_pk_fma_f32 v[66:67], v[110:111], v[146:147], v[66:67] op_sel_hi:[1,0,1]
	v_cvt_pk_f32_fp8_e32 v[104:105], v57
	v_cvt_pk_f32_fp8_e32 v[108:109], v61
	v_cvt_pk_f32_fp8_sdwa v[106:107], v57 src0_sel:WORD_1
	v_cvt_pk_f32_fp8_sdwa v[110:111], v61 src0_sel:WORD_1
	v_pk_fma_f32 v[68:69], v[104:105], v[144:145], v[68:69] op_sel_hi:[1,0,1]
	v_pk_fma_f32 v[70:71], v[106:107], v[144:145], v[70:71] op_sel_hi:[1,0,1]
	v_pk_fma_f32 v[68:69], v[108:109], v[146:147], v[68:69] op_sel_hi:[1,0,1]
	v_pk_fma_f32 v[70:71], v[110:111], v[146:147], v[70:71] op_sel_hi:[1,0,1]
	v_cvt_pk_f32_fp8_e32 v[104:105], v58
	v_cvt_pk_f32_fp8_e32 v[108:109], v62
	v_cvt_pk_f32_fp8_sdwa v[106:107], v58 src0_sel:WORD_1
	v_cvt_pk_f32_fp8_sdwa v[110:111], v62 src0_sel:WORD_1
	v_pk_fma_f32 v[72:73], v[104:105], v[144:145], v[72:73] op_sel_hi:[1,0,1]
	v_pk_fma_f32 v[74:75], v[106:107], v[144:145], v[74:75] op_sel_hi:[1,0,1]
	v_pk_fma_f32 v[72:73], v[108:109], v[146:147], v[72:73] op_sel_hi:[1,0,1]
	v_pk_fma_f32 v[74:75], v[110:111], v[146:147], v[74:75] op_sel_hi:[1,0,1]
	v_cvt_pk_f32_fp8_e32 v[104:105], v59
	v_cvt_pk_f32_fp8_e32 v[108:109], v63
	v_cvt_pk_f32_fp8_sdwa v[106:107], v59 src0_sel:WORD_1
	v_cvt_pk_f32_fp8_sdwa v[110:111], v63 src0_sel:WORD_1
	v_pk_fma_f32 v[76:77], v[104:105], v[144:145], v[76:77] op_sel_hi:[1,0,1]
	v_pk_fma_f32 v[78:79], v[106:107], v[144:145], v[78:79] op_sel_hi:[1,0,1]
	s_waitcnt lgkmcnt(0)
	v_and_or_b32 v142, v142, s90, v240
	v_and_or_b32 v143, v143, s90, v240
	global_load_dwordx4 v[56:59], v142, s[84:85]
	global_load_dwordx4 v[60:63], v143, s[84:85]
	v_pk_fma_f32 v[76:77], v[108:109], v[146:147], v[76:77] op_sel_hi:[1,0,1]
	v_pk_fma_f32 v[78:79], v[110:111], v[146:147], v[78:79] op_sel_hi:[1,0,1]
	s_add_u32 s92, s100, 2
	s_min_u32 s92, s92, 127
	s_and_b32 s92, s92, 15
	s_lshl_b32 vcc_lo, s92, 9
	s_add_u32 vcc_lo, vcc_lo, s101
	v_add_u32_e32 v116, vcc_lo, v234
	ds_read_b32 v134, v116
	ds_read_b32 v135, v116 offset:256
	s_add_u32 s92, s100, 1
	s_min_u32 s92, s92, 127
	s_and_b32 s92, s92, 15
	s_lshl_b32 vcc_lo, s92, 9
	s_add_u32 vcc_lo, vcc_lo, s101
	s_add_u32 vcc_lo, vcc_lo, 0x10000
	v_add_u32_e32 v117, vcc_lo, v234
	ds_read_b32 v136, v117
	ds_read_b32 v137, v117 offset:256
	s_nop 1
	v_permlane32_swap_b32_e32 v64, v65
	v_permlane32_swap_b32_e32 v66, v67
	v_permlane32_swap_b32_e32 v68, v69
	v_permlane32_swap_b32_e32 v70, v71
	v_permlane32_swap_b32_e32 v72, v73
	v_permlane32_swap_b32_e32 v74, v75
	v_permlane32_swap_b32_e32 v76, v77
	v_permlane32_swap_b32_e32 v78, v79
	v_add_f32_e32 v64, v64, v65
	v_add_f32_e32 v66, v66, v67
	v_add_f32_e32 v68, v68, v69
	v_add_f32_e32 v70, v70, v71
	v_add_f32_e32 v72, v72, v73
	v_add_f32_e32 v74, v74, v75
	v_add_f32_e32 v76, v76, v77
	v_add_f32_e32 v78, v78, v79
	s_nop 1
	v_permlane16_swap_b32_e32 v64, v66
	v_permlane16_swap_b32_e32 v68, v70
	v_permlane16_swap_b32_e32 v72, v74
	v_permlane16_swap_b32_e32 v76, v78
	v_add_f32_e32 v64, v64, v66
	v_add_f32_e32 v68, v68, v70
	v_add_f32_e32 v72, v72, v74
	v_add_f32_e32 v76, v76, v78
	s_mov_b32 s88, 0xff00ff00
	s_mov_b32 s89, 0xff00ff00
	s_nop 0
	v_cndmask_b32_e64 v65, v64, v68, s[88:89]
	v_cndmask_b32_e64 v66, v68, v64, s[88:89]
	v_cndmask_b32_e64 v73, v72, v76, s[88:89]
	v_cndmask_b32_e64 v74, v76, v72, s[88:89]
	s_nop 1
	v_add_f32_dpp v64, v66, v65 row_ror:8 row_mask:0xf bank_mask:0xf
	v_add_f32_dpp v72, v74, v73 row_ror:8 row_mask:0xf bank_mask:0xf
	s_waitcnt vmcnt(16)
	v_fmac_f32_e32 v80, 0x3c800000, v64
	v_fmac_f32_e32 v81, 0x3c800000, v72
	global_store_dword v119, v80, s[82:83]
	global_store_dword v119, v81, s[82:83] offset:32
	s_add_u32 s100, s100, 1
	s_cmp_lt_u32 s100, 128
	s_cbranch_scc1 .Lpg0_vloop
; DEV void peer_gather(const Params& P, int l, int m0, const int* idxs, const float* gs) {
;     ...
;     for (int q = 0; q < 4; ++q) {
;       const f32x4 g = *(const f32x4*)(gp + lane * 16 + 4 * q);
	s_waitcnt vmcnt(0) lgkmcnt(0)
	v_readfirstlane_b32 s88, v130
	v_readfirstlane_b32 s89, v131
	s_nop 4
	v_lshlrev_b32_e32 v117, 6, v233
	global_load_dwordx4 v[16:19], v117, s[88:89] offset:0
	global_load_dwordx4 v[20:23], v117, s[88:89] offset:16
	global_load_dwordx4 v[24:27], v117, s[88:89] offset:32
	global_load_dwordx4 v[28:31], v117, s[88:89] offset:48
	s_mov_b32 s2, 0

; DEV void sort_lists(int lane, int& myi0, int& myi1, float& myg0, float& myg1) {
; #pragma unroll
;     for (int k = 2; k <= 128; k <<= 1) {
; #pragma unroll
;       for (int j = k >> 1; j >= 1; j >>= 1) {
;         if (j == 64) {
;           const bool sw_ = myi1 < myi0;
;           const int ti = sw_ ? myi1 : myi0, tj = sw_ ? myi0 : myi1; const float tg = sw_ ? myg1 : myg0, th = sw_ ? myg0 : myg1;
;           myi0 = ti; myi1 = tj; myg0 = tg; myg1 = th;
;         } else {
;           const bool lower = (lane & j) == 0;
;           {
;             const bool up = (k == 128) ? true : ((k == 64) ? true : ((lane & k) == 0));
;             const int oi = __shfl_xor(myi0, j); const float og = __shfl_xor(myg0, j);
;             const bool take = (lower == up) ? (oi < myi0) : (oi > myi0);
;             myi0 = take ? oi : myi0; myg0 = take ? og : myg0;
;           }
; DEV void peer_gather(const Params& P, int l, int m0, const int* idxs, const float* gs) {
;     ...
;   int ni0 = idxs[(wid * 16) * 128 + lane], ni1 = idxs[(wid * 16) * 128 + 64 + lane];
;   float ng0 = gs[(wid * 16) * 128 + lane], ng1 = gs[(wid * 16) * 128 + 64 + lane];
;   sort_lists(lane, ni0, ni1, ng0, ng1);
.Lpg1_p0:
	v_readlane_b32 s82, v231, 13
	v_readlane_b32 s83, v231, 14
	s_nop 4
	s_lshl_b32 s98, s2, 2
	s_add_u32 s98, s98, s33
	s_add_u32 s98, s98, 0
	s_lshl_b32 s98, s98, 9
	v_add_u32_e32 v116, s98, v234
	global_load_dword v241, v116, s[82:83]
	global_load_dword v242, v116, s[82:83] offset:256
	s_lshl_b32 s98, s2, 2
	s_add_u32 s98, s98, s33
	s_add_u32 s98, s98, 1
	s_lshl_b32 s98, s98, 9
	v_add_u32_e32 v117, s98, v234
	global_load_dword v243, v117, s[82:83]
	global_load_dword v244, v117, s[82:83] offset:256
	s_lshl_b32 s98, s2, 2
	s_add_u32 s98, s98, s33
	s_add_u32 s98, s98, 2
	s_lshl_b32 s98, s98, 9
	v_add_u32_e32 v118, s98, v234
	global_load_dword v245, v118, s[82:83]
	global_load_dword v246, v118, s[82:83] offset:256
	s_lshl_b32 s98, s2, 2
	s_add_u32 s98, s98, s33
	s_add_u32 s98, s98, 3
	s_lshl_b32 s98, s98, 9
	v_add_u32_e32 v119, s98, v234
	global_load_dword v247, v119, s[82:83]
	global_load_dword v248, v119, s[82:83] offset:256
	s_waitcnt vmcnt(0)
	v_or_b32_e32 v116, 64, v233
	v_lshl_or_b32 v241, v241, 7, v233
	v_lshl_or_b32 v242, v242, 7, v116
	v_lshl_or_b32 v243, v243, 7, v233
	v_lshl_or_b32 v244, v244, 7, v116
	v_lshl_or_b32 v245, v245, 7, v233
	v_lshl_or_b32 v246, v246, 7, v116
	v_lshl_or_b32 v247, v247, 7, v233
	v_lshl_or_b32 v248, v248, 7, v116
	v_xor_b32_e32 v116, 4, v234
	ds_bpermute_b32 v0, v116, v241
	ds_bpermute_b32 v1, v116, v243
	ds_bpermute_b32 v2, v116, v245
	ds_bpermute_b32 v3, v116, v247
	ds_bpermute_b32 v4, v116, v242
	ds_bpermute_b32 v5, v116, v244
	ds_bpermute_b32 v6, v116, v246
	ds_bpermute_b32 v7, v116, v248
	s_waitcnt lgkmcnt(0)
	s_mov_b32 s88, 0x99999999
	s_mov_b32 s89, 0x99999999
	v_min_u32_e32 v104, v241, v0
	v_max_u32_e32 v105, v241, v0
	v_cndmask_b32_e64 v241, v105, v104, s[88:89]
	v_min_u32_e32 v106, v243, v1
	v_max_u32_e32 v107, v243, v1
	v_cndmask_b32_e64 v243, v107, v106, s[88:89]
	v_min_u32_e32 v104, v245, v2
	v_max_u32_e32 v105, v245, v2
	v_cndmask_b32_e64 v245, v105, v104, s[88:89]
	v_min_u32_e32 v106, v247, v3
	v_max_u32_e32 v107, v247, v3
	v_cndmask_b32_e64 v247, v107, v106, s[88:89]
	v_min_u32_e32 v104, v242, v4
	v_max_u32_e32 v105, v242, v4
	v_cndmask_b32_e64 v242, v105, v104, s[88:89]
	v_min_u32_e32 v106, v244, v5
	v_max_u32_e32 v107, v244, v5
	v_cndmask_b32_e64 v244, v107, v106, s[88:89]
	v_min_u32_e32 v104, v246, v6
	v_max_u32_e32 v105, v246, v6
	v_cndmask_b32_e64 v246, v105, v104, s[88:89]
	v_min_u32_e32 v106, v248, v7
	v_max_u32_e32 v107, v248, v7
	v_cndmask_b32_e64 v248, v107, v106, s[88:89]
	v_xor_b32_e32 v116, 8, v234
	ds_bpermute_b32 v0, v116, v241
	ds_bpermute_b32 v1, v116, v243
	ds_bpermute_b32 v2, v116, v245
	ds_bpermute_b32 v3, v116, v247
	ds_bpermute_b32 v4, v116, v242
	ds_bpermute_b32 v5, v116, v244
	ds_bpermute_b32 v6, v116, v246
	ds_bpermute_b32 v7, v116, v248
	s_waitcnt lgkmcnt(0)
	s_mov_b32 s88, 0xc3c3c3c3
	s_mov_b32 s89, 0xc3c3c3c3
	v_min_u32_e32 v104, v241, v0
	v_max_u32_e32 v105, v241, v0
	v_cndmask_b32_e64 v241, v105, v104, s[88:89]
	v_min_u32_e32 v106, v243, v1
	v_max_u32_e32 v107, v243, v1
	v_cndmask_b32_e64 v243, v107, v106, s[88:89]
	v_min_u32_e32 v104, v245, v2
	v_max_u32_e32 v105, v245, v2
	v_cndmask_b32_e64 v245, v105, v104, s[88:89]
	v_min_u32_e32 v106, v247, v3
	v_max_u32_e32 v107, v247, v3
	v_cndmask_b32_e64 v247, v107, v106, s[88:89]
	v_min_u32_e32 v104, v242, v4
	v_max_u32_e32 v105, v242, v4
	v_cndmask_b32_e64 v242, v105, v104, s[88:89]
	v_min_u32_e32 v106, v244, v5
	v_max_u32_e32 v107, v244, v5
	v_cndmask_b32_e64 v244, v107, v106, s[88:89]
	v_min_u32_e32 v104, v246, v6
	v_max_u32_e32 v105, v246, v6
	v_cndmask_b32_e64 v246, v105, v104, s[88:89]
	v_min_u32_e32 v106, v248, v7
	v_max_u32_e32 v107, v248, v7
	v_cndmask_b32_e64 v248, v107, v106, s[88:89]
	v_xor_b32_e32 v116, 4, v234
	ds_bpermute_b32 v0, v116, v241
	ds_bpermute_b32 v1, v116, v243
	ds_bpermute_b32 v2, v116, v245
	ds_bpermute_b32 v3, v116, v247
	ds_bpermute_b32 v4, v116, v242
	ds_bpermute_b32 v5, v116, v244
	ds_bpermute_b32 v6, v116, v246
	ds_bpermute_b32 v7, v116, v248
	s_waitcnt lgkmcnt(0)
	s_mov_b32 s88, 0xa5a5a5a5
	s_mov_b32 s89, 0xa5a5a5a5
	v_min_u32_e32 v104, v241, v0
	v_max_u32_e32 v105, v241, v0
	v_cndmask_b32_e64 v241, v105, v104, s[88:89]
	v_min_u32_e32 v106, v243, v1
	v_max_u32_e32 v107, v243, v1
	v_cndmask_b32_e64 v243, v107, v106, s[88:89]
	v_min_u32_e32 v104, v245, v2
	v_max_u32_e32 v105, v245, v2
	v_cndmask_b32_e64 v245, v105, v104, s[88:89]
	v_min_u32_e32 v106, v247, v3
	v_max_u32_e32 v107, v247, v3
	v_cndmask_b32_e64 v247, v107, v106, s[88:89]
	v_min_u32_e32 v104, v242, v4
	v_max_u32_e32 v105, v242, v4
	v_cndmask_b32_e64 v242, v105, v104, s[88:89]
	v_min_u32_e32 v106, v244, v5
	v_max_u32_e32 v107, v244, v5
	v_cndmask_b32_e64 v244, v107, v106, s[88:89]
	v_min_u32_e32 v104, v246, v6
	v_max_u32_e32 v105, v246, v6
	v_cndmask_b32_e64 v246, v105, v104, s[88:89]
	v_min_u32_e32 v106, v248, v7
	v_max_u32_e32 v107, v248, v7
	v_cndmask_b32_e64 v248, v107, v106, s[88:89]
	v_xor_b32_e32 v116, 16, v234
	ds_bpermute_b32 v0, v116, v241
	ds_bpermute_b32 v1, v116, v243
	ds_bpermute_b32 v2, v116, v245
	ds_bpermute_b32 v3, v116, v247
	ds_bpermute_b32 v4, v116, v242
	ds_bpermute_b32 v5, v116, v244
	ds_bpermute_b32 v6, v116, v246
	ds_bpermute_b32 v7, v116, v248
	s_waitcnt lgkmcnt(0)
; DEV void sort_lists(int lane, int& myi0, int& myi1, float& myg0, float& myg1) {
; #pragma unroll
;     for (int k = 2; k <= 128; k <<= 1) {
; #pragma unroll
;       for (int j = k >> 1; j >= 1; j >>= 1) {
;         if (j == 64) {
;           const bool sw_ = myi1 < myi0;
;           const int ti = sw_ ? myi1 : myi0, tj = sw_ ? myi0 : myi1; const float tg = sw_ ? myg1 : myg0, th = sw_ ? myg0 : myg1;
;           myi0 = ti; myi1 = tj; myg0 = tg; myg1 = th;
;         } else {
;           const bool lower = (lane & j) == 0;
;           {
;             const bool up = (k == 128) ? true : ((k == 64) ? true : ((lane & k) == 0));
;             const int oi = __shfl_xor(myi0, j); const float og = __shfl_xor(myg0, j);
;             const bool take = (lower == up) ? (oi < myi0) : (oi > myi0);
;             myi0 = take ? oi : myi0; myg0 = take ? og : myg0;
;           }
;           {
;             const bool up = (k == 128) ? true : ((k == 64) ? false : ((lane & k) == 0));
;             const int oi = __shfl_xor(myi1, j); const float og = __shfl_xor(myg1, j);
;             const bool take = (lower == up) ? (oi < myi1) : (oi > myi1);
;             myi1 = take ? oi : myi1; myg1 = take ? og : myg1;
;           }
;         }
;       }
;     }
; }
	s_mov_b32 s88, 0xf00ff00f
	s_mov_b32 s89, 0xf00ff00f
	v_min_u32_e32 v104, v241, v0
	v_max_u32_e32 v105, v241, v0
	v_cndmask_b32_e64 v241, v105, v104, s[88:89]
	v_min_u32_e32 v106, v243, v1
	v_max_u32_e32 v107, v243, v1
	v_cndmask_b32_e64 v243, v107, v106, s[88:89]
	v_min_u32_e32 v104, v245, v2
	v_max_u32_e32 v105, v245, v2
	v_cndmask_b32_e64 v245, v105, v104, s[88:89]
	v_min_u32_e32 v106, v247, v3
	v_max_u32_e32 v107, v247, v3
	v_cndmask_b32_e64 v247, v107, v106, s[88:89]
	v_min_u32_e32 v104, v242, v4
	v_max_u32_e32 v105, v242, v4
	v_cndmask_b32_e64 v242, v105, v104, s[88:89]
	v_min_u32_e32 v106, v244, v5
	v_max_u32_e32 v107, v244, v5
	v_cndmask_b32_e64 v244, v107, v106, s[88:89]
	v_min_u32_e32 v104, v246, v6
	v_max_u32_e32 v105, v246, v6
	v_cndmask_b32_e64 v246, v105, v104, s[88:89]
	v_min_u32_e32 v106, v248, v7
	v_max_u32_e32 v107, v248, v7
	v_cndmask_b32_e64 v248, v107, v106, s[88:89]
	v_xor_b32_e32 v116, 8, v234
	ds_bpermute_b32 v0, v116, v241
	ds_bpermute_b32 v1, v116, v243
	ds_bpermute_b32 v2, v116, v245
	ds_bpermute_b32 v3, v116, v247
	ds_bpermute_b32 v4, v116, v242
	ds_bpermute_b32 v5, v116, v244
	ds_bpermute_b32 v6, v116, v246
	ds_bpermute_b32 v7, v116, v248
	s_waitcnt lgkmcnt(0)
	s_mov_b32 s88, 0xcc33cc33
	s_mov_b32 s89, 0xcc33cc33
	v_min_u32_e32 v104, v241, v0
	v_max_u32_e32 v105, v241, v0
	v_cndmask_b32_e64 v241, v105, v104, s[88:89]
	v_min_u32_e32 v106, v243, v1
	v_max_u32_e32 v107, v243, v1
	v_cndmask_b32_e64 v243, v107, v106, s[88:89]
	v_min_u32_e32 v104, v245, v2
	v_max_u32_e32 v105, v245, v2
	v_cndmask_b32_e64 v245, v105, v104, s[88:89]
	v_min_u32_e32 v106, v247, v3
	v_max_u32_e32 v107, v247, v3
	v_cndmask_b32_e64 v247, v107, v106, s[88:89]
	v_min_u32_e32 v104, v242, v4
	v_max_u32_e32 v105, v242, v4
	v_cndmask_b32_e64 v242, v105, v104, s[88:89]
	v_min_u32_e32 v106, v244, v5
	v_max_u32_e32 v107, v244, v5
	v_cndmask_b32_e64 v244, v107, v106, s[88:89]
	v_min_u32_e32 v104, v246, v6
	v_max_u32_e32 v105, v246, v6
	v_cndmask_b32_e64 v246, v105, v104, s[88:89]
	v_min_u32_e32 v106, v248, v7
	v_max_u32_e32 v107, v248, v7
	v_cndmask_b32_e64 v248, v107, v106, s[88:89]
	v_xor_b32_e32 v116, 4, v234
	ds_bpermute_b32 v0, v116, v241
	ds_bpermute_b32 v1, v116, v243
	ds_bpermute_b32 v2, v116, v245
	ds_bpermute_b32 v3, v116, v247
	ds_bpermute_b32 v4, v116, v242
	ds_bpermute_b32 v5, v116, v244
	ds_bpermute_b32 v6, v116, v246
	ds_bpermute_b32 v7, v116, v248
	s_waitcnt lgkmcnt(0)
	s_mov_b32 s88, 0xaa55aa55
	s_mov_b32 s89, 0xaa55aa55
	v_min_u32_e32 v104, v241, v0
	v_max_u32_e32 v105, v241, v0
	v_cndmask_b32_e64 v241, v105, v104, s[88:89]
	v_min_u32_e32 v106, v243, v1
	v_max_u32_e32 v107, v243, v1
	v_cndmask_b32_e64 v243, v107, v106, s[88:89]
	v_min_u32_e32 v104, v245, v2
	v_max_u32_e32 v105, v245, v2
	v_cndmask_b32_e64 v245, v105, v104, s[88:89]
	v_min_u32_e32 v106, v247, v3
	v_max_u32_e32 v107, v247, v3
	v_cndmask_b32_e64 v247, v107, v106, s[88:89]
	v_min_u32_e32 v104, v242, v4
	v_max_u32_e32 v105, v242, v4
	v_cndmask_b32_e64 v242, v105, v104, s[88:89]
	v_min_u32_e32 v106, v244, v5
	v_max_u32_e32 v107, v244, v5
	v_cndmask_b32_e64 v244, v107, v106, s[88:89]
	v_min_u32_e32 v104, v246, v6
	v_max_u32_e32 v105, v246, v6
	v_cndmask_b32_e64 v246, v105, v104, s[88:89]
	v_min_u32_e32 v106, v248, v7
	v_max_u32_e32 v107, v248, v7
	v_cndmask_b32_e64 v248, v107, v106, s[88:89]
	v_xor_b32_e32 v116, 32, v234
	ds_bpermute_b32 v0, v116, v241
	ds_bpermute_b32 v1, v116, v243
	ds_bpermute_b32 v2, v116, v245
	ds_bpermute_b32 v3, v116, v247
	ds_bpermute_b32 v4, v116, v242
	ds_bpermute_b32 v5, v116, v244
	ds_bpermute_b32 v6, v116, v246
	ds_bpermute_b32 v7, v116, v248
	s_waitcnt lgkmcnt(0)
	s_mov_b32 s88, 0xff0000ff
	s_mov_b32 s89, 0xff0000ff
	v_min_u32_e32 v104, v241, v0
	v_max_u32_e32 v105, v241, v0
	v_cndmask_b32_e64 v241, v105, v104, s[88:89]
	v_min_u32_e32 v106, v243, v1
	v_max_u32_e32 v107, v243, v1
	v_cndmask_b32_e64 v243, v107, v106, s[88:89]
	v_min_u32_e32 v104, v245, v2
	v_max_u32_e32 v105, v245, v2
	v_cndmask_b32_e64 v245, v105, v104, s[88:89]
	v_min_u32_e32 v106, v247, v3
	v_max_u32_e32 v107, v247, v3
	v_cndmask_b32_e64 v247, v107, v106, s[88:89]
	v_min_u32_e32 v104, v242, v4
	v_max_u32_e32 v105, v242, v4
	v_cndmask_b32_e64 v242, v105, v104, s[88:89]
	v_min_u32_e32 v106, v244, v5
	v_max_u32_e32 v107, v244, v5
	v_cndmask_b32_e64 v244, v107, v106, s[88:89]
	v_min_u32_e32 v104, v246, v6
	v_max_u32_e32 v105, v246, v6
	v_cndmask_b32_e64 v246, v105, v104, s[88:89]
	v_min_u32_e32 v106, v248, v7
	v_max_u32_e32 v107, v248, v7
	v_cndmask_b32_e64 v248, v107, v106, s[88:89]
	v_xor_b32_e32 v116, 16, v234
	ds_bpermute_b32 v0, v116, v241
	ds_bpermute_b32 v1, v116, v243
	ds_bpermute_b32 v2, v116, v245
	ds_bpermute_b32 v3, v116, v247
	ds_bpermute_b32 v4, v116, v242
	ds_bpermute_b32 v5, v116, v244
	ds_bpermute_b32 v6, v116, v246
	ds_bpermute_b32 v7, v116, v248
	s_waitcnt lgkmcnt(0)
	s_mov_b32 s88, 0xf0f00f0f
	s_mov_b32 s89, 0xf0f00f0f
	v_min_u32_e32 v104, v241, v0
	v_max_u32_e32 v105, v241, v0
	v_cndmask_b32_e64 v241, v105, v104, s[88:89]
	v_min_u32_e32 v106, v243, v1
	v_max_u32_e32 v107, v243, v1
	v_cndmask_b32_e64 v243, v107, v106, s[88:89]
	v_min_u32_e32 v104, v245, v2
	v_max_u32_e32 v105, v245, v2
	v_cndmask_b32_e64 v245, v105, v104, s[88:89]
	v_min_u32_e32 v106, v247, v3
	v_max_u32_e32 v107, v247, v3
	v_cndmask_b32_e64 v247, v107, v106, s[88:89]
	v_min_u32_e32 v104, v242, v4
	v_max_u32_e32 v105, v242, v4
	v_cndmask_b32_e64 v242, v105, v104, s[88:89]
	v_min_u32_e32 v106, v244, v5
	v_max_u32_e32 v107, v244, v5
	v_cndmask_b32_e64 v244, v107, v106, s[88:89]
	v_min_u32_e32 v104, v246, v6
	v_max_u32_e32 v105, v246, v6
	v_cndmask_b32_e64 v246, v105, v104, s[88:89]
	v_min_u32_e32 v106, v248, v7
	v_max_u32_e32 v107, v248, v7
	v_cndmask_b32_e64 v248, v107, v106, s[88:89]
	v_xor_b32_e32 v116, 8, v234
	ds_bpermute_b32 v0, v116, v241
	ds_bpermute_b32 v1, v116, v243
	ds_bpermute_b32 v2, v116, v245
	ds_bpermute_b32 v3, v116, v247
	ds_bpermute_b32 v4, v116, v242
	ds_bpermute_b32 v5, v116, v244
	ds_bpermute_b32 v6, v116, v246
	ds_bpermute_b32 v7, v116, v248
	s_waitcnt lgkmcnt(0)
; DEV void sort_lists(int lane, int& myi0, int& myi1, float& myg0, float& myg1) {
; #pragma unroll
;     for (int k = 2; k <= 128; k <<= 1) {
; #pragma unroll
;       for (int j = k >> 1; j >= 1; j >>= 1) {
;         if (j == 64) {
;           const bool sw_ = myi1 < myi0;
;           const int ti = sw_ ? myi1 : myi0, tj = sw_ ? myi0 : myi1; const float tg = sw_ ? myg1 : myg0, th = sw_ ? myg0 : myg1;
;           myi0 = ti; myi1 = tj; myg0 = tg; myg1 = th;
;         } else {
;           const bool lower = (lane & j) == 0;
;           {
;             const bool up = (k == 128) ? true : ((k == 64) ? true : ((lane & k) == 0));
;             const int oi = __shfl_xor(myi0, j); const float og = __shfl_xor(myg0, j);
;             const bool take = (lower == up) ? (oi < myi0) : (oi > myi0);
;             myi0 = take ? oi : myi0; myg0 = take ? og : myg0;
;           }
;           {
;             const bool up = (k == 128) ? true : ((k == 64) ? false : ((lane & k) == 0));
;             const int oi = __shfl_xor(myi1, j); const float og = __shfl_xor(myg1, j);
;             const bool take = (lower == up) ? (oi < myi1) : (oi > myi1);
;             myi1 = take ? oi : myi1; myg1 = take ? og : myg1;
;           }
;         }
;       }
;     }
; }
	s_mov_b32 s88, 0xcccc3333
	s_mov_b32 s89, 0xcccc3333
	v_min_u32_e32 v104, v241, v0
	v_max_u32_e32 v105, v241, v0
	v_cndmask_b32_e64 v241, v105, v104, s[88:89]
	v_min_u32_e32 v106, v243, v1
	v_max_u32_e32 v107, v243, v1
	v_cndmask_b32_e64 v243, v107, v106, s[88:89]
	v_min_u32_e32 v104, v245, v2
	v_max_u32_e32 v105, v245, v2
	v_cndmask_b32_e64 v245, v105, v104, s[88:89]
	v_min_u32_e32 v106, v247, v3
	v_max_u32_e32 v107, v247, v3
	v_cndmask_b32_e64 v247, v107, v106, s[88:89]
	v_min_u32_e32 v104, v242, v4
	v_max_u32_e32 v105, v242, v4
	v_cndmask_b32_e64 v242, v105, v104, s[88:89]
	v_min_u32_e32 v106, v244, v5
	v_max_u32_e32 v107, v244, v5
	v_cndmask_b32_e64 v244, v107, v106, s[88:89]
	v_min_u32_e32 v104, v246, v6
	v_max_u32_e32 v105, v246, v6
	v_cndmask_b32_e64 v246, v105, v104, s[88:89]
	v_min_u32_e32 v106, v248, v7
	v_max_u32_e32 v107, v248, v7
	v_cndmask_b32_e64 v248, v107, v106, s[88:89]
	v_xor_b32_e32 v116, 4, v234
	ds_bpermute_b32 v0, v116, v241
	ds_bpermute_b32 v1, v116, v243
	ds_bpermute_b32 v2, v116, v245
	ds_bpermute_b32 v3, v116, v247
	ds_bpermute_b32 v4, v116, v242
	ds_bpermute_b32 v5, v116, v244
	ds_bpermute_b32 v6, v116, v246
	ds_bpermute_b32 v7, v116, v248
	s_waitcnt lgkmcnt(0)
	s_mov_b32 s88, 0xaaaa5555
	s_mov_b32 s89, 0xaaaa5555
	v_min_u32_e32 v104, v241, v0
	v_max_u32_e32 v105, v241, v0
	v_cndmask_b32_e64 v241, v105, v104, s[88:89]
	v_min_u32_e32 v106, v243, v1
	v_max_u32_e32 v107, v243, v1
	v_cndmask_b32_e64 v243, v107, v106, s[88:89]
	v_min_u32_e32 v104, v245, v2
	v_max_u32_e32 v105, v245, v2
	v_cndmask_b32_e64 v245, v105, v104, s[88:89]
	v_min_u32_e32 v106, v247, v3
	v_max_u32_e32 v107, v247, v3
	v_cndmask_b32_e64 v247, v107, v106, s[88:89]
	v_min_u32_e32 v104, v242, v4
	v_max_u32_e32 v105, v242, v4
	v_cndmask_b32_e64 v242, v105, v104, s[88:89]
	v_min_u32_e32 v106, v244, v5
	v_max_u32_e32 v107, v244, v5
	v_cndmask_b32_e64 v244, v107, v106, s[88:89]
	v_min_u32_e32 v104, v246, v6
	v_max_u32_e32 v105, v246, v6
	v_cndmask_b32_e64 v246, v105, v104, s[88:89]
	v_min_u32_e32 v106, v248, v7
	v_max_u32_e32 v107, v248, v7
	v_cndmask_b32_e64 v248, v107, v106, s[88:89]
	v_xor_b32_e32 v116, 64, v234
	ds_bpermute_b32 v0, v116, v241
	ds_bpermute_b32 v1, v116, v243
	ds_bpermute_b32 v2, v116, v245
	ds_bpermute_b32 v3, v116, v247
	ds_bpermute_b32 v4, v116, v242
	ds_bpermute_b32 v5, v116, v244
	ds_bpermute_b32 v6, v116, v246
	ds_bpermute_b32 v7, v116, v248
	s_waitcnt lgkmcnt(0)
	s_mov_b32 s88, 0xffff
	s_mov_b32 s89, 0xffff0000
	v_min_u32_e32 v104, v241, v0
	v_max_u32_e32 v105, v241, v0
	v_cndmask_b32_e64 v241, v105, v104, s[88:89]
	v_min_u32_e32 v106, v243, v1
	v_max_u32_e32 v107, v243, v1
	v_cndmask_b32_e64 v243, v107, v106, s[88:89]
	v_min_u32_e32 v104, v245, v2
	v_max_u32_e32 v105, v245, v2
	v_cndmask_b32_e64 v245, v105, v104, s[88:89]
	v_min_u32_e32 v106, v247, v3
	v_max_u32_e32 v107, v247, v3
	v_cndmask_b32_e64 v247, v107, v106, s[88:89]
	v_min_u32_e32 v104, v242, v4
	v_max_u32_e32 v105, v242, v4
	v_cndmask_b32_e64 v242, v105, v104, s[88:89]
	v_min_u32_e32 v106, v244, v5
	v_max_u32_e32 v107, v244, v5
	v_cndmask_b32_e64 v244, v107, v106, s[88:89]
	v_min_u32_e32 v104, v246, v6
	v_max_u32_e32 v105, v246, v6
	v_cndmask_b32_e64 v246, v105, v104, s[88:89]
	v_min_u32_e32 v106, v248, v7
	v_max_u32_e32 v107, v248, v7
	v_cndmask_b32_e64 v248, v107, v106, s[88:89]
	v_xor_b32_e32 v116, 32, v234
	ds_bpermute_b32 v0, v116, v241
	ds_bpermute_b32 v1, v116, v243
	ds_bpermute_b32 v2, v116, v245
	ds_bpermute_b32 v3, v116, v247
	ds_bpermute_b32 v4, v116, v242
	ds_bpermute_b32 v5, v116, v244
	ds_bpermute_b32 v6, v116, v246
	ds_bpermute_b32 v7, v116, v248
	s_waitcnt lgkmcnt(0)
	s_mov_b32 s88, 0xff00ff
	s_mov_b32 s89, 0xff00ff00
	v_min_u32_e32 v104, v241, v0
	v_max_u32_e32 v105, v241, v0
	v_cndmask_b32_e64 v241, v105, v104, s[88:89]
	v_min_u32_e32 v106, v243, v1
	v_max_u32_e32 v107, v243, v1
	v_cndmask_b32_e64 v243, v107, v106, s[88:89]
	v_min_u32_e32 v104, v245, v2
	v_max_u32_e32 v105, v245, v2
	v_cndmask_b32_e64 v245, v105, v104, s[88:89]
	v_min_u32_e32 v106, v247, v3
	v_max_u32_e32 v107, v247, v3
	v_cndmask_b32_e64 v247, v107, v106, s[88:89]
	v_min_u32_e32 v104, v242, v4
	v_max_u32_e32 v105, v242, v4
	v_cndmask_b32_e64 v242, v105, v104, s[88:89]
	v_min_u32_e32 v106, v244, v5
	v_max_u32_e32 v107, v244, v5
	v_cndmask_b32_e64 v244, v107, v106, s[88:89]
	v_min_u32_e32 v104, v246, v6
	v_max_u32_e32 v105, v246, v6
	v_cndmask_b32_e64 v246, v105, v104, s[88:89]
	v_min_u32_e32 v106, v248, v7
	v_max_u32_e32 v107, v248, v7
	v_cndmask_b32_e64 v248, v107, v106, s[88:89]
	v_xor_b32_e32 v116, 16, v234
	ds_bpermute_b32 v0, v116, v241
	ds_bpermute_b32 v1, v116, v243
	ds_bpermute_b32 v2, v116, v245
	ds_bpermute_b32 v3, v116, v247
	ds_bpermute_b32 v4, v116, v242
	ds_bpermute_b32 v5, v116, v244
	ds_bpermute_b32 v6, v116, v246
	ds_bpermute_b32 v7, v116, v248
	s_waitcnt lgkmcnt(0)
	s_mov_b32 s88, 0xf0f0f0f
	s_mov_b32 s89, 0xf0f0f0f0
	v_min_u32_e32 v104, v241, v0
	v_max_u32_e32 v105, v241, v0
	v_cndmask_b32_e64 v241, v105, v104, s[88:89]
	v_min_u32_e32 v106, v243, v1
	v_max_u32_e32 v107, v243, v1
	v_cndmask_b32_e64 v243, v107, v106, s[88:89]
	v_min_u32_e32 v104, v245, v2
	v_max_u32_e32 v105, v245, v2
	v_cndmask_b32_e64 v245, v105, v104, s[88:89]
	v_min_u32_e32 v106, v247, v3
	v_max_u32_e32 v107, v247, v3
	v_cndmask_b32_e64 v247, v107, v106, s[88:89]
	v_min_u32_e32 v104, v242, v4
	v_max_u32_e32 v105, v242, v4
	v_cndmask_b32_e64 v242, v105, v104, s[88:89]
	v_min_u32_e32 v106, v244, v5
	v_max_u32_e32 v107, v244, v5
	v_cndmask_b32_e64 v244, v107, v106, s[88:89]
	v_min_u32_e32 v104, v246, v6
	v_max_u32_e32 v105, v246, v6
	v_cndmask_b32_e64 v246, v105, v104, s[88:89]
	v_min_u32_e32 v106, v248, v7
	v_max_u32_e32 v107, v248, v7
	v_cndmask_b32_e64 v248, v107, v106, s[88:89]
	v_xor_b32_e32 v116, 8, v234
	ds_bpermute_b32 v0, v116, v241
	ds_bpermute_b32 v1, v116, v243
	ds_bpermute_b32 v2, v116, v245
	ds_bpermute_b32 v3, v116, v247
	ds_bpermute_b32 v4, v116, v242
	ds_bpermute_b32 v5, v116, v244
	ds_bpermute_b32 v6, v116, v246
	ds_bpermute_b32 v7, v116, v248
	s_waitcnt lgkmcnt(0)
; DEV void sort_lists(int lane, int& myi0, int& myi1, float& myg0, float& myg1) {
; #pragma unroll
;     for (int k = 2; k <= 128; k <<= 1) {
; #pragma unroll
;       for (int j = k >> 1; j >= 1; j >>= 1) {
;         if (j == 64) {
;           const bool sw_ = myi1 < myi0;
;           const int ti = sw_ ? myi1 : myi0, tj = sw_ ? myi0 : myi1; const float tg = sw_ ? myg1 : myg0, th = sw_ ? myg0 : myg1;
;           myi0 = ti; myi1 = tj; myg0 = tg; myg1 = th;
;         } else {
;           const bool lower = (lane & j) == 0;
;           {
;             const bool up = (k == 128) ? true : ((k == 64) ? true : ((lane & k) == 0));
;             const int oi = __shfl_xor(myi0, j); const float og = __shfl_xor(myg0, j);
;             const bool take = (lower == up) ? (oi < myi0) : (oi > myi0);
;             myi0 = take ? oi : myi0; myg0 = take ? og : myg0;
;           }
;           {
;             const bool up = (k == 128) ? true : ((k == 64) ? false : ((lane & k) == 0));
;             const int oi = __shfl_xor(myi1, j); const float og = __shfl_xor(myg1, j);
;             const bool take = (lower == up) ? (oi < myi1) : (oi > myi1);
;             myi1 = take ? oi : myi1; myg1 = take ? og : myg1;
;           }
;         }
;       }
;     }
; }
	s_mov_b32 s88, 0x33333333
	s_mov_b32 s89, 0xcccccccc
	v_min_u32_e32 v104, v241, v0
	v_max_u32_e32 v105, v241, v0
	v_cndmask_b32_e64 v241, v105, v104, s[88:89]
	v_min_u32_e32 v106, v243, v1
	v_max_u32_e32 v107, v243, v1
	v_cndmask_b32_e64 v243, v107, v106, s[88:89]
	v_min_u32_e32 v104, v245, v2
	v_max_u32_e32 v105, v245, v2
	v_cndmask_b32_e64 v245, v105, v104, s[88:89]
	v_min_u32_e32 v106, v247, v3
	v_max_u32_e32 v107, v247, v3
	v_cndmask_b32_e64 v247, v107, v106, s[88:89]
	v_min_u32_e32 v104, v242, v4
	v_max_u32_e32 v105, v242, v4
	v_cndmask_b32_e64 v242, v105, v104, s[88:89]
	v_min_u32_e32 v106, v244, v5
	v_max_u32_e32 v107, v244, v5
	v_cndmask_b32_e64 v244, v107, v106, s[88:89]
	v_min_u32_e32 v104, v246, v6
	v_max_u32_e32 v105, v246, v6
	v_cndmask_b32_e64 v246, v105, v104, s[88:89]
	v_min_u32_e32 v106, v248, v7
	v_max_u32_e32 v107, v248, v7
	v_cndmask_b32_e64 v248, v107, v106, s[88:89]
	v_xor_b32_e32 v116, 4, v234
	ds_bpermute_b32 v0, v116, v241
	ds_bpermute_b32 v1, v116, v243
	ds_bpermute_b32 v2, v116, v245
	ds_bpermute_b32 v3, v116, v247
	ds_bpermute_b32 v4, v116, v242
	ds_bpermute_b32 v5, v116, v244
	ds_bpermute_b32 v6, v116, v246
	ds_bpermute_b32 v7, v116, v248
	s_waitcnt lgkmcnt(0)
	s_mov_b32 s88, 0x55555555
	s_mov_b32 s89, 0xaaaaaaaa
	v_min_u32_e32 v104, v241, v0
	v_max_u32_e32 v105, v241, v0
	v_cndmask_b32_e64 v241, v105, v104, s[88:89]
	v_min_u32_e32 v106, v243, v1
	v_max_u32_e32 v107, v243, v1
	v_cndmask_b32_e64 v243, v107, v106, s[88:89]
	v_min_u32_e32 v104, v245, v2
	v_max_u32_e32 v105, v245, v2
	v_cndmask_b32_e64 v245, v105, v104, s[88:89]
	v_min_u32_e32 v106, v247, v3
	v_max_u32_e32 v107, v247, v3
	v_cndmask_b32_e64 v247, v107, v106, s[88:89]
	v_min_u32_e32 v104, v242, v4
	v_max_u32_e32 v105, v242, v4
	v_cndmask_b32_e64 v242, v105, v104, s[88:89]
	v_min_u32_e32 v106, v244, v5
	v_max_u32_e32 v107, v244, v5
	v_cndmask_b32_e64 v244, v107, v106, s[88:89]
	v_min_u32_e32 v104, v246, v6
	v_max_u32_e32 v105, v246, v6
	v_cndmask_b32_e64 v246, v105, v104, s[88:89]
	v_min_u32_e32 v106, v248, v7
	v_max_u32_e32 v107, v248, v7
	v_cndmask_b32_e64 v248, v107, v106, s[88:89]
	v_xor_b32_e32 v116, 128, v234
	ds_bpermute_b32 v0, v116, v241
	ds_bpermute_b32 v1, v116, v243
	ds_bpermute_b32 v2, v116, v245
	ds_bpermute_b32 v3, v116, v247
	ds_bpermute_b32 v4, v116, v242
	ds_bpermute_b32 v5, v116, v244
	ds_bpermute_b32 v6, v116, v246
	ds_bpermute_b32 v7, v116, v248
	s_waitcnt lgkmcnt(0)
	s_mov_b32 s88, 0xffffffff
	s_mov_b32 s89, 0x0
	v_min_u32_e32 v104, v241, v0
	v_max_u32_e32 v105, v241, v0
	v_cndmask_b32_e64 v241, v105, v104, s[88:89]
	v_min_u32_e32 v106, v243, v1
	v_max_u32_e32 v107, v243, v1
	v_cndmask_b32_e64 v243, v107, v106, s[88:89]
	v_min_u32_e32 v104, v245, v2
	v_max_u32_e32 v105, v245, v2
	v_cndmask_b32_e64 v245, v105, v104, s[88:89]
	v_min_u32_e32 v106, v247, v3
	v_max_u32_e32 v107, v247, v3
	v_cndmask_b32_e64 v247, v107, v106, s[88:89]
	s_mov_b32 s88, 0x0
	s_mov_b32 s89, 0xffffffff
	v_min_u32_e32 v104, v242, v4
	v_max_u32_e32 v105, v242, v4
	v_cndmask_b32_e64 v242, v105, v104, s[88:89]
	v_min_u32_e32 v106, v244, v5
	v_max_u32_e32 v107, v244, v5
	v_cndmask_b32_e64 v244, v107, v106, s[88:89]
	v_min_u32_e32 v104, v246, v6
	v_max_u32_e32 v105, v246, v6
	v_cndmask_b32_e64 v246, v105, v104, s[88:89]
	v_min_u32_e32 v106, v248, v7
	v_max_u32_e32 v107, v248, v7
	v_cndmask_b32_e64 v248, v107, v106, s[88:89]
	v_xor_b32_e32 v116, 64, v234
	ds_bpermute_b32 v0, v116, v241
	ds_bpermute_b32 v1, v116, v243
	ds_bpermute_b32 v2, v116, v245
	ds_bpermute_b32 v3, v116, v247
	ds_bpermute_b32 v4, v116, v242
	ds_bpermute_b32 v5, v116, v244
	ds_bpermute_b32 v6, v116, v246
	ds_bpermute_b32 v7, v116, v248
	s_waitcnt lgkmcnt(0)
	s_mov_b32 s88, 0xffff
	s_mov_b32 s89, 0xffff
	v_min_u32_e32 v104, v241, v0
	v_max_u32_e32 v105, v241, v0
	v_cndmask_b32_e64 v241, v105, v104, s[88:89]
	v_min_u32_e32 v106, v243, v1
	v_max_u32_e32 v107, v243, v1
	v_cndmask_b32_e64 v243, v107, v106, s[88:89]
	v_min_u32_e32 v104, v245, v2
	v_max_u32_e32 v105, v245, v2
	v_cndmask_b32_e64 v245, v105, v104, s[88:89]
	v_min_u32_e32 v106, v247, v3
	v_max_u32_e32 v107, v247, v3
	v_cndmask_b32_e64 v247, v107, v106, s[88:89]
	s_mov_b32 s88, 0xffff0000
	s_mov_b32 s89, 0xffff0000
	v_min_u32_e32 v104, v242, v4
	v_max_u32_e32 v105, v242, v4
	v_cndmask_b32_e64 v242, v105, v104, s[88:89]
	v_min_u32_e32 v106, v244, v5
	v_max_u32_e32 v107, v244, v5
	v_cndmask_b32_e64 v244, v107, v106, s[88:89]
	v_min_u32_e32 v104, v246, v6
	v_max_u32_e32 v105, v246, v6
	v_cndmask_b32_e64 v246, v105, v104, s[88:89]
	v_min_u32_e32 v106, v248, v7
	v_max_u32_e32 v107, v248, v7
	v_cndmask_b32_e64 v248, v107, v106, s[88:89]
	v_xor_b32_e32 v116, 32, v234
	ds_bpermute_b32 v0, v116, v241
	ds_bpermute_b32 v1, v116, v243
	ds_bpermute_b32 v2, v116, v245
	ds_bpermute_b32 v3, v116, v247
	ds_bpermute_b32 v4, v116, v242
	ds_bpermute_b32 v5, v116, v244
	ds_bpermute_b32 v6, v116, v246
	ds_bpermute_b32 v7, v116, v248
	s_waitcnt lgkmcnt(0)
	s_mov_b32 s88, 0xff00ff
	s_mov_b32 s89, 0xff00ff
	v_min_u32_e32 v104, v241, v0
	v_max_u32_e32 v105, v241, v0
	v_cndmask_b32_e64 v241, v105, v104, s[88:89]
	v_min_u32_e32 v106, v243, v1
	v_max_u32_e32 v107, v243, v1
	v_cndmask_b32_e64 v243, v107, v106, s[88:89]
	v_min_u32_e32 v104, v245, v2
	v_max_u32_e32 v105, v245, v2
	v_cndmask_b32_e64 v245, v105, v104, s[88:89]
	v_min_u32_e32 v106, v247, v3
	v_max_u32_e32 v107, v247, v3
	v_cndmask_b32_e64 v247, v107, v106, s[88:89]
	s_mov_b32 s88, 0xff00ff00
	s_mov_b32 s89, 0xff00ff00
	v_min_u32_e32 v104, v242, v4
	v_max_u32_e32 v105, v242, v4
	v_cndmask_b32_e64 v242, v105, v104, s[88:89]
	v_min_u32_e32 v106, v244, v5
	v_max_u32_e32 v107, v244, v5
	v_cndmask_b32_e64 v244, v107, v106, s[88:89]
	v_min_u32_e32 v104, v246, v6
	v_max_u32_e32 v105, v246, v6
	v_cndmask_b32_e64 v246, v105, v104, s[88:89]
	v_min_u32_e32 v106, v248, v7
	v_max_u32_e32 v107, v248, v7
	v_cndmask_b32_e64 v248, v107, v106, s[88:89]
	v_xor_b32_e32 v116, 16, v234
	ds_bpermute_b32 v0, v116, v241
	ds_bpermute_b32 v1, v116, v243
	ds_bpermute_b32 v2, v116, v245
	ds_bpermute_b32 v3, v116, v247
	ds_bpermute_b32 v4, v116, v242
	ds_bpermute_b32 v5, v116, v244
	ds_bpermute_b32 v6, v116, v246
	ds_bpermute_b32 v7, v116, v248
	s_waitcnt lgkmcnt(0)
; DEV void sort_lists(int lane, int& myi0, int& myi1, float& myg0, float& myg1) {
; #pragma unroll
;     for (int k = 2; k <= 128; k <<= 1) {
; #pragma unroll
;       for (int j = k >> 1; j >= 1; j >>= 1) {
;         if (j == 64) {
;           const bool sw_ = myi1 < myi0;
;           const int ti = sw_ ? myi1 : myi0, tj = sw_ ? myi0 : myi1; const float tg = sw_ ? myg1 : myg0, th = sw_ ? myg0 : myg1;
;           myi0 = ti; myi1 = tj; myg0 = tg; myg1 = th;
;         } else {
;           const bool lower = (lane & j) == 0;
;           {
;             const bool up = (k == 128) ? true : ((k == 64) ? true : ((lane & k) == 0));
;             const int oi = __shfl_xor(myi0, j); const float og = __shfl_xor(myg0, j);
;             const bool take = (lower == up) ? (oi < myi0) : (oi > myi0);
;             myi0 = take ? oi : myi0; myg0 = take ? og : myg0;
;           }
;           {
;             const bool up = (k == 128) ? true : ((k == 64) ? false : ((lane & k) == 0));
;             const int oi = __shfl_xor(myi1, j); const float og = __shfl_xor(myg1, j);
;             const bool take = (lower == up) ? (oi < myi1) : (oi > myi1);
;             myi1 = take ? oi : myi1; myg1 = take ? og : myg1;
;           }
;         }
;       }
;     }
; }
	s_mov_b32 s88, 0xf0f0f0f
	s_mov_b32 s89, 0xf0f0f0f
	v_min_u32_e32 v104, v241, v0
	v_max_u32_e32 v105, v241, v0
	v_cndmask_b32_e64 v241, v105, v104, s[88:89]
	v_min_u32_e32 v106, v243, v1
	v_max_u32_e32 v107, v243, v1
	v_cndmask_b32_e64 v243, v107, v106, s[88:89]
	v_min_u32_e32 v104, v245, v2
	v_max_u32_e32 v105, v245, v2
	v_cndmask_b32_e64 v245, v105, v104, s[88:89]
	v_min_u32_e32 v106, v247, v3
	v_max_u32_e32 v107, v247, v3
	v_cndmask_b32_e64 v247, v107, v106, s[88:89]
	s_mov_b32 s88, 0xf0f0f0f0
	s_mov_b32 s89, 0xf0f0f0f0
	v_min_u32_e32 v104, v242, v4
	v_max_u32_e32 v105, v242, v4
	v_cndmask_b32_e64 v242, v105, v104, s[88:89]
	v_min_u32_e32 v106, v244, v5
	v_max_u32_e32 v107, v244, v5
	v_cndmask_b32_e64 v244, v107, v106, s[88:89]
	v_min_u32_e32 v104, v246, v6
	v_max_u32_e32 v105, v246, v6
	v_cndmask_b32_e64 v246, v105, v104, s[88:89]
	v_min_u32_e32 v106, v248, v7
	v_max_u32_e32 v107, v248, v7
	v_cndmask_b32_e64 v248, v107, v106, s[88:89]
	v_xor_b32_e32 v116, 8, v234
	ds_bpermute_b32 v0, v116, v241
	ds_bpermute_b32 v1, v116, v243
	ds_bpermute_b32 v2, v116, v245
	ds_bpermute_b32 v3, v116, v247
	ds_bpermute_b32 v4, v116, v242
	ds_bpermute_b32 v5, v116, v244
	ds_bpermute_b32 v6, v116, v246
	ds_bpermute_b32 v7, v116, v248
	s_waitcnt lgkmcnt(0)
	s_mov_b32 s88, 0x33333333
	s_mov_b32 s89, 0x33333333
	v_min_u32_e32 v104, v241, v0
	v_max_u32_e32 v105, v241, v0
	v_cndmask_b32_e64 v241, v105, v104, s[88:89]
	v_min_u32_e32 v106, v243, v1
	v_max_u32_e32 v107, v243, v1
	v_cndmask_b32_e64 v243, v107, v106, s[88:89]
	v_min_u32_e32 v104, v245, v2
	v_max_u32_e32 v105, v245, v2
	v_cndmask_b32_e64 v245, v105, v104, s[88:89]
	v_min_u32_e32 v106, v247, v3
	v_max_u32_e32 v107, v247, v3
	v_cndmask_b32_e64 v247, v107, v106, s[88:89]
	s_mov_b32 s88, 0xcccccccc
	s_mov_b32 s89, 0xcccccccc
	v_min_u32_e32 v104, v242, v4
	v_max_u32_e32 v105, v242, v4
	v_cndmask_b32_e64 v242, v105, v104, s[88:89]
	v_min_u32_e32 v106, v244, v5
	v_max_u32_e32 v107, v244, v5
	v_cndmask_b32_e64 v244, v107, v106, s[88:89]
	v_min_u32_e32 v104, v246, v6
	v_max_u32_e32 v105, v246, v6
	v_cndmask_b32_e64 v246, v105, v104, s[88:89]
	v_min_u32_e32 v106, v248, v7
	v_max_u32_e32 v107, v248, v7
	v_cndmask_b32_e64 v248, v107, v106, s[88:89]
	v_xor_b32_e32 v116, 4, v234
	ds_bpermute_b32 v0, v116, v241
	ds_bpermute_b32 v1, v116, v243
	ds_bpermute_b32 v2, v116, v245
	ds_bpermute_b32 v3, v116, v247
	ds_bpermute_b32 v4, v116, v242
	ds_bpermute_b32 v5, v116, v244
	ds_bpermute_b32 v6, v116, v246
	ds_bpermute_b32 v7, v116, v248
	s_waitcnt lgkmcnt(0)
	s_mov_b32 s88, 0x55555555
	s_mov_b32 s89, 0x55555555
	v_min_u32_e32 v104, v241, v0
	v_max_u32_e32 v105, v241, v0
	v_cndmask_b32_e64 v241, v105, v104, s[88:89]
	v_min_u32_e32 v106, v243, v1
	v_max_u32_e32 v107, v243, v1
	v_cndmask_b32_e64 v243, v107, v106, s[88:89]
	v_min_u32_e32 v104, v245, v2
	v_max_u32_e32 v105, v245, v2
	v_cndmask_b32_e64 v245, v105, v104, s[88:89]
	v_min_u32_e32 v106, v247, v3
	v_max_u32_e32 v107, v247, v3
	v_cndmask_b32_e64 v247, v107, v106, s[88:89]
	s_mov_b32 s88, 0xaaaaaaaa
	s_mov_b32 s89, 0xaaaaaaaa
	v_min_u32_e32 v104, v242, v4
	v_max_u32_e32 v105, v242, v4
	v_cndmask_b32_e64 v242, v105, v104, s[88:89]
	v_min_u32_e32 v106, v244, v5
	v_max_u32_e32 v107, v244, v5
	v_cndmask_b32_e64 v244, v107, v106, s[88:89]
	v_min_u32_e32 v104, v246, v6
	v_max_u32_e32 v105, v246, v6
	v_cndmask_b32_e64 v246, v105, v104, s[88:89]
	v_min_u32_e32 v106, v248, v7
	v_max_u32_e32 v107, v248, v7
	v_cndmask_b32_e64 v248, v107, v106, s[88:89]
	v_min_u32_e32 v104, v241, v242
	v_max_u32_e32 v242, v241, v242
	v_mov_b32_e32 v241, v104
	v_min_u32_e32 v106, v243, v244
	v_max_u32_e32 v244, v243, v244
	v_mov_b32_e32 v243, v106
	v_min_u32_e32 v104, v245, v246
	v_max_u32_e32 v246, v245, v246
	v_mov_b32_e32 v245, v104
	v_min_u32_e32 v106, v247, v248
	v_max_u32_e32 v248, v247, v248
	v_mov_b32_e32 v247, v106
	v_xor_b32_e32 v116, 128, v234
	ds_bpermute_b32 v0, v116, v241
	ds_bpermute_b32 v1, v116, v243
	ds_bpermute_b32 v2, v116, v245
	ds_bpermute_b32 v3, v116, v247
	ds_bpermute_b32 v4, v116, v242
	ds_bpermute_b32 v5, v116, v244
	ds_bpermute_b32 v6, v116, v246
	ds_bpermute_b32 v7, v116, v248
	s_waitcnt lgkmcnt(0)
	s_mov_b32 s88, 0xffffffff
	s_mov_b32 s89, 0x0
	v_min_u32_e32 v104, v241, v0
	v_max_u32_e32 v105, v241, v0
	v_cndmask_b32_e64 v241, v105, v104, s[88:89]
	v_min_u32_e32 v106, v243, v1
	v_max_u32_e32 v107, v243, v1
	v_cndmask_b32_e64 v243, v107, v106, s[88:89]
	v_min_u32_e32 v104, v245, v2
	v_max_u32_e32 v105, v245, v2
	v_cndmask_b32_e64 v245, v105, v104, s[88:89]
	v_min_u32_e32 v106, v247, v3
	v_max_u32_e32 v107, v247, v3
	v_cndmask_b32_e64 v247, v107, v106, s[88:89]
	v_min_u32_e32 v104, v242, v4
	v_max_u32_e32 v105, v242, v4
	v_cndmask_b32_e64 v242, v105, v104, s[88:89]
	v_min_u32_e32 v106, v244, v5
	v_max_u32_e32 v107, v244, v5
	v_cndmask_b32_e64 v244, v107, v106, s[88:89]
	v_min_u32_e32 v104, v246, v6
	v_max_u32_e32 v105, v246, v6
	v_cndmask_b32_e64 v246, v105, v104, s[88:89]
	v_min_u32_e32 v106, v248, v7
	v_max_u32_e32 v107, v248, v7
	v_cndmask_b32_e64 v248, v107, v106, s[88:89]
	v_xor_b32_e32 v116, 64, v234
	ds_bpermute_b32 v0, v116, v241
	ds_bpermute_b32 v1, v116, v243
	ds_bpermute_b32 v2, v116, v245
	ds_bpermute_b32 v3, v116, v247
	ds_bpermute_b32 v4, v116, v242
	ds_bpermute_b32 v5, v116, v244
	ds_bpermute_b32 v6, v116, v246
	ds_bpermute_b32 v7, v116, v248
	s_waitcnt lgkmcnt(0)
; DEV void sort_lists(int lane, int& myi0, int& myi1, float& myg0, float& myg1) {
; #pragma unroll
;     for (int k = 2; k <= 128; k <<= 1) {
; #pragma unroll
;       for (int j = k >> 1; j >= 1; j >>= 1) {
;         if (j == 64) {
;           const bool sw_ = myi1 < myi0;
;           const int ti = sw_ ? myi1 : myi0, tj = sw_ ? myi0 : myi1; const float tg = sw_ ? myg1 : myg0, th = sw_ ? myg0 : myg1;
;           myi0 = ti; myi1 = tj; myg0 = tg; myg1 = th;
;         } else {
;           const bool lower = (lane & j) == 0;
;           {
;             const bool up = (k == 128) ? true : ((k == 64) ? true : ((lane & k) == 0));
;             const int oi = __shfl_xor(myi0, j); const float og = __shfl_xor(myg0, j);
;             const bool take = (lower == up) ? (oi < myi0) : (oi > myi0);
;             myi0 = take ? oi : myi0; myg0 = take ? og : myg0;
;           }
;           {
;             const bool up = (k == 128) ? true : ((k == 64) ? false : ((lane & k) == 0));
;             const int oi = __shfl_xor(myi1, j); const float og = __shfl_xor(myg1, j);
;             const bool take = (lower == up) ? (oi < myi1) : (oi > myi1);
;             myi1 = take ? oi : myi1; myg1 = take ? og : myg1;
;           }
;         }
;       }
;     }
; }
; DEV void peer_gather(const Params& P, int l, int m0, const int* idxs, const float* gs) {
;     ...
;   sort_lists(lane, ni0, ni1, ng0, ng1);
	s_mov_b32 s88, 0xffff
	s_mov_b32 s89, 0xffff
	v_min_u32_e32 v104, v241, v0
	v_max_u32_e32 v105, v241, v0
	v_cndmask_b32_e64 v241, v105, v104, s[88:89]
	v_min_u32_e32 v106, v243, v1
	v_max_u32_e32 v107, v243, v1
	v_cndmask_b32_e64 v243, v107, v106, s[88:89]
	v_min_u32_e32 v104, v245, v2
	v_max_u32_e32 v105, v245, v2
	v_cndmask_b32_e64 v245, v105, v104, s[88:89]
	v_min_u32_e32 v106, v247, v3
	v_max_u32_e32 v107, v247, v3
	v_cndmask_b32_e64 v247, v107, v106, s[88:89]
	v_min_u32_e32 v104, v242, v4
	v_max_u32_e32 v105, v242, v4
	v_cndmask_b32_e64 v242, v105, v104, s[88:89]
	v_min_u32_e32 v106, v244, v5
	v_max_u32_e32 v107, v244, v5
	v_cndmask_b32_e64 v244, v107, v106, s[88:89]
	v_min_u32_e32 v104, v246, v6
	v_max_u32_e32 v105, v246, v6
	v_cndmask_b32_e64 v246, v105, v104, s[88:89]
	v_min_u32_e32 v106, v248, v7
	v_max_u32_e32 v107, v248, v7
	v_cndmask_b32_e64 v248, v107, v106, s[88:89]
	v_xor_b32_e32 v116, 32, v234
	ds_bpermute_b32 v0, v116, v241
	ds_bpermute_b32 v1, v116, v243
	ds_bpermute_b32 v2, v116, v245
	ds_bpermute_b32 v3, v116, v247
	ds_bpermute_b32 v4, v116, v242
	ds_bpermute_b32 v5, v116, v244
	ds_bpermute_b32 v6, v116, v246
	ds_bpermute_b32 v7, v116, v248
	s_waitcnt lgkmcnt(0)
	s_mov_b32 s88, 0xff00ff
	s_mov_b32 s89, 0xff00ff
	v_min_u32_e32 v104, v241, v0
	v_max_u32_e32 v105, v241, v0
	v_cndmask_b32_e64 v241, v105, v104, s[88:89]
	v_min_u32_e32 v106, v243, v1
	v_max_u32_e32 v107, v243, v1
	v_cndmask_b32_e64 v243, v107, v106, s[88:89]
	v_min_u32_e32 v104, v245, v2
	v_max_u32_e32 v105, v245, v2
	v_cndmask_b32_e64 v245, v105, v104, s[88:89]
	v_min_u32_e32 v106, v247, v3
	v_max_u32_e32 v107, v247, v3
	v_cndmask_b32_e64 v247, v107, v106, s[88:89]
	v_min_u32_e32 v104, v242, v4
	v_max_u32_e32 v105, v242, v4
	v_cndmask_b32_e64 v242, v105, v104, s[88:89]
	v_min_u32_e32 v106, v244, v5
	v_max_u32_e32 v107, v244, v5
	v_cndmask_b32_e64 v244, v107, v106, s[88:89]
	v_min_u32_e32 v104, v246, v6
	v_max_u32_e32 v105, v246, v6
	v_cndmask_b32_e64 v246, v105, v104, s[88:89]
	v_min_u32_e32 v106, v248, v7
	v_max_u32_e32 v107, v248, v7
	v_cndmask_b32_e64 v248, v107, v106, s[88:89]
	v_xor_b32_e32 v116, 16, v234
	ds_bpermute_b32 v0, v116, v241
	ds_bpermute_b32 v1, v116, v243
	ds_bpermute_b32 v2, v116, v245
	ds_bpermute_b32 v3, v116, v247
	ds_bpermute_b32 v4, v116, v242
	ds_bpermute_b32 v5, v116, v244
	ds_bpermute_b32 v6, v116, v246
	ds_bpermute_b32 v7, v116, v248
	s_waitcnt lgkmcnt(0)
	s_mov_b32 s88, 0xf0f0f0f
	s_mov_b32 s89, 0xf0f0f0f
	v_min_u32_e32 v104, v241, v0
	v_max_u32_e32 v105, v241, v0
	v_cndmask_b32_e64 v241, v105, v104, s[88:89]
	v_min_u32_e32 v106, v243, v1
	v_max_u32_e32 v107, v243, v1
	v_cndmask_b32_e64 v243, v107, v106, s[88:89]
	v_min_u32_e32 v104, v245, v2
	v_max_u32_e32 v105, v245, v2
	v_cndmask_b32_e64 v245, v105, v104, s[88:89]
	v_min_u32_e32 v106, v247, v3
	v_max_u32_e32 v107, v247, v3
	v_cndmask_b32_e64 v247, v107, v106, s[88:89]
	v_min_u32_e32 v104, v242, v4
	v_max_u32_e32 v105, v242, v4
	v_cndmask_b32_e64 v242, v105, v104, s[88:89]
	v_min_u32_e32 v106, v244, v5
	v_max_u32_e32 v107, v244, v5
	v_cndmask_b32_e64 v244, v107, v106, s[88:89]
	v_min_u32_e32 v104, v246, v6
	v_max_u32_e32 v105, v246, v6
	v_cndmask_b32_e64 v246, v105, v104, s[88:89]
	v_min_u32_e32 v106, v248, v7
	v_max_u32_e32 v107, v248, v7
	v_cndmask_b32_e64 v248, v107, v106, s[88:89]
	v_xor_b32_e32 v116, 8, v234
	ds_bpermute_b32 v0, v116, v241
	ds_bpermute_b32 v1, v116, v243
	ds_bpermute_b32 v2, v116, v245
	ds_bpermute_b32 v3, v116, v247
	ds_bpermute_b32 v4, v116, v242
	ds_bpermute_b32 v5, v116, v244
	ds_bpermute_b32 v6, v116, v246
	ds_bpermute_b32 v7, v116, v248
	s_waitcnt lgkmcnt(0)
	s_mov_b32 s88, 0x33333333
	s_mov_b32 s89, 0x33333333
	v_min_u32_e32 v104, v241, v0
	v_max_u32_e32 v105, v241, v0
	v_cndmask_b32_e64 v241, v105, v104, s[88:89]
	v_min_u32_e32 v106, v243, v1
	v_max_u32_e32 v107, v243, v1
	v_cndmask_b32_e64 v243, v107, v106, s[88:89]
	v_min_u32_e32 v104, v245, v2
	v_max_u32_e32 v105, v245, v2
	v_cndmask_b32_e64 v245, v105, v104, s[88:89]
	v_min_u32_e32 v106, v247, v3
	v_max_u32_e32 v107, v247, v3
	v_cndmask_b32_e64 v247, v107, v106, s[88:89]
	v_min_u32_e32 v104, v242, v4
	v_max_u32_e32 v105, v242, v4
	v_cndmask_b32_e64 v242, v105, v104, s[88:89]
	v_min_u32_e32 v106, v244, v5
	v_max_u32_e32 v107, v244, v5
	v_cndmask_b32_e64 v244, v107, v106, s[88:89]
	v_min_u32_e32 v104, v246, v6
	v_max_u32_e32 v105, v246, v6
	v_cndmask_b32_e64 v246, v105, v104, s[88:89]
	v_min_u32_e32 v106, v248, v7
	v_max_u32_e32 v107, v248, v7
	v_cndmask_b32_e64 v248, v107, v106, s[88:89]
	v_xor_b32_e32 v116, 4, v234
	ds_bpermute_b32 v0, v116, v241
	ds_bpermute_b32 v1, v116, v243
	ds_bpermute_b32 v2, v116, v245
	ds_bpermute_b32 v3, v116, v247
	ds_bpermute_b32 v4, v116, v242
	ds_bpermute_b32 v5, v116, v244
	ds_bpermute_b32 v6, v116, v246
	ds_bpermute_b32 v7, v116, v248
	s_waitcnt lgkmcnt(0)
	s_mov_b32 s88, 0x55555555
	s_mov_b32 s89, 0x55555555
	v_min_u32_e32 v104, v241, v0
	v_max_u32_e32 v105, v241, v0
	v_cndmask_b32_e64 v241, v105, v104, s[88:89]
	v_min_u32_e32 v106, v243, v1
	v_max_u32_e32 v107, v243, v1
	v_cndmask_b32_e64 v243, v107, v106, s[88:89]
	v_min_u32_e32 v104, v245, v2
	v_max_u32_e32 v105, v245, v2
	v_cndmask_b32_e64 v245, v105, v104, s[88:89]
	v_min_u32_e32 v106, v247, v3
	v_max_u32_e32 v107, v247, v3
	v_cndmask_b32_e64 v247, v107, v106, s[88:89]
	v_min_u32_e32 v104, v242, v4
	v_max_u32_e32 v105, v242, v4
	v_cndmask_b32_e64 v242, v105, v104, s[88:89]
	v_min_u32_e32 v106, v244, v5
	v_max_u32_e32 v107, v244, v5
	v_cndmask_b32_e64 v244, v107, v106, s[88:89]
	v_min_u32_e32 v104, v246, v6
	v_max_u32_e32 v105, v246, v6
	v_cndmask_b32_e64 v246, v105, v104, s[88:89]
	v_min_u32_e32 v106, v248, v7
	v_max_u32_e32 v107, v248, v7
	v_cndmask_b32_e64 v248, v107, v106, s[88:89]
	v_mov_b32_e32 v117, 0
	s_lshl_b32 s98, s2, 11
	s_add_u32 s98, s98, s101
	v_add_u32_e32 v116, s98, v234
	ds_write_b32 v116, v241 offset:0
	ds_write_b32 v116, v242 offset:256
	ds_write_b32 v116, v243 offset:512
	ds_write_b32 v116, v244 offset:768
	ds_write_b32 v116, v245 offset:1024
	ds_write_b32 v116, v246 offset:1280
	ds_write_b32 v116, v247 offset:1536
	ds_write_b32 v116, v248 offset:1792
	v_add_u32_e32 v118, 0x10000, v116
	ds_write_b32 v118, v117 offset:0
	ds_write_b32 v118, v117 offset:256
	ds_write_b32 v118, v117 offset:512
	ds_write_b32 v118, v117 offset:768
	ds_write_b32 v118, v117 offset:1024
	ds_write_b32 v118, v117 offset:1280
	ds_write_b32 v118, v117 offset:1536
	ds_write_b32 v118, v117 offset:1792
	s_add_u32 s2, s2, 1
	s_cmp_lt_u32 s2, 4
	s_cbranch_scc1 .Lpg1_p0
	s_waitcnt lgkmcnt(0)
	v_lshrrev_b32_e32 v248, 3, v233
	v_readfirstlane_b32 s80, v126
	v_readfirstlane_b32 s81, v127
	s_nop 4
	s_mov_b32 s90, 0xffffff80
	s_mov_b32 s100, 0
	s_mov_b32 s98, 0
	s_mov_b32 s99, 0
	v_readfirstlane_b32 s82, v122
	v_readfirstlane_b32 s83, v123
	s_nop 4
	s_add_u32 vcc_lo, s3, s98
	s_lshl_b32 vcc_lo, vcc_lo, 11
	s_lshl_b32 vcc_hi, s99, 8
	s_add_u32 vcc_lo, vcc_lo, vcc_hi
	v_add_u32_e32 v119, vcc_lo, v236
	global_load_dwordx4 v[80:83], v119, s[82:83]
	global_load_dwordx4 v[84:87], v119, s[82:83] offset:16
	s_lshl_b32 vcc_lo, s98, 9
	s_add_u32 vcc_lo, vcc_lo, s101
	v_add_u32_e32 v116, vcc_lo, v234
	ds_read_b32 v134, v116
	ds_read_b32 v135, v116 offset:256
	s_lshl_b32 vcc_lo, s99, 21
	s_add_u32 s84, s80, vcc_lo
	s_addc_u32 s85, s81, 0
	v_mov_b32_e32 v240, v235
	s_waitcnt lgkmcnt(0)
	ds_bpermute_b32 v142, v249, v134
	ds_bpermute_b32 v143, v250, v134
	s_waitcnt lgkmcnt(0)
	v_and_or_b32 v142, v142, s90, v240
	v_and_or_b32 v143, v143, s90, v240
	global_load_dwordx4 v[0:3], v142, s[84:85]
	global_load_dwordx4 v[4:7], v143, s[84:85]
	ds_bpermute_b32 v142, v251, v134
	ds_bpermute_b32 v143, v252, v134
	s_waitcnt lgkmcnt(0)
	v_and_or_b32 v142, v142, s90, v240
	v_and_or_b32 v143, v143, s90, v240
	global_load_dwordx4 v[8:11], v142, s[84:85]
	global_load_dwordx4 v[12:15], v143, s[84:85]
	ds_bpermute_b32 v142, v253, v134
	ds_bpermute_b32 v143, v254, v134
	s_waitcnt lgkmcnt(0)
	v_and_or_b32 v142, v142, s90, v240
	v_and_or_b32 v143, v143, s90, v240
	global_load_dwordx4 v[16:19], v142, s[84:85]
	global_load_dwordx4 v[20:23], v143, s[84:85]
	ds_bpermute_b32 v142, v255, v134
	ds_bpermute_b32 v143, v153, v134
	s_waitcnt lgkmcnt(0)
	v_and_or_b32 v142, v142, s90, v240
	v_and_or_b32 v143, v143, s90, v240
	global_load_dwordx4 v[24:27], v142, s[84:85]
	global_load_dwordx4 v[28:31], v143, s[84:85]
	ds_bpermute_b32 v142, v249, v135
	ds_bpermute_b32 v143, v250, v135
	s_waitcnt lgkmcnt(0)
	v_and_or_b32 v142, v142, s90, v240
	v_and_or_b32 v143, v143, s90, v240
	global_load_dwordx4 v[32:35], v142, s[84:85]
	global_load_dwordx4 v[36:39], v143, s[84:85]
	ds_bpermute_b32 v142, v251, v135
	ds_bpermute_b32 v143, v252, v135
	s_waitcnt lgkmcnt(0)
	v_and_or_b32 v142, v142, s90, v240
	v_and_or_b32 v143, v143, s90, v240
	global_load_dwordx4 v[40:43], v142, s[84:85]
	global_load_dwordx4 v[44:47], v143, s[84:85]
	ds_bpermute_b32 v142, v253, v135
	ds_bpermute_b32 v143, v254, v135
	s_waitcnt lgkmcnt(0)
	v_and_or_b32 v142, v142, s90, v240
	v_and_or_b32 v143, v143, s90, v240
	global_load_dwordx4 v[48:51], v142, s[84:85]
	global_load_dwordx4 v[52:55], v143, s[84:85]
	ds_bpermute_b32 v142, v255, v135
	ds_bpermute_b32 v143, v153, v135
	s_waitcnt lgkmcnt(0)
	v_and_or_b32 v142, v142, s90, v240
	v_and_or_b32 v143, v143, s90, v240
	global_load_dwordx4 v[56:59], v142, s[84:85]
	global_load_dwordx4 v[60:63], v143, s[84:85]
	s_mov_b32 s92, 1
	s_lshl_b32 vcc_lo, s92, 9
	s_add_u32 vcc_lo, vcc_lo, s101
	v_add_u32_e32 v116, vcc_lo, v234
	ds_read_b32 v134, v116
	ds_read_b32 v135, v116 offset:256
.Lpg1_uloop:
	s_and_b32 s98, s100, 15
	s_lshr_b32 s99, s100, 4
	s_add_u32 s92, s100, 1
	s_min_u32 s92, s92, 127
	s_lshr_b32 s93, s92, 4
	s_and_b32 s92, s92, 15
	s_waitcnt vmcnt(16)
	v_lshlrev_b32_e32 v64, 16, v80
	v_and_b32_e32 v65, 0xffff0000, v80
	v_lshlrev_b32_e32 v66, 16, v81
	v_and_b32_e32 v67, 0xffff0000, v81
	v_lshlrev_b32_e32 v68, 16, v82
	v_and_b32_e32 v69, 0xffff0000, v82
	v_lshlrev_b32_e32 v70, 16, v83
	v_and_b32_e32 v71, 0xffff0000, v83
	v_lshlrev_b32_e32 v72, 16, v84
	v_and_b32_e32 v73, 0xffff0000, v84
	v_lshlrev_b32_e32 v74, 16, v85
	v_and_b32_e32 v75, 0xffff0000, v85
	v_lshlrev_b32_e32 v76, 16, v86
	v_and_b32_e32 v77, 0xffff0000, v86
	v_lshlrev_b32_e32 v78, 16, v87
	v_and_b32_e32 v79, 0xffff0000, v87
	v_readfirstlane_b32 s82, v122
	v_readfirstlane_b32 s83, v123
	s_nop 4
	s_add_u32 vcc_lo, s3, s92
	s_lshl_b32 vcc_lo, vcc_lo, 11
	s_lshl_b32 vcc_hi, s93, 8
	s_add_u32 vcc_lo, vcc_lo, vcc_hi
	v_add_u32_e32 v119, vcc_lo, v236
	global_load_dwordx4 v[80:83], v119, s[82:83]
	global_load_dwordx4 v[84:87], v119, s[82:83] offset:16
	s_lshl_b32 vcc_lo, s93, 21
	s_add_u32 s84, s80, vcc_lo
	s_addc_u32 s85, s81, 0
	v_mov_b32_e32 v240, v235
	s_waitcnt lgkmcnt(0)
	ds_bpermute_b32 v142, v249, v134
	ds_bpermute_b32 v143, v250, v134
	s_waitcnt vmcnt(16)
	v_cvt_pk_f32_fp8_e32 v[104:105], v0
	v_cvt_pk_f32_fp8_e32 v[108:109], v4
	v_cvt_pk_f32_fp8_sdwa v[106:107], v0 src0_sel:WORD_1
	v_cvt_pk_f32_fp8_sdwa v[110:111], v4 src0_sel:WORD_1
	v_pk_mul_f32 v[112:113], v[64:65], v[104:105]
	v_pk_mul_f32 v[114:115], v[64:65], v[108:109]
	v_pk_fma_f32 v[112:113], v[66:67], v[106:107], v[112:113]
	v_pk_fma_f32 v[114:115], v[66:67], v[110:111], v[114:115]
	v_cvt_pk_f32_fp8_e32 v[104:105], v1
	v_cvt_pk_f32_fp8_e32 v[108:109], v5
	v_cvt_pk_f32_fp8_sdwa v[106:107], v1 src0_sel:WORD_1
	v_cvt_pk_f32_fp8_sdwa v[110:111], v5 src0_sel:WORD_1
	v_pk_fma_f32 v[112:113], v[68:69], v[104:105], v[112:113]
	v_pk_fma_f32 v[114:115], v[68:69], v[108:109], v[114:115]
	v_pk_fma_f32 v[112:113], v[70:71], v[106:107], v[112:113]
	v_pk_fma_f32 v[114:115], v[70:71], v[110:111], v[114:115]
	v_cvt_pk_f32_fp8_e32 v[104:105], v2
	v_cvt_pk_f32_fp8_e32 v[108:109], v6
	v_cvt_pk_f32_fp8_sdwa v[106:107], v2 src0_sel:WORD_1
	v_cvt_pk_f32_fp8_sdwa v[110:111], v6 src0_sel:WORD_1
	v_pk_fma_f32 v[112:113], v[72:73], v[104:105], v[112:113]
	v_pk_fma_f32 v[114:115], v[72:73], v[108:109], v[114:115]
	v_pk_fma_f32 v[112:113], v[74:75], v[106:107], v[112:113]
	v_pk_fma_f32 v[114:115], v[74:75], v[110:111], v[114:115]
	v_cvt_pk_f32_fp8_e32 v[104:105], v3
	v_cvt_pk_f32_fp8_e32 v[108:109], v7
	v_cvt_pk_f32_fp8_sdwa v[106:107], v3 src0_sel:WORD_1
	v_cvt_pk_f32_fp8_sdwa v[110:111], v7 src0_sel:WORD_1
	v_pk_fma_f32 v[112:113], v[76:77], v[104:105], v[112:113]
	v_pk_fma_f32 v[114:115], v[76:77], v[108:109], v[114:115]
	s_waitcnt lgkmcnt(0)
	v_and_or_b32 v142, v142, s90, v240
	v_and_or_b32 v143, v143, s90, v240
	global_load_dwordx4 v[0:3], v142, s[84:85]
	global_load_dwordx4 v[4:7], v143, s[84:85]
	v_pk_fma_f32 v[112:113], v[78:79], v[106:107], v[112:113]
	v_pk_fma_f32 v[114:115], v[78:79], v[110:111], v[114:115]
	v_add_f32_e32 v88, v112, v113
	v_add_f32_e32 v89, v114, v115
	ds_bpermute_b32 v142, v251, v134
	ds_bpermute_b32 v143, v252, v134
	s_waitcnt vmcnt(16)
	v_cvt_pk_f32_fp8_e32 v[104:105], v8
	v_cvt_pk_f32_fp8_e32 v[108:109], v12
	v_cvt_pk_f32_fp8_sdwa v[106:107], v8 src0_sel:WORD_1
	v_cvt_pk_f32_fp8_sdwa v[110:111], v12 src0_sel:WORD_1
	v_pk_mul_f32 v[112:113], v[64:65], v[104:105]
	v_pk_mul_f32 v[114:115], v[64:65], v[108:109]
	v_pk_fma_f32 v[112:113], v[66:67], v[106:107], v[112:113]
	v_pk_fma_f32 v[114:115], v[66:67], v[110:111], v[114:115]
	v_cvt_pk_f32_fp8_e32 v[104:105], v9
	v_cvt_pk_f32_fp8_e32 v[108:109], v13
	v_cvt_pk_f32_fp8_sdwa v[106:107], v9 src0_sel:WORD_1
	v_cvt_pk_f32_fp8_sdwa v[110:111], v13 src0_sel:WORD_1
	v_pk_fma_f32 v[112:113], v[68:69], v[104:105], v[112:113]
	v_pk_fma_f32 v[114:115], v[68:69], v[108:109], v[114:115]
	v_pk_fma_f32 v[112:113], v[70:71], v[106:107], v[112:113]
	v_pk_fma_f32 v[114:115], v[70:71], v[110:111], v[114:115]
	v_cvt_pk_f32_fp8_e32 v[104:105], v10
	v_cvt_pk_f32_fp8_e32 v[108:109], v14
	v_cvt_pk_f32_fp8_sdwa v[106:107], v10 src0_sel:WORD_1
	v_cvt_pk_f32_fp8_sdwa v[110:111], v14 src0_sel:WORD_1
	v_pk_fma_f32 v[112:113], v[72:73], v[104:105], v[112:113]
	v_pk_fma_f32 v[114:115], v[72:73], v[108:109], v[114:115]
	v_pk_fma_f32 v[112:113], v[74:75], v[106:107], v[112:113]
	v_pk_fma_f32 v[114:115], v[74:75], v[110:111], v[114:115]
	v_cvt_pk_f32_fp8_e32 v[104:105], v11
	v_cvt_pk_f32_fp8_e32 v[108:109], v15
	v_cvt_pk_f32_fp8_sdwa v[106:107], v11 src0_sel:WORD_1
	v_cvt_pk_f32_fp8_sdwa v[110:111], v15 src0_sel:WORD_1
	v_pk_fma_f32 v[112:113], v[76:77], v[104:105], v[112:113]
	v_pk_fma_f32 v[114:115], v[76:77], v[108:109], v[114:115]
	s_waitcnt lgkmcnt(0)
	v_and_or_b32 v142, v142, s90, v240
	v_and_or_b32 v143, v143, s90, v240
	global_load_dwordx4 v[8:11], v142, s[84:85]
	global_load_dwordx4 v[12:15], v143, s[84:85]
	v_pk_fma_f32 v[112:113], v[78:79], v[106:107], v[112:113]
	v_pk_fma_f32 v[114:115], v[78:79], v[110:111], v[114:115]
	v_add_f32_e32 v90, v112, v113
	v_add_f32_e32 v91, v114, v115
	ds_bpermute_b32 v142, v253, v134
	ds_bpermute_b32 v143, v254, v134
	s_waitcnt vmcnt(16)
	v_cvt_pk_f32_fp8_e32 v[104:105], v16
	v_cvt_pk_f32_fp8_e32 v[108:109], v20
	v_cvt_pk_f32_fp8_sdwa v[106:107], v16 src0_sel:WORD_1
	v_cvt_pk_f32_fp8_sdwa v[110:111], v20 src0_sel:WORD_1
	v_pk_mul_f32 v[112:113], v[64:65], v[104:105]
	v_pk_mul_f32 v[114:115], v[64:65], v[108:109]
	v_pk_fma_f32 v[112:113], v[66:67], v[106:107], v[112:113]
	v_pk_fma_f32 v[114:115], v[66:67], v[110:111], v[114:115]
	v_cvt_pk_f32_fp8_e32 v[104:105], v17
	v_cvt_pk_f32_fp8_e32 v[108:109], v21
	v_cvt_pk_f32_fp8_sdwa v[106:107], v17 src0_sel:WORD_1
	v_cvt_pk_f32_fp8_sdwa v[110:111], v21 src0_sel:WORD_1
	v_pk_fma_f32 v[112:113], v[68:69], v[104:105], v[112:113]
	v_pk_fma_f32 v[114:115], v[68:69], v[108:109], v[114:115]
	v_pk_fma_f32 v[112:113], v[70:71], v[106:107], v[112:113]
	v_pk_fma_f32 v[114:115], v[70:71], v[110:111], v[114:115]
	v_cvt_pk_f32_fp8_e32 v[104:105], v18
	v_cvt_pk_f32_fp8_e32 v[108:109], v22
	v_cvt_pk_f32_fp8_sdwa v[106:107], v18 src0_sel:WORD_1
	v_cvt_pk_f32_fp8_sdwa v[110:111], v22 src0_sel:WORD_1
	v_pk_fma_f32 v[112:113], v[72:73], v[104:105], v[112:113]
	v_pk_fma_f32 v[114:115], v[72:73], v[108:109], v[114:115]
	v_pk_fma_f32 v[112:113], v[74:75], v[106:107], v[112:113]
	v_pk_fma_f32 v[114:115], v[74:75], v[110:111], v[114:115]
	v_cvt_pk_f32_fp8_e32 v[104:105], v19
	v_cvt_pk_f32_fp8_e32 v[108:109], v23
	v_cvt_pk_f32_fp8_sdwa v[106:107], v19 src0_sel:WORD_1
	v_cvt_pk_f32_fp8_sdwa v[110:111], v23 src0_sel:WORD_1
	v_pk_fma_f32 v[112:113], v[76:77], v[104:105], v[112:113]
	v_pk_fma_f32 v[114:115], v[76:77], v[108:109], v[114:115]
	s_waitcnt lgkmcnt(0)
	v_and_or_b32 v142, v142, s90, v240
	v_and_or_b32 v143, v143, s90, v240
	global_load_dwordx4 v[16:19], v142, s[84:85]
	global_load_dwordx4 v[20:23], v143, s[84:85]
	v_pk_fma_f32 v[112:113], v[78:79], v[106:107], v[112:113]
	v_pk_fma_f32 v[114:115], v[78:79], v[110:111], v[114:115]
	v_add_f32_e32 v92, v112, v113
	v_add_f32_e32 v93, v114, v115
	ds_bpermute_b32 v142, v255, v134
	ds_bpermute_b32 v143, v153, v134
	s_waitcnt vmcnt(16)
	v_cvt_pk_f32_fp8_e32 v[104:105], v24
	v_cvt_pk_f32_fp8_e32 v[108:109], v28
	v_cvt_pk_f32_fp8_sdwa v[106:107], v24 src0_sel:WORD_1
	v_cvt_pk_f32_fp8_sdwa v[110:111], v28 src0_sel:WORD_1
	v_pk_mul_f32 v[112:113], v[64:65], v[104:105]
	v_pk_mul_f32 v[114:115], v[64:65], v[108:109]
	v_pk_fma_f32 v[112:113], v[66:67], v[106:107], v[112:113]
	v_pk_fma_f32 v[114:115], v[66:67], v[110:111], v[114:115]
	v_cvt_pk_f32_fp8_e32 v[104:105], v25
	v_cvt_pk_f32_fp8_e32 v[108:109], v29
	v_cvt_pk_f32_fp8_sdwa v[106:107], v25 src0_sel:WORD_1
	v_cvt_pk_f32_fp8_sdwa v[110:111], v29 src0_sel:WORD_1
	v_pk_fma_f32 v[112:113], v[68:69], v[104:105], v[112:113]
	v_pk_fma_f32 v[114:115], v[68:69], v[108:109], v[114:115]
	v_pk_fma_f32 v[112:113], v[70:71], v[106:107], v[112:113]
	v_pk_fma_f32 v[114:115], v[70:71], v[110:111], v[114:115]
	v_cvt_pk_f32_fp8_e32 v[104:105], v26
	v_cvt_pk_f32_fp8_e32 v[108:109], v30
	v_cvt_pk_f32_fp8_sdwa v[106:107], v26 src0_sel:WORD_1
	v_cvt_pk_f32_fp8_sdwa v[110:111], v30 src0_sel:WORD_1
	v_pk_fma_f32 v[112:113], v[72:73], v[104:105], v[112:113]
	v_pk_fma_f32 v[114:115], v[72:73], v[108:109], v[114:115]
	v_pk_fma_f32 v[112:113], v[74:75], v[106:107], v[112:113]
	v_pk_fma_f32 v[114:115], v[74:75], v[110:111], v[114:115]
	v_cvt_pk_f32_fp8_e32 v[104:105], v27
	v_cvt_pk_f32_fp8_e32 v[108:109], v31
	v_cvt_pk_f32_fp8_sdwa v[106:107], v27 src0_sel:WORD_1
	v_cvt_pk_f32_fp8_sdwa v[110:111], v31 src0_sel:WORD_1
	v_pk_fma_f32 v[112:113], v[76:77], v[104:105], v[112:113]
	v_pk_fma_f32 v[114:115], v[76:77], v[108:109], v[114:115]
	s_waitcnt lgkmcnt(0)
	v_and_or_b32 v142, v142, s90, v240
	v_and_or_b32 v143, v143, s90, v240
	global_load_dwordx4 v[24:27], v142, s[84:85]
	global_load_dwordx4 v[28:31], v143, s[84:85]
	v_pk_fma_f32 v[112:113], v[78:79], v[106:107], v[112:113]
	v_pk_fma_f32 v[114:115], v[78:79], v[110:111], v[114:115]
	v_add_f32_e32 v94, v112, v113
	v_add_f32_e32 v95, v114, v115
	ds_bpermute_b32 v142, v249, v135
	ds_bpermute_b32 v143, v250, v135
	s_waitcnt vmcnt(16)
	v_cvt_pk_f32_fp8_e32 v[104:105], v32
	v_cvt_pk_f32_fp8_e32 v[108:109], v36
	v_cvt_pk_f32_fp8_sdwa v[106:107], v32 src0_sel:WORD_1
	v_cvt_pk_f32_fp8_sdwa v[110:111], v36 src0_sel:WORD_1
	v_pk_mul_f32 v[112:113], v[64:65], v[104:105]
	v_pk_mul_f32 v[114:115], v[64:65], v[108:109]
	v_pk_fma_f32 v[112:113], v[66:67], v[106:107], v[112:113]
	v_pk_fma_f32 v[114:115], v[66:67], v[110:111], v[114:115]
	v_cvt_pk_f32_fp8_e32 v[104:105], v33
	v_cvt_pk_f32_fp8_e32 v[108:109], v37
	v_cvt_pk_f32_fp8_sdwa v[106:107], v33 src0_sel:WORD_1
	v_cvt_pk_f32_fp8_sdwa v[110:111], v37 src0_sel:WORD_1
	v_pk_fma_f32 v[112:113], v[68:69], v[104:105], v[112:113]
	v_pk_fma_f32 v[114:115], v[68:69], v[108:109], v[114:115]
	v_pk_fma_f32 v[112:113], v[70:71], v[106:107], v[112:113]
	v_pk_fma_f32 v[114:115], v[70:71], v[110:111], v[114:115]
	v_cvt_pk_f32_fp8_e32 v[104:105], v34
	v_cvt_pk_f32_fp8_e32 v[108:109], v38
	v_cvt_pk_f32_fp8_sdwa v[106:107], v34 src0_sel:WORD_1
	v_cvt_pk_f32_fp8_sdwa v[110:111], v38 src0_sel:WORD_1
	v_pk_fma_f32 v[112:113], v[72:73], v[104:105], v[112:113]
	v_pk_fma_f32 v[114:115], v[72:73], v[108:109], v[114:115]
	v_pk_fma_f32 v[112:113], v[74:75], v[106:107], v[112:113]
	v_pk_fma_f32 v[114:115], v[74:75], v[110:111], v[114:115]
	v_cvt_pk_f32_fp8_e32 v[104:105], v35
	v_cvt_pk_f32_fp8_e32 v[108:109], v39
	v_cvt_pk_f32_fp8_sdwa v[106:107], v35 src0_sel:WORD_1
	v_cvt_pk_f32_fp8_sdwa v[110:111], v39 src0_sel:WORD_1
	v_pk_fma_f32 v[112:113], v[76:77], v[104:105], v[112:113]
	v_pk_fma_f32 v[114:115], v[76:77], v[108:109], v[114:115]
	s_waitcnt lgkmcnt(0)
	v_and_or_b32 v142, v142, s90, v240
	v_and_or_b32 v143, v143, s90, v240
	global_load_dwordx4 v[32:35], v142, s[84:85]
	global_load_dwordx4 v[36:39], v143, s[84:85]
	v_pk_fma_f32 v[112:113], v[78:79], v[106:107], v[112:113]
	v_pk_fma_f32 v[114:115], v[78:79], v[110:111], v[114:115]
	v_add_f32_e32 v96, v112, v113
	v_add_f32_e32 v97, v114, v115
	ds_bpermute_b32 v142, v251, v135
	ds_bpermute_b32 v143, v252, v135
	s_waitcnt vmcnt(16)
	v_cvt_pk_f32_fp8_e32 v[104:105], v40
	v_cvt_pk_f32_fp8_e32 v[108:109], v44
	v_cvt_pk_f32_fp8_sdwa v[106:107], v40 src0_sel:WORD_1
	v_cvt_pk_f32_fp8_sdwa v[110:111], v44 src0_sel:WORD_1
	v_pk_mul_f32 v[112:113], v[64:65], v[104:105]
	v_pk_mul_f32 v[114:115], v[64:65], v[108:109]
	v_pk_fma_f32 v[112:113], v[66:67], v[106:107], v[112:113]
	v_pk_fma_f32 v[114:115], v[66:67], v[110:111], v[114:115]
	v_cvt_pk_f32_fp8_e32 v[104:105], v41
	v_cvt_pk_f32_fp8_e32 v[108:109], v45
	v_cvt_pk_f32_fp8_sdwa v[106:107], v41 src0_sel:WORD_1
	v_cvt_pk_f32_fp8_sdwa v[110:111], v45 src0_sel:WORD_1
	v_pk_fma_f32 v[112:113], v[68:69], v[104:105], v[112:113]
	v_pk_fma_f32 v[114:115], v[68:69], v[108:109], v[114:115]
	v_pk_fma_f32 v[112:113], v[70:71], v[106:107], v[112:113]
	v_pk_fma_f32 v[114:115], v[70:71], v[110:111], v[114:115]
	v_cvt_pk_f32_fp8_e32 v[104:105], v42
	v_cvt_pk_f32_fp8_e32 v[108:109], v46
	v_cvt_pk_f32_fp8_sdwa v[106:107], v42 src0_sel:WORD_1
	v_cvt_pk_f32_fp8_sdwa v[110:111], v46 src0_sel:WORD_1
	v_pk_fma_f32 v[112:113], v[72:73], v[104:105], v[112:113]
	v_pk_fma_f32 v[114:115], v[72:73], v[108:109], v[114:115]
	v_pk_fma_f32 v[112:113], v[74:75], v[106:107], v[112:113]
	v_pk_fma_f32 v[114:115], v[74:75], v[110:111], v[114:115]
	v_cvt_pk_f32_fp8_e32 v[104:105], v43
	v_cvt_pk_f32_fp8_e32 v[108:109], v47
	v_cvt_pk_f32_fp8_sdwa v[106:107], v43 src0_sel:WORD_1
	v_cvt_pk_f32_fp8_sdwa v[110:111], v47 src0_sel:WORD_1
	v_pk_fma_f32 v[112:113], v[76:77], v[104:105], v[112:113]
	v_pk_fma_f32 v[114:115], v[76:77], v[108:109], v[114:115]
	s_waitcnt lgkmcnt(0)
	v_and_or_b32 v142, v142, s90, v240
	v_and_or_b32 v143, v143, s90, v240
	global_load_dwordx4 v[40:43], v142, s[84:85]
	global_load_dwordx4 v[44:47], v143, s[84:85]
	v_pk_fma_f32 v[112:113], v[78:79], v[106:107], v[112:113]
	v_pk_fma_f32 v[114:115], v[78:79], v[110:111], v[114:115]
	v_add_f32_e32 v98, v112, v113
	v_add_f32_e32 v99, v114, v115
	ds_bpermute_b32 v142, v253, v135
	ds_bpermute_b32 v143, v254, v135
	s_waitcnt vmcnt(16)
	v_cvt_pk_f32_fp8_e32 v[104:105], v48
	v_cvt_pk_f32_fp8_e32 v[108:109], v52
	v_cvt_pk_f32_fp8_sdwa v[106:107], v48 src0_sel:WORD_1
	v_cvt_pk_f32_fp8_sdwa v[110:111], v52 src0_sel:WORD_1
	v_pk_mul_f32 v[112:113], v[64:65], v[104:105]
	v_pk_mul_f32 v[114:115], v[64:65], v[108:109]
	v_pk_fma_f32 v[112:113], v[66:67], v[106:107], v[112:113]
	v_pk_fma_f32 v[114:115], v[66:67], v[110:111], v[114:115]
	v_cvt_pk_f32_fp8_e32 v[104:105], v49
	v_cvt_pk_f32_fp8_e32 v[108:109], v53
	v_cvt_pk_f32_fp8_sdwa v[106:107], v49 src0_sel:WORD_1
	v_cvt_pk_f32_fp8_sdwa v[110:111], v53 src0_sel:WORD_1
	v_pk_fma_f32 v[112:113], v[68:69], v[104:105], v[112:113]
	v_pk_fma_f32 v[114:115], v[68:69], v[108:109], v[114:115]
	v_pk_fma_f32 v[112:113], v[70:71], v[106:107], v[112:113]
	v_pk_fma_f32 v[114:115], v[70:71], v[110:111], v[114:115]
	v_cvt_pk_f32_fp8_e32 v[104:105], v50
	v_cvt_pk_f32_fp8_e32 v[108:109], v54
	v_cvt_pk_f32_fp8_sdwa v[106:107], v50 src0_sel:WORD_1
	v_cvt_pk_f32_fp8_sdwa v[110:111], v54 src0_sel:WORD_1
	v_pk_fma_f32 v[112:113], v[72:73], v[104:105], v[112:113]
	v_pk_fma_f32 v[114:115], v[72:73], v[108:109], v[114:115]
	v_pk_fma_f32 v[112:113], v[74:75], v[106:107], v[112:113]
	v_pk_fma_f32 v[114:115], v[74:75], v[110:111], v[114:115]
	v_cvt_pk_f32_fp8_e32 v[104:105], v51
	v_cvt_pk_f32_fp8_e32 v[108:109], v55
	v_cvt_pk_f32_fp8_sdwa v[106:107], v51 src0_sel:WORD_1
	v_cvt_pk_f32_fp8_sdwa v[110:111], v55 src0_sel:WORD_1
	v_pk_fma_f32 v[112:113], v[76:77], v[104:105], v[112:113]
	v_pk_fma_f32 v[114:115], v[76:77], v[108:109], v[114:115]
	s_waitcnt lgkmcnt(0)
	v_and_or_b32 v142, v142, s90, v240
	v_and_or_b32 v143, v143, s90, v240
	global_load_dwordx4 v[48:51], v142, s[84:85]
	global_load_dwordx4 v[52:55], v143, s[84:85]
	v_pk_fma_f32 v[112:113], v[78:79], v[106:107], v[112:113]
	v_pk_fma_f32 v[114:115], v[78:79], v[110:111], v[114:115]
	v_add_f32_e32 v100, v112, v113
	v_add_f32_e32 v101, v114, v115
	ds_bpermute_b32 v142, v255, v135
	ds_bpermute_b32 v143, v153, v135
	s_waitcnt vmcnt(16)
	v_cvt_pk_f32_fp8_e32 v[104:105], v56
	v_cvt_pk_f32_fp8_e32 v[108:109], v60
	v_cvt_pk_f32_fp8_sdwa v[106:107], v56 src0_sel:WORD_1
	v_cvt_pk_f32_fp8_sdwa v[110:111], v60 src0_sel:WORD_1
	v_pk_mul_f32 v[112:113], v[64:65], v[104:105]
	v_pk_mul_f32 v[114:115], v[64:65], v[108:109]
	v_pk_fma_f32 v[112:113], v[66:67], v[106:107], v[112:113]
	v_pk_fma_f32 v[114:115], v[66:67], v[110:111], v[114:115]
	v_cvt_pk_f32_fp8_e32 v[104:105], v57
	v_cvt_pk_f32_fp8_e32 v[108:109], v61
	v_cvt_pk_f32_fp8_sdwa v[106:107], v57 src0_sel:WORD_1
	v_cvt_pk_f32_fp8_sdwa v[110:111], v61 src0_sel:WORD_1
	v_pk_fma_f32 v[112:113], v[68:69], v[104:105], v[112:113]
	v_pk_fma_f32 v[114:115], v[68:69], v[108:109], v[114:115]
	v_pk_fma_f32 v[112:113], v[70:71], v[106:107], v[112:113]
	v_pk_fma_f32 v[114:115], v[70:71], v[110:111], v[114:115]
	v_cvt_pk_f32_fp8_e32 v[104:105], v58
	v_cvt_pk_f32_fp8_e32 v[108:109], v62
	v_cvt_pk_f32_fp8_sdwa v[106:107], v58 src0_sel:WORD_1
	v_cvt_pk_f32_fp8_sdwa v[110:111], v62 src0_sel:WORD_1
	v_pk_fma_f32 v[112:113], v[72:73], v[104:105], v[112:113]
	v_pk_fma_f32 v[114:115], v[72:73], v[108:109], v[114:115]
	v_pk_fma_f32 v[112:113], v[74:75], v[106:107], v[112:113]
	v_pk_fma_f32 v[114:115], v[74:75], v[110:111], v[114:115]
	v_cvt_pk_f32_fp8_e32 v[104:105], v59
	v_cvt_pk_f32_fp8_e32 v[108:109], v63
	v_cvt_pk_f32_fp8_sdwa v[106:107], v59 src0_sel:WORD_1
	v_cvt_pk_f32_fp8_sdwa v[110:111], v63 src0_sel:WORD_1
	v_pk_fma_f32 v[112:113], v[76:77], v[104:105], v[112:113]
	v_pk_fma_f32 v[114:115], v[76:77], v[108:109], v[114:115]
	s_waitcnt lgkmcnt(0)
	v_and_or_b32 v142, v142, s90, v240
	v_and_or_b32 v143, v143, s90, v240
	global_load_dwordx4 v[56:59], v142, s[84:85]
	global_load_dwordx4 v[60:63], v143, s[84:85]
	v_pk_fma_f32 v[112:113], v[78:79], v[106:107], v[112:113]
	v_pk_fma_f32 v[114:115], v[78:79], v[110:111], v[114:115]
	v_add_f32_e32 v102, v112, v113
	v_add_f32_e32 v103, v114, v115
	s_add_u32 s92, s100, 2
	s_min_u32 s92, s92, 127
	s_and_b32 s92, s92, 15
	s_lshl_b32 vcc_lo, s92, 9
	s_add_u32 vcc_lo, vcc_lo, s101
	v_add_u32_e32 v116, vcc_lo, v234
	ds_read_b32 v134, v116
	ds_read_b32 v135, v116 offset:256
	s_lshl_b32 vcc_lo, s98, 9
	s_add_u32 vcc_lo, vcc_lo, s101
	s_add_u32 vcc_lo, vcc_lo, 0x10000
	v_add_u32_e32 v117, vcc_lo, v234
	ds_read_b32 v136, v117
	ds_read_b32 v137, v117 offset:256
	s_mov_b32 s88, 0xf0f0f0f0
	s_mov_b32 s89, 0xf0f0f0f0
	v_cndmask_b32_e64 v144, v88, v92, s[88:89]
	v_cndmask_b32_e64 v92, v92, v88, s[88:89]
	v_cndmask_b32_e64 v145, v89, v93, s[88:89]
	v_cndmask_b32_e64 v93, v93, v89, s[88:89]
	v_cndmask_b32_e64 v146, v90, v94, s[88:89]
	v_cndmask_b32_e64 v94, v94, v90, s[88:89]
	v_cndmask_b32_e64 v147, v91, v95, s[88:89]
	v_cndmask_b32_e64 v95, v95, v91, s[88:89]
	v_add_f32_dpp v88, v92, v144 row_half_mirror row_mask:0xf bank_mask:0xf
	v_add_f32_dpp v89, v93, v145 row_half_mirror row_mask:0xf bank_mask:0xf
	v_add_f32_dpp v90, v94, v146 row_half_mirror row_mask:0xf bank_mask:0xf
	v_add_f32_dpp v91, v95, v147 row_half_mirror row_mask:0xf bank_mask:0xf
	v_cndmask_b32_e64 v144, v96, v100, s[88:89]
	v_cndmask_b32_e64 v100, v100, v96, s[88:89]
	v_cndmask_b32_e64 v145, v97, v101, s[88:89]
	v_cndmask_b32_e64 v101, v101, v97, s[88:89]
	v_cndmask_b32_e64 v146, v98, v102, s[88:89]
	v_cndmask_b32_e64 v102, v102, v98, s[88:89]
	v_cndmask_b32_e64 v147, v99, v103, s[88:89]
	v_cndmask_b32_e64 v103, v103, v99, s[88:89]
	v_add_f32_dpp v96, v100, v144 row_half_mirror row_mask:0xf bank_mask:0xf
	v_add_f32_dpp v97, v101, v145 row_half_mirror row_mask:0xf bank_mask:0xf
	v_add_f32_dpp v98, v102, v146 row_half_mirror row_mask:0xf bank_mask:0xf
	v_add_f32_dpp v99, v103, v147 row_half_mirror row_mask:0xf bank_mask:0xf
	s_mov_b32 s88, 0xcccccccc
	s_mov_b32 s89, 0xcccccccc
	v_cndmask_b32_e64 v144, v88, v90, s[88:89]
	v_cndmask_b32_e64 v90, v90, v88, s[88:89]
	v_cndmask_b32_e64 v145, v89, v91, s[88:89]
	v_cndmask_b32_e64 v91, v91, v89, s[88:89]
	v_cndmask_b32_e64 v146, v96, v98, s[88:89]
	v_cndmask_b32_e64 v98, v98, v96, s[88:89]
	v_cndmask_b32_e64 v147, v97, v99, s[88:89]
	v_cndmask_b32_e64 v99, v99, v97, s[88:89]
	v_add_f32_dpp v88, v90, v144 quad_perm:[2,3,0,1] row_mask:0xf bank_mask:0xf
	v_add_f32_dpp v89, v91, v145 quad_perm:[2,3,0,1] row_mask:0xf bank_mask:0xf
	v_add_f32_dpp v96, v98, v146 quad_perm:[2,3,0,1] row_mask:0xf bank_mask:0xf
	v_add_f32_dpp v97, v99, v147 quad_perm:[2,3,0,1] row_mask:0xf bank_mask:0xf
	s_mov_b32 s88, 0xaaaaaaaa
	s_mov_b32 s89, 0xaaaaaaaa
	v_cndmask_b32_e64 v144, v88, v89, s[88:89]
	v_cndmask_b32_e64 v89, v89, v88, s[88:89]
	v_cndmask_b32_e64 v145, v96, v97, s[88:89]
	v_cndmask_b32_e64 v97, v97, v96, s[88:89]
	s_nop 1
	v_add_f32_dpp v88, v89, v144 quad_perm:[1,0,3,2] row_mask:0xf bank_mask:0xf
	v_add_f32_dpp v96, v97, v145 quad_perm:[1,0,3,2] row_mask:0xf bank_mask:0xf
	s_nop 0
	ds_bpermute_b32 v144, v239, v88
	ds_bpermute_b32 v145, v239, v96
	s_waitcnt lgkmcnt(0)
	v_add_f32_e32 v136, v136, v144
	v_add_f32_e32 v137, v137, v145
	ds_write_b32 v117, v136
	ds_write_b32 v117, v137 offset:256
	s_add_u32 s100, s100, 1
	s_cmp_lt_u32 s100, 128
	s_cbranch_scc1 .Lpg1_uloop
	s_waitcnt vmcnt(0) lgkmcnt(0)
	s_mov_b32 s2, 0
.Lpg1_act:
	v_readlane_b32 s82, v232, 1
	v_readlane_b32 s83, v232, 2
	s_nop 4
	s_lshl_b32 s98, s2, 11
	s_add_u32 s98, s98, s101
	v_add_u32_e32 v116, s98, v234
	v_add_u32_e32 v117, 0x10000, v116
	ds_read_b32 v0, v116 offset:0
	ds_read_b32 v8, v117 offset:0
	ds_read_b32 v1, v116 offset:256
	ds_read_b32 v9, v117 offset:256
	ds_read_b32 v2, v116 offset:512
	ds_read_b32 v10, v117 offset:512
	ds_read_b32 v3, v116 offset:768
	ds_read_b32 v11, v117 offset:768
	ds_read_b32 v4, v116 offset:1024
	ds_read_b32 v12, v117 offset:1024
	ds_read_b32 v5, v116 offset:1280
	ds_read_b32 v13, v117 offset:1280
	ds_read_b32 v6, v116 offset:1536
	ds_read_b32 v14, v117 offset:1536
	ds_read_b32 v7, v116 offset:1792
	ds_read_b32 v15, v117 offset:1792
	s_waitcnt lgkmcnt(0)
	s_lshl_b32 s99, s2, 2
	s_add_u32 s99, s99, s33
	s_add_u32 s99, s99, 0
	s_lshl_b32 s99, s99, 9
	v_and_b32_e32 v0, 0x7f, v0
	v_lshl_add_u32 v0, v0, 2, s99
	global_load_dword v16, v0, s[82:83]
	v_and_b32_e32 v1, 0x7f, v1
	v_lshl_add_u32 v1, v1, 2, s99
	global_load_dword v17, v1, s[82:83]
	s_lshl_b32 s99, s2, 2
	s_add_u32 s99, s99, s33
	s_add_u32 s99, s99, 1
	s_lshl_b32 s99, s99, 9
	v_and_b32_e32 v2, 0x7f, v2
	v_lshl_add_u32 v2, v2, 2, s99
	global_load_dword v18, v2, s[82:83]
	v_and_b32_e32 v3, 0x7f, v3
	v_lshl_add_u32 v3, v3, 2, s99
	global_load_dword v19, v3, s[82:83]
	s_lshl_b32 s99, s2, 2
	s_add_u32 s99, s99, s33
	s_add_u32 s99, s99, 2
	s_lshl_b32 s99, s99, 9
	v_and_b32_e32 v4, 0x7f, v4
	v_lshl_add_u32 v4, v4, 2, s99
	global_load_dword v20, v4, s[82:83]
	v_and_b32_e32 v5, 0x7f, v5
	v_lshl_add_u32 v5, v5, 2, s99
	global_load_dword v21, v5, s[82:83]
	s_lshl_b32 s99, s2, 2
	s_add_u32 s99, s99, s33
	s_add_u32 s99, s99, 3
	s_lshl_b32 s99, s99, 9
	v_and_b32_e32 v6, 0x7f, v6
	v_lshl_add_u32 v6, v6, 2, s99
	global_load_dword v22, v6, s[82:83]
	v_and_b32_e32 v7, 0x7f, v7
	v_lshl_add_u32 v7, v7, 2, s99
	global_load_dword v23, v7, s[82:83]
	v_mul_f32_e32 v8, 0x3c800000, v8
	v_mul_f32_e32 v9, 0x3c800000, v9
	v_mul_f32_e32 v10, 0x3c800000, v10
	v_mul_f32_e32 v11, 0x3c800000, v11
	v_mul_f32_e32 v12, 0x3c800000, v12
	v_mul_f32_e32 v13, 0x3c800000, v13
	v_mul_f32_e32 v14, 0x3c800000, v14
	v_mul_f32_e32 v15, 0x3c800000, v15
	v_mul_f32_e32 v24, 0x3d372713, v8
	v_mul_f32_e32 v25, 0x3d372713, v9
	v_mul_f32_e32 v26, 0x3d372713, v10
	v_mul_f32_e32 v27, 0x3d372713, v11
	v_mul_f32_e32 v28, 0x3d372713, v12
	v_mul_f32_e32 v29, 0x3d372713, v13
	v_mul_f32_e32 v30, 0x3d372713, v14
	v_mul_f32_e32 v31, 0x3d372713, v15
	v_mul_f32_e32 v24, v8, v24
	v_mul_f32_e32 v25, v9, v25
	v_mul_f32_e32 v26, v10, v26
	v_mul_f32_e32 v27, v11, v27
	v_mul_f32_e32 v28, v12, v28
	v_mul_f32_e32 v29, v13, v29
	v_mul_f32_e32 v30, v14, v30
	v_mul_f32_e32 v31, v15, v31
	v_fma_f32 v24, v8, v24, v8
	v_fma_f32 v25, v9, v25, v9
	v_fma_f32 v26, v10, v26, v10
	v_fma_f32 v27, v11, v27, v11
	v_fma_f32 v28, v12, v28, v12
	v_fma_f32 v29, v13, v29, v13
	v_fma_f32 v30, v14, v30, v14
	v_fma_f32 v31, v15, v31, v15
	v_mul_f32_e32 v24, 0xbfcc422a, v24
	v_mul_f32_e32 v25, 0xbfcc422a, v25
	v_mul_f32_e32 v26, 0xbfcc422a, v26
	v_mul_f32_e32 v27, 0xbfcc422a, v27
	v_mul_f32_e32 v28, 0xbfcc422a, v28
	v_mul_f32_e32 v29, 0xbfcc422a, v29
	v_mul_f32_e32 v30, 0xbfcc422a, v30
	v_mul_f32_e32 v31, 0xbfcc422a, v31
	v_mul_f32_e32 v24, 0x3fb8aa3b, v24
	v_mul_f32_e32 v25, 0x3fb8aa3b, v25
	v_mul_f32_e32 v26, 0x3fb8aa3b, v26
	v_mul_f32_e32 v27, 0x3fb8aa3b, v27
	v_mul_f32_e32 v28, 0x3fb8aa3b, v28
	v_mul_f32_e32 v29, 0x3fb8aa3b, v29
	v_mul_f32_e32 v30, 0x3fb8aa3b, v30
	v_mul_f32_e32 v31, 0x3fb8aa3b, v31
	v_exp_f32_e32 v24, v24
	v_exp_f32_e32 v25, v25
	v_exp_f32_e32 v26, v26
	v_exp_f32_e32 v27, v27
	v_exp_f32_e32 v28, v28
	v_exp_f32_e32 v29, v29
	v_exp_f32_e32 v30, v30
	v_exp_f32_e32 v31, v31
	s_nop 0
	v_add_f32_e32 v24, 1.0, v24
	v_add_f32_e32 v25, 1.0, v25
	v_add_f32_e32 v26, 1.0, v26
	v_add_f32_e32 v27, 1.0, v27
	v_add_f32_e32 v28, 1.0, v28
	v_add_f32_e32 v29, 1.0, v29
	v_add_f32_e32 v30, 1.0, v30
	v_add_f32_e32 v31, 1.0, v31
	v_rcp_f32_e32 v24, v24
	v_rcp_f32_e32 v25, v25
	v_rcp_f32_e32 v26, v26
	v_rcp_f32_e32 v27, v27
	v_rcp_f32_e32 v28, v28
	v_rcp_f32_e32 v29, v29
	v_rcp_f32_e32 v30, v30
	v_rcp_f32_e32 v31, v31
	s_nop 0
	v_mul_f32_e32 v24, v8, v24
	v_mul_f32_e32 v25, v9, v25
	v_mul_f32_e32 v26, v10, v26
	v_mul_f32_e32 v27, v11, v27
	v_mul_f32_e32 v28, v12, v28
	v_mul_f32_e32 v29, v13, v29
	v_mul_f32_e32 v30, v14, v30
	v_mul_f32_e32 v31, v15, v31
	s_waitcnt vmcnt(0)
	v_mul_f32_e32 v24, v24, v16
	ds_write_b32 v117, v24 offset:0
	v_mul_f32_e32 v25, v25, v17
	ds_write_b32 v117, v25 offset:256
	v_mul_f32_e32 v26, v26, v18
	ds_write_b32 v117, v26 offset:512
	v_mul_f32_e32 v27, v27, v19
	ds_write_b32 v117, v27 offset:768
	v_mul_f32_e32 v28, v28, v20
	ds_write_b32 v117, v28 offset:1024
	v_mul_f32_e32 v29, v29, v21
	ds_write_b32 v117, v29 offset:1280
	v_mul_f32_e32 v30, v30, v22
	ds_write_b32 v117, v30 offset:1536
	v_mul_f32_e32 v31, v31, v23
	ds_write_b32 v117, v31 offset:1792
	s_add_u32 s2, s2, 1
	s_cmp_lt_u32 s2, 4
	s_cbranch_scc1 .Lpg1_act
	s_waitcnt lgkmcnt(0)
	v_add_u32_e32 v249, 0, v237
	v_add_u32_e32 v250, 32, v237
	v_add_u32_e32 v251, 64, v237
	v_add_u32_e32 v252, 96, v237
	v_add_u32_e32 v253, 128, v237
	v_add_u32_e32 v254, 160, v237
	v_add_u32_e32 v255, 192, v237
	v_add_u32_e32 v153, 224, v237
	v_readfirstlane_b32 s80, v128
	v_readfirstlane_b32 s81, v129
	s_nop 4
	s_mov_b32 s90, 0xffffff80
	s_mov_b32 s100, 0
	s_mov_b32 s98, 0
	s_mov_b32 s99, 0
	s_lshl_b32 vcc_lo, s98, 9
	s_add_u32 vcc_lo, vcc_lo, s101
	v_add_u32_e32 v116, vcc_lo, v234
	ds_read_b32 v134, v116
	ds_read_b32 v135, v116 offset:256
	s_lshl_b32 vcc_lo, s99, 21
	s_add_u32 s84, s80, vcc_lo
	s_addc_u32 s85, s81, 0
	v_mov_b32_e32 v240, v235
	s_waitcnt lgkmcnt(0)
	ds_bpermute_b32 v142, v249, v134
	ds_bpermute_b32 v143, v250, v134
	s_waitcnt lgkmcnt(0)
	v_and_or_b32 v142, v142, s90, v240
	v_and_or_b32 v143, v143, s90, v240
	global_load_dwordx4 v[0:3], v142, s[84:85]
	global_load_dwordx4 v[4:7], v143, s[84:85]
	ds_bpermute_b32 v142, v251, v134
	ds_bpermute_b32 v143, v252, v134
	s_waitcnt lgkmcnt(0)
	v_and_or_b32 v142, v142, s90, v240
	v_and_or_b32 v143, v143, s90, v240
	global_load_dwordx4 v[8:11], v142, s[84:85]
	global_load_dwordx4 v[12:15], v143, s[84:85]
	ds_bpermute_b32 v142, v253, v134
	ds_bpermute_b32 v143, v254, v134
	s_waitcnt lgkmcnt(0)
	v_and_or_b32 v142, v142, s90, v240
	v_and_or_b32 v143, v143, s90, v240
	global_load_dwordx4 v[16:19], v142, s[84:85]
	global_load_dwordx4 v[20:23], v143, s[84:85]
	ds_bpermute_b32 v142, v255, v134
	ds_bpermute_b32 v143, v153, v134
	s_waitcnt lgkmcnt(0)
	v_and_or_b32 v142, v142, s90, v240
	v_and_or_b32 v143, v143, s90, v240
	global_load_dwordx4 v[24:27], v142, s[84:85]
	global_load_dwordx4 v[28:31], v143, s[84:85]
	ds_bpermute_b32 v142, v249, v135
	ds_bpermute_b32 v143, v250, v135
	s_waitcnt lgkmcnt(0)
	v_and_or_b32 v142, v142, s90, v240
	v_and_or_b32 v143, v143, s90, v240
	global_load_dwordx4 v[32:35], v142, s[84:85]
	global_load_dwordx4 v[36:39], v143, s[84:85]
	ds_bpermute_b32 v142, v251, v135
	ds_bpermute_b32 v143, v252, v135
	s_waitcnt lgkmcnt(0)
	v_and_or_b32 v142, v142, s90, v240
	v_and_or_b32 v143, v143, s90, v240
	global_load_dwordx4 v[40:43], v142, s[84:85]
	global_load_dwordx4 v[44:47], v143, s[84:85]
	ds_bpermute_b32 v142, v253, v135
	ds_bpermute_b32 v143, v254, v135
	s_waitcnt lgkmcnt(0)
	v_and_or_b32 v142, v142, s90, v240
	v_and_or_b32 v143, v143, s90, v240
	global_load_dwordx4 v[48:51], v142, s[84:85]
	global_load_dwordx4 v[52:55], v143, s[84:85]
	ds_bpermute_b32 v142, v255, v135
	ds_bpermute_b32 v143, v153, v135
	s_waitcnt lgkmcnt(0)
	v_and_or_b32 v142, v142, s90, v240
	v_and_or_b32 v143, v143, s90, v240
	global_load_dwordx4 v[56:59], v142, s[84:85]
	global_load_dwordx4 v[60:63], v143, s[84:85]
	s_mov_b32 s92, 1
	s_lshl_b32 vcc_lo, s92, 9
	s_add_u32 vcc_lo, vcc_lo, s101
	v_add_u32_e32 v116, vcc_lo, v234
	ds_read_b32 v134, v116
	ds_read_b32 v135, v116 offset:256
	s_lshl_b32 vcc_lo, s98, 9
	s_add_u32 vcc_lo, vcc_lo, s101
	s_add_u32 vcc_lo, vcc_lo, 0x10000
	v_add_u32_e32 v117, vcc_lo, v234
	ds_read_b32 v136, v117
	ds_read_b32 v137, v117 offset:256
	s_waitcnt vmcnt(0)
